# load cache policy: nt on the read-once residual-base loads in the four residual-add GEMM epilogues; on top of v70
# baseline (speedup 1.0000x reference)
; #define PG8_STAGE(bufoff, gbase, voff) do { _Pragma("unroll") for (int _i = 0; _i < 2; ++_i) \
;         __builtin_amdgcn_global_load_lds((const unsigned*)((const char*)(gbase) + (voff)[_i]), (LAS unsigned*)(lds + (bufoff) + ldsw + _i * 8192), 16, 0, 0); } while (0)
; #define PG8_LDA(dst, b, h) do { _Pragma("unroll") for (int m = 0; m < 4; ++m) _Pragma("unroll") for (int k = 0; k < 2; ++k) dst[m][k] = *(const LAS bf16x8*)(lds + PG8_SA(b, h) + aoff + m * 2048 + k * 1024); } while (0)
; #define PG8_LDB(dst, b, h) do { _Pragma("unroll") for (int n = 0; n < 2; ++n) _Pragma("unroll") for (int k = 0; k < 2; ++k) dst[n][k] = *(const LAS bf16x8*)(lds + PG8_SB(b, h) + boff + n * 2048 + k * 1024); } while (0)
; #define PG8_MMA(ai, bj, At, Bt) do { __builtin_amdgcn_s_setprio(1); _Pragma("unroll") for (int m = 0; m < 4; ++m) _Pragma("unroll") for (int n = 0; n < 2; ++n) _Pragma("unroll") for (int k = 0; k < 2; ++k) \
;         acc[ai][bj][m][n] = __builtin_amdgcn_mfma_f32_16x16x32_bf16(Bt[n][k], At[m][k], acc[ai][bj][m][n], 0, 0, 0); __builtin_amdgcn_s_setprio(0); } while (0)
; #define PG8_WAIT_L(n) asm volatile("s_waitcnt lgkmcnt(" #n ")" ::: "memory")
; #define PG8_BAR __builtin_amdgcn_s_barrier()
; #define PG8_SCHED __builtin_amdgcn_sched_barrier(0)
; template <class Epi>
; __device__ __forceinline__ void gemm_phase(LAS unsigned char* lds, const Gemm g, const Order& S, const Epi& E, const int tid) {
;     ...
;         for (int t = 0; t < nt; t += 2) {
;             const bool last = (t == nt - 2);
;             const char* a1 = cA + (size_t)(t + 1) * kstep;
;             const char* a2 = last ? nA : cA + (size_t)(t + 2) * kstep; const char* b2 = last ? nB : cB + (size_t)(t + 2) * kstep;
;             const char* a3 = a2 + kstep; const char* b3 = b2 + kstep;
;             PG8_LDB(B0, 0, 0); PG8_SCHED; PG8_LDA(At, 0, 0); PG8_STAGE(PG8_SA(1, 1), a1 + hstepA, voffA);
;             PG8_WAIT_L(8); PG8_BAR; PG8_WAIT_L(0); PG8_MMA(0, 0, At, B0); PG8_BAR; PG8_SCHED;
;             PG8_LDB(B1, 0, 1); PG8_STAGE(PG8_SB(0, 0), b2, voffB);
;             PG8_BAR; PG8_WAIT_L(0); PG8_MMA(0, 1, At, B1); PG8_BAR;
;             PG8_LDA(At, 0, 1); PG8_STAGE(PG8_SA(0, 0), a2, voffA);
;             PG8_BAR; PG8_WAIT_L(0); PG8_MMA(1, 0, At, B0); PG8_BAR; PG8_SCHED;
.LBB0_592:
	ds_read_b128 v[128:131], v171
	ds_read_b128 v[132:135], v171 offset:1024
	ds_read_b128 v[136:139], v171 offset:2048
	ds_read_b128 v[140:143], v171 offset:3072
	s_add_u32 s28, s26, 0xfff80080
	s_addc_u32 s29, s27, -1
	s_cmp_eq_u32 s51, 28
	s_cselect_b32 s31, s7, s29
	s_cselect_b32 s30, s15, s28
	s_cselect_b32 s29, s17, s50
	s_cselect_b32 s28, s48, s49
	v_lshl_add_u64 v[200:201], s[26:27], 0, v[152:153]
	s_add_i32 m0, s34, 0xc000
	ds_read_b128 v[160:163], v172
	ds_read_b128 v[164:167], v172 offset:1024
	ds_read_b128 v[176:179], v172 offset:2048
	ds_read_b128 v[180:183], v172 offset:3072
	ds_read_b128 v[184:187], v172 offset:4096
	ds_read_b128 v[188:191], v172 offset:5120
	ds_read_b128 v[192:195], v172 offset:6144
	ds_read_b128 v[196:199], v172 offset:7168
	global_load_lds_dwordx4 v[200:201], off
	v_lshl_add_u64 v[200:201], s[26:27], 0, v[154:155]
	s_add_i32 m0, s34, 0xe000
	s_nop 0
	global_load_lds_dwordx4 v[200:201], off
	s_waitcnt lgkmcnt(8)
	s_barrier
	s_waitcnt lgkmcnt(0)
	s_setprio 1
	s_waitcnt lgkmcnt(0)
	v_mfma_f32_16x16x32_bf16 v[124:127], v[128:131], v[160:163], v[124:127]
	v_mfma_f32_16x16x32_bf16 v[120:123], v[136:139], v[160:163], v[120:123]
	v_mfma_f32_16x16x32_bf16 v[108:111], v[128:131], v[176:179], v[108:111]
	v_mfma_f32_16x16x32_bf16 v[104:107], v[136:139], v[176:179], v[104:107]
	v_mfma_f32_16x16x32_bf16 v[92:95], v[128:131], v[184:187], v[92:95]
	v_mfma_f32_16x16x32_bf16 v[88:91], v[136:139], v[184:187], v[88:91]
	v_mfma_f32_16x16x32_bf16 v[76:79], v[128:131], v[192:195], v[76:79]
	v_mfma_f32_16x16x32_bf16 v[72:75], v[136:139], v[192:195], v[72:75]
	v_mfma_f32_16x16x32_bf16 v[124:127], v[132:135], v[164:167], v[124:127]
	v_mfma_f32_16x16x32_bf16 v[120:123], v[140:143], v[164:167], v[120:123]
	v_mfma_f32_16x16x32_bf16 v[108:111], v[132:135], v[180:183], v[108:111]
	v_mfma_f32_16x16x32_bf16 v[104:107], v[140:143], v[180:183], v[104:107]
	v_mfma_f32_16x16x32_bf16 v[92:95], v[132:135], v[188:191], v[92:95]
	v_mfma_f32_16x16x32_bf16 v[88:91], v[140:143], v[188:191], v[88:91]
	v_mfma_f32_16x16x32_bf16 v[76:79], v[132:135], v[196:199], v[76:79]
	v_mfma_f32_16x16x32_bf16 v[72:75], v[140:143], v[196:199], v[72:75]
	s_setprio 0
	s_barrier
	s_add_i32 s52, s45, s33
	v_lshl_add_u64 v[216:217], s[28:29], 0, v[146:147]
	s_mov_b32 m0, s52
	ds_read_b128 v[200:203], v173
	ds_read_b128 v[204:207], v173 offset:1024
	ds_read_b128 v[208:211], v173 offset:2048
	ds_read_b128 v[212:215], v173 offset:3072
	global_load_lds_dwordx4 v[216:217], off
	v_lshl_add_u64 v[218:219], s[28:29], 0, v[150:151]
	s_add_i32 m0, s52, 0x2000
	s_nop 0
	global_load_lds_dwordx4 v[218:219], off
	s_barrier
	s_waitcnt lgkmcnt(0)
	s_setprio 1
	s_waitcnt lgkmcnt(0)
	v_mfma_f32_16x16x32_bf16 v[116:119], v[200:203], v[160:163], v[116:119]
	v_mfma_f32_16x16x32_bf16 v[112:115], v[208:211], v[160:163], v[112:115]
	v_mfma_f32_16x16x32_bf16 v[100:103], v[200:203], v[176:179], v[100:103]
	v_mfma_f32_16x16x32_bf16 v[96:99], v[208:211], v[176:179], v[96:99]
	v_mfma_f32_16x16x32_bf16 v[84:87], v[200:203], v[184:187], v[84:87]
	v_mfma_f32_16x16x32_bf16 v[80:83], v[208:211], v[184:187], v[80:83]
	v_mfma_f32_16x16x32_bf16 v[68:71], v[200:203], v[192:195], v[68:71]
	v_mfma_f32_16x16x32_bf16 v[64:67], v[208:211], v[192:195], v[64:67]
	v_mfma_f32_16x16x32_bf16 v[116:119], v[204:207], v[164:167], v[116:119]
	v_mfma_f32_16x16x32_bf16 v[112:115], v[212:215], v[164:167], v[112:115]
	v_mfma_f32_16x16x32_bf16 v[100:103], v[204:207], v[180:183], v[100:103]
	v_mfma_f32_16x16x32_bf16 v[96:99], v[212:215], v[180:183], v[96:99]
	v_mfma_f32_16x16x32_bf16 v[84:87], v[204:207], v[188:191], v[84:87]
	v_mfma_f32_16x16x32_bf16 v[80:83], v[212:215], v[188:191], v[80:83]
	v_mfma_f32_16x16x32_bf16 v[68:71], v[204:207], v[196:199], v[68:71]
	v_mfma_f32_16x16x32_bf16 v[64:67], v[212:215], v[196:199], v[64:67]
	s_setprio 0
	s_mov_b32 m0, s34
	v_lshl_add_u64 v[220:221], s[30:31], 0, v[144:145]
	s_barrier
	ds_read_b128 v[160:163], v172 offset:16384
	ds_read_b128 v[164:167], v172 offset:17408
	ds_read_b128 v[176:179], v172 offset:18432
	ds_read_b128 v[180:183], v172 offset:19456
	ds_read_b128 v[184:187], v172 offset:20480
	ds_read_b128 v[188:191], v172 offset:21504
	ds_read_b128 v[192:195], v172 offset:22528
	ds_read_b128 v[196:199], v172 offset:23552
	global_load_lds_dwordx4 v[220:221], off
	v_lshl_add_u64 v[222:223], s[30:31], 0, v[148:149]
	s_mov_b32 m0, s35
	s_nop 0
	global_load_lds_dwordx4 v[222:223], off
	s_barrier
	s_waitcnt lgkmcnt(0)
	s_setprio 1
	s_waitcnt lgkmcnt(0)
	v_mfma_f32_16x16x32_bf16 v[60:63], v[128:131], v[160:163], v[60:63]
	v_mfma_f32_16x16x32_bf16 v[56:59], v[136:139], v[160:163], v[56:59]
	v_mfma_f32_16x16x32_bf16 v[44:47], v[128:131], v[176:179], v[44:47]
	v_mfma_f32_16x16x32_bf16 v[40:43], v[136:139], v[176:179], v[40:43]
	v_mfma_f32_16x16x32_bf16 v[28:31], v[128:131], v[184:187], v[28:31]
	v_mfma_f32_16x16x32_bf16 v[24:27], v[136:139], v[184:187], v[24:27]
	v_mfma_f32_16x16x32_bf16 v[12:15], v[128:131], v[192:195], v[12:15]
	v_mfma_f32_16x16x32_bf16 v[8:11], v[136:139], v[192:195], v[8:11]
	v_mfma_f32_16x16x32_bf16 v[60:63], v[132:135], v[164:167], v[60:63]
	v_mfma_f32_16x16x32_bf16 v[56:59], v[140:143], v[164:167], v[56:59]
	v_mfma_f32_16x16x32_bf16 v[44:47], v[132:135], v[180:183], v[44:47]
	v_mfma_f32_16x16x32_bf16 v[40:43], v[140:143], v[180:183], v[40:43]
	v_mfma_f32_16x16x32_bf16 v[28:31], v[132:135], v[188:191], v[28:31]
	v_mfma_f32_16x16x32_bf16 v[24:27], v[140:143], v[188:191], v[24:27]
	v_mfma_f32_16x16x32_bf16 v[12:15], v[132:135], v[196:199], v[12:15]
	v_mfma_f32_16x16x32_bf16 v[8:11], v[140:143], v[196:199], v[8:11]
	s_setprio 0
	s_barrier
; #define PG8_STAGE(bufoff, gbase, voff) do { _Pragma("unroll") for (int _i = 0; _i < 2; ++_i) \
;         __builtin_amdgcn_global_load_lds((const unsigned*)((const char*)(gbase) + (voff)[_i]), (LAS unsigned*)(lds + (bufoff) + ldsw + _i * 8192), 16, 0, 0); } while (0)
; #define PG8_LDA(dst, b, h) do { _Pragma("unroll") for (int m = 0; m < 4; ++m) _Pragma("unroll") for (int k = 0; k < 2; ++k) dst[m][k] = *(const LAS bf16x8*)(lds + PG8_SA(b, h) + aoff + m * 2048 + k * 1024); } while (0)
; #define PG8_LDB(dst, b, h) do { _Pragma("unroll") for (int n = 0; n < 2; ++n) _Pragma("unroll") for (int k = 0; k < 2; ++k) dst[n][k] = *(const LAS bf16x8*)(lds + PG8_SB(b, h) + boff + n * 2048 + k * 1024); } while (0)
; #define PG8_MMA(ai, bj, At, Bt) do { __builtin_amdgcn_s_setprio(1); _Pragma("unroll") for (int m = 0; m < 4; ++m) _Pragma("unroll") for (int n = 0; n < 2; ++n) _Pragma("unroll") for (int k = 0; k < 2; ++k) \
;         acc[ai][bj][m][n] = __builtin_amdgcn_mfma_f32_16x16x32_bf16(Bt[n][k], At[m][k], acc[ai][bj][m][n], 0, 0, 0); __builtin_amdgcn_s_setprio(0); } while (0)
; #define PG8_WAIT_V(n) asm volatile("s_waitcnt vmcnt(" #n ")" ::: "memory")
; #define PG8_WAIT_L(n) asm volatile("s_waitcnt lgkmcnt(" #n ")" ::: "memory")
; #define PG8_BAR __builtin_amdgcn_s_barrier()
; #define PG8_SCHED __builtin_amdgcn_sched_barrier(0)
; template <class Epi>
; __device__ __forceinline__ void gemm_phase(LAS unsigned char* lds, const Gemm g, const Order& S, const Epi& E, const int tid) {
;     ...
;             PG8_STAGE(PG8_SB(0, 1), b2 + hstepB, voffB);
;             PG8_WAIT_V(6); PG8_BAR; PG8_MMA(1, 1, At, B1); PG8_BAR;
;             PG8_LDB(B0, 1, 0); PG8_SCHED; PG8_LDA(At, 1, 0); PG8_STAGE(PG8_SA(0, 1), a2 + hstepA, voffA);
;             PG8_WAIT_L(8); PG8_BAR; PG8_WAIT_L(0); PG8_MMA(0, 0, At, B0); PG8_BAR; PG8_SCHED;
;             PG8_LDB(B1, 1, 1); PG8_STAGE(PG8_SB(1, 0), b3, voffB);
;             PG8_BAR; PG8_WAIT_L(0); PG8_MMA(0, 1, At, B1); PG8_BAR;
;             PG8_LDA(At, 1, 1); PG8_STAGE(PG8_SA(1, 0), a3, voffA);
	s_add_u32 s52, s28, 0x80000
	s_addc_u32 s53, s29, 0
	s_add_i32 s55, s46, s33
	v_lshl_add_u64 v[128:129], s[52:53], 0, v[146:147]
	s_mov_b32 m0, s55
	s_nop 0
	global_load_lds_dwordx4 v[128:129], off
	v_lshl_add_u64 v[128:129], s[52:53], 0, v[150:151]
	s_add_i32 m0, s55, 0x2000
	s_nop 0
	global_load_lds_dwordx4 v[128:129], off
	s_waitcnt vmcnt(6)
	s_barrier
	s_setprio 1
	v_mfma_f32_16x16x32_bf16 v[52:55], v[200:203], v[160:163], v[52:55]
	v_mfma_f32_16x16x32_bf16 v[48:51], v[208:211], v[160:163], v[48:51]
	v_mfma_f32_16x16x32_bf16 v[36:39], v[200:203], v[176:179], v[36:39]
	v_mfma_f32_16x16x32_bf16 v[32:35], v[208:211], v[176:179], v[32:35]
	v_mfma_f32_16x16x32_bf16 v[20:23], v[200:203], v[184:187], v[20:23]
	v_mfma_f32_16x16x32_bf16 v[16:19], v[208:211], v[184:187], v[16:19]
	v_mfma_f32_16x16x32_bf16 v[4:7], v[200:203], v[192:195], v[4:7]
	v_mfma_f32_16x16x32_bf16 v[0:3], v[208:211], v[192:195], v[0:3]
	v_mfma_f32_16x16x32_bf16 v[52:55], v[204:207], v[164:167], v[52:55]
	v_mfma_f32_16x16x32_bf16 v[48:51], v[212:215], v[164:167], v[48:51]
	v_mfma_f32_16x16x32_bf16 v[36:39], v[204:207], v[180:183], v[36:39]
	v_mfma_f32_16x16x32_bf16 v[32:35], v[212:215], v[180:183], v[32:35]
	v_mfma_f32_16x16x32_bf16 v[20:23], v[204:207], v[188:191], v[20:23]
	v_mfma_f32_16x16x32_bf16 v[16:19], v[212:215], v[188:191], v[16:19]
	v_mfma_f32_16x16x32_bf16 v[4:7], v[204:207], v[196:199], v[4:7]
	v_mfma_f32_16x16x32_bf16 v[0:3], v[212:215], v[196:199], v[0:3]
	s_setprio 0
	s_add_i32 s52, 0, 0x18000
	v_add_u32_e32 v140, s52, v169
	s_barrier
	ds_read_b128 v[128:131], v140
	ds_read_b128 v[132:135], v140 offset:1024
	ds_read_b128 v[136:139], v140 offset:2048
	ds_read_b128 v[140:143], v140 offset:3072
	s_add_u32 s30, s30, 0x80000
	s_addc_u32 s31, s31, 0
	s_mov_b32 m0, s39
	v_lshl_add_u64 v[200:201], s[30:31], 0, v[144:145]
	ds_read_b128 v[160:163], v172 offset:32768
	ds_read_b128 v[164:167], v172 offset:33792
	ds_read_b128 v[176:179], v172 offset:34816
	ds_read_b128 v[180:183], v172 offset:35840
	ds_read_b128 v[184:187], v172 offset:36864
	ds_read_b128 v[188:191], v172 offset:37888
	ds_read_b128 v[192:195], v172 offset:38912
	ds_read_b128 v[196:199], v172 offset:39936
	global_load_lds_dwordx4 v[200:201], off
	v_lshl_add_u64 v[200:201], s[30:31], 0, v[148:149]
	s_mov_b32 m0, s40
	s_nop 0
	global_load_lds_dwordx4 v[200:201], off
	s_waitcnt lgkmcnt(8)
	s_barrier
	s_waitcnt lgkmcnt(0)
	s_setprio 1
	s_waitcnt lgkmcnt(0)
	v_mfma_f32_16x16x32_bf16 v[124:127], v[128:131], v[160:163], v[124:127]
	v_mfma_f32_16x16x32_bf16 v[120:123], v[136:139], v[160:163], v[120:123]
	v_mfma_f32_16x16x32_bf16 v[108:111], v[128:131], v[176:179], v[108:111]
	v_mfma_f32_16x16x32_bf16 v[104:107], v[136:139], v[176:179], v[104:107]
	v_mfma_f32_16x16x32_bf16 v[92:95], v[128:131], v[184:187], v[92:95]
	v_mfma_f32_16x16x32_bf16 v[88:91], v[136:139], v[184:187], v[88:91]
	v_mfma_f32_16x16x32_bf16 v[76:79], v[128:131], v[192:195], v[76:79]
	v_mfma_f32_16x16x32_bf16 v[72:75], v[136:139], v[192:195], v[72:75]
	v_mfma_f32_16x16x32_bf16 v[124:127], v[132:135], v[164:167], v[124:127]
	v_mfma_f32_16x16x32_bf16 v[120:123], v[140:143], v[164:167], v[120:123]
	v_mfma_f32_16x16x32_bf16 v[108:111], v[132:135], v[180:183], v[108:111]
	v_mfma_f32_16x16x32_bf16 v[104:107], v[140:143], v[180:183], v[104:107]
	v_mfma_f32_16x16x32_bf16 v[92:95], v[132:135], v[188:191], v[92:95]
	v_mfma_f32_16x16x32_bf16 v[88:91], v[140:143], v[188:191], v[88:91]
	v_mfma_f32_16x16x32_bf16 v[76:79], v[132:135], v[196:199], v[76:79]
	v_mfma_f32_16x16x32_bf16 v[72:75], v[140:143], v[196:199], v[72:75]
	s_setprio 0
	s_barrier
	s_add_i32 s30, 0, 0x1c000
	s_add_i32 s31, s52, s33
	v_add_u32_e32 v175, s30, v169
	v_lshl_add_u64 v[216:217], v[216:217], 0, s[12:13]
	s_mov_b32 m0, s31
	ds_read_b128 v[200:203], v175
	ds_read_b128 v[204:207], v175 offset:1024
	ds_read_b128 v[208:211], v175 offset:2048
	ds_read_b128 v[212:215], v175 offset:3072
	global_load_lds_dwordx4 v[216:217], off
	v_lshl_add_u64 v[216:217], v[218:219], 0, s[12:13]
	s_add_i32 m0, s31, 0x2000
	s_nop 0
	global_load_lds_dwordx4 v[216:217], off
	s_barrier
	s_waitcnt lgkmcnt(0)
	s_setprio 1
	s_waitcnt lgkmcnt(0)
	v_mfma_f32_16x16x32_bf16 v[116:119], v[200:203], v[160:163], v[116:119]
	v_mfma_f32_16x16x32_bf16 v[112:115], v[208:211], v[160:163], v[112:115]
	v_mfma_f32_16x16x32_bf16 v[100:103], v[200:203], v[176:179], v[100:103]
	v_mfma_f32_16x16x32_bf16 v[96:99], v[208:211], v[176:179], v[96:99]
	v_mfma_f32_16x16x32_bf16 v[84:87], v[200:203], v[184:187], v[84:87]
	v_mfma_f32_16x16x32_bf16 v[80:83], v[208:211], v[184:187], v[80:83]
	v_mfma_f32_16x16x32_bf16 v[68:71], v[200:203], v[192:195], v[68:71]
	v_mfma_f32_16x16x32_bf16 v[64:67], v[208:211], v[192:195], v[64:67]
	v_mfma_f32_16x16x32_bf16 v[116:119], v[204:207], v[164:167], v[116:119]
	v_mfma_f32_16x16x32_bf16 v[112:115], v[212:215], v[164:167], v[112:115]
	v_mfma_f32_16x16x32_bf16 v[100:103], v[204:207], v[180:183], v[100:103]
	v_mfma_f32_16x16x32_bf16 v[96:99], v[212:215], v[180:183], v[96:99]
	v_mfma_f32_16x16x32_bf16 v[84:87], v[204:207], v[188:191], v[84:87]
	v_mfma_f32_16x16x32_bf16 v[80:83], v[212:215], v[188:191], v[80:83]
	v_mfma_f32_16x16x32_bf16 v[68:71], v[204:207], v[196:199], v[68:71]
	v_mfma_f32_16x16x32_bf16 v[64:67], v[212:215], v[196:199], v[64:67]
	s_setprio 0
	s_mov_b32 m0, s43
	v_lshl_add_u64 v[216:217], v[220:221], 0, s[12:13]
	s_barrier
	ds_read_b128 v[160:163], v172 offset:49152
	ds_read_b128 v[164:167], v172 offset:50176
	ds_read_b128 v[176:179], v172 offset:51200
	ds_read_b128 v[180:183], v172 offset:52224
	ds_read_b128 v[184:187], v172 offset:53248
	ds_read_b128 v[188:191], v172 offset:54272
	ds_read_b128 v[192:195], v172 offset:55296
	ds_read_b128 v[196:199], v172 offset:56320
	global_load_lds_dwordx4 v[216:217], off
	v_lshl_add_u64 v[216:217], v[222:223], 0, s[12:13]
	s_mov_b32 m0, s44
	s_nop 0
	global_load_lds_dwordx4 v[216:217], off
	s_barrier
; #define PG8_STAGE(bufoff, gbase, voff) do { _Pragma("unroll") for (int _i = 0; _i < 2; ++_i) \
;         __builtin_amdgcn_global_load_lds((const unsigned*)((const char*)(gbase) + (voff)[_i]), (LAS unsigned*)(lds + (bufoff) + ldsw + _i * 8192), 16, 0, 0); } while (0)
; #define PG8_WAIT_V(n) asm volatile("s_waitcnt vmcnt(" #n ")" ::: "memory")
; #define PG8_WAIT_L(n) asm volatile("s_waitcnt lgkmcnt(" #n ")" ::: "memory")
; #define PG8_BAR __builtin_amdgcn_s_barrier()
; template <class Epi>
; __device__ __forceinline__ void gemm_phase(LAS unsigned char* lds, const Gemm g, const Order& S, const Epi& E, const int tid) {
;     ...
;             PG8_BAR; PG8_WAIT_L(0); PG8_MMA(1, 0, At, B0); PG8_BAR; PG8_SCHED;
;             PG8_STAGE(PG8_SB(1, 1), b3 + hstepB, voffB);
;             PG8_WAIT_V(6); PG8_BAR; PG8_MMA(1, 1, At, B1); PG8_BAR;
;     __device__ __forceinline__ void operator()(const f32x4 (&acc)[2][2][4][2], const Unit& u, int wr, int wc, int fr, int fq) const {
;     ...
;                 for (int m = 0; m < 4; m += 2) {
;                     f32x4 bs[2][2][2];
; #pragma unroll
;                     for (int mm = 0; mm < 2; ++mm) { const size_t off = (size_t)(row0 + ai * HALF + (m + mm) * 16) * DM + col0;
; #pragma unroll
;                         for (int bj = 0; bj < 2; ++bj)
; #pragma unroll
;                             for (int n = 0; n < 2; ++n) bs[mm][bj][n] = *(const f32x4*)(basef + off + bj * HALF + n * 4); }
; #pragma unroll
;                     for (int mm = 0; mm < 2; ++mm) { const size_t off = (size_t)(row0 + ai * HALF + (m + mm) * 16) * DM + col0;
;                         float ss = 0.f;
; #pragma unroll
;                         for (int bj = 0; bj < 2; ++bj) { const f32x4 v0 = bs[mm][bj][0] + acc[ai][bj][m + mm][0], v1 = bs[mm][bj][1] + acc[ai][bj][m + mm][1];
;                             ss += (v0[0] * v0[0] + v0[1] * v0[1]) + (v0[2] * v0[2] + v0[3] * v0[3]) + (v1[0] * v1[0] + v1[1] * v1[1]) + (v1[2] * v1[2] + v1[3] * v1[3]);
;                             u32x4 w; w.x = pk2(v0[0], v0[1]); w.y = pk2(v0[2], v0[3]); w.z = pk2(v1[0], v1[1]); w.w = pk2(v1[2], v1[3]);
;                             *(u32x4*)(out + off + bj * HALF) = w; }
;                         if (ssqp) { ss += __shfl_xor(ss, 16); ss += __shfl_xor(ss, 32); if (fq == 0) ssqp[(size_t)(row0 + ai * HALF + (m + mm) * 16) * 32 + u.pn * 4 + wc] = ss; } }
	s_waitcnt lgkmcnt(0)
	s_setprio 1
	s_waitcnt lgkmcnt(0)
	v_mfma_f32_16x16x32_bf16 v[60:63], v[128:131], v[160:163], v[60:63]
	v_mfma_f32_16x16x32_bf16 v[56:59], v[136:139], v[160:163], v[56:59]
	v_mfma_f32_16x16x32_bf16 v[44:47], v[128:131], v[176:179], v[44:47]
	v_mfma_f32_16x16x32_bf16 v[40:43], v[136:139], v[176:179], v[40:43]
	v_mfma_f32_16x16x32_bf16 v[28:31], v[128:131], v[184:187], v[28:31]
	v_mfma_f32_16x16x32_bf16 v[24:27], v[136:139], v[184:187], v[24:27]
	v_mfma_f32_16x16x32_bf16 v[12:15], v[128:131], v[192:195], v[12:15]
	v_mfma_f32_16x16x32_bf16 v[8:11], v[136:139], v[192:195], v[8:11]
	v_mfma_f32_16x16x32_bf16 v[60:63], v[132:135], v[164:167], v[60:63]
	v_mfma_f32_16x16x32_bf16 v[56:59], v[140:143], v[164:167], v[56:59]
	v_mfma_f32_16x16x32_bf16 v[44:47], v[132:135], v[180:183], v[44:47]
	v_mfma_f32_16x16x32_bf16 v[40:43], v[140:143], v[180:183], v[40:43]
	v_mfma_f32_16x16x32_bf16 v[28:31], v[132:135], v[188:191], v[28:31]
	v_mfma_f32_16x16x32_bf16 v[24:27], v[140:143], v[188:191], v[24:27]
	v_mfma_f32_16x16x32_bf16 v[12:15], v[132:135], v[196:199], v[12:15]
	v_mfma_f32_16x16x32_bf16 v[8:11], v[140:143], v[196:199], v[8:11]
	s_setprio 0
	s_barrier
	s_add_u32 s28, s28, 0x80080
	s_addc_u32 s29, s29, 0
	s_add_i32 s30, s30, s33
	v_lshl_add_u64 v[128:129], s[28:29], 0, v[146:147]
	s_mov_b32 m0, s30
	s_nop 0
	global_load_lds_dwordx4 v[128:129], off
	v_lshl_add_u64 v[128:129], s[28:29], 0, v[150:151]
	s_add_i32 m0, s30, 0x2000
	s_nop 0
	global_load_lds_dwordx4 v[128:129], off
	s_waitcnt vmcnt(6)
	s_barrier
	s_setprio 1
	v_mfma_f32_16x16x32_bf16 v[52:55], v[200:203], v[160:163], v[52:55]
	v_mfma_f32_16x16x32_bf16 v[48:51], v[208:211], v[160:163], v[48:51]
	v_mfma_f32_16x16x32_bf16 v[36:39], v[200:203], v[176:179], v[36:39]
	v_mfma_f32_16x16x32_bf16 v[32:35], v[208:211], v[176:179], v[32:35]
	v_mfma_f32_16x16x32_bf16 v[20:23], v[200:203], v[184:187], v[20:23]
	v_mfma_f32_16x16x32_bf16 v[16:19], v[208:211], v[184:187], v[16:19]
	v_mfma_f32_16x16x32_bf16 v[4:7], v[200:203], v[192:195], v[4:7]
	v_mfma_f32_16x16x32_bf16 v[0:3], v[208:211], v[192:195], v[0:3]
	v_mfma_f32_16x16x32_bf16 v[52:55], v[204:207], v[164:167], v[52:55]
	v_mfma_f32_16x16x32_bf16 v[48:51], v[212:215], v[164:167], v[48:51]
	v_mfma_f32_16x16x32_bf16 v[36:39], v[204:207], v[180:183], v[36:39]
	v_mfma_f32_16x16x32_bf16 v[32:35], v[212:215], v[180:183], v[32:35]
	v_mfma_f32_16x16x32_bf16 v[20:23], v[204:207], v[188:191], v[20:23]
	v_mfma_f32_16x16x32_bf16 v[16:19], v[212:215], v[188:191], v[16:19]
	v_mfma_f32_16x16x32_bf16 v[4:7], v[204:207], v[196:199], v[4:7]
	v_mfma_f32_16x16x32_bf16 v[0:3], v[212:215], v[196:199], v[0:3]
	s_setprio 0
	s_add_i32 s51, s51, 2
	s_add_u32 s26, s26, 0x100
	s_addc_u32 s27, s27, 0
	s_add_u32 s49, s49, 0x100
	s_addc_u32 s50, s50, 0
	s_cmp_gt_u32 s51, 29
	s_barrier
	s_cbranch_scc0 .LBB0_592
	v_lshl_add_u32 v162, s8, 8, v168
	v_lshl_or_b32 v160, s6, 8, v170
	v_ashrrev_i32_e32 v161, 31, v160
	v_ashrrev_i32_e32 v163, 31, v162
	v_lshl_add_u64 v[164:165], v[160:161], 2, s[56:57]
	v_lshlrev_b64 v[128:129], 13, v[162:163]
	v_or_b32_e32 v166, 16, v162
	v_lshl_add_u64 v[128:129], v[164:165], 0, v[128:129]
	v_ashrrev_i32_e32 v167, 31, v166
	global_load_dwordx4 v[176:179], v[128:129], off nt
	global_load_dwordx4 v[180:183], v[128:129], off offset:16 nt
	global_load_dwordx4 v[184:187], v[128:129], off offset:512 nt
	global_load_dwordx4 v[188:191], v[128:129], off offset:528 nt
	v_lshlrev_b64 v[128:129], 13, v[166:167]
	v_lshl_add_u64 v[132:133], v[164:165], 0, v[128:129]
	global_load_dwordx4 v[136:139], v[132:133], off offset:16 nt
	global_load_dwordx4 v[140:143], v[132:133], off nt
	global_load_dwordx4 v[128:131], v[132:133], off offset:528 nt
	s_nop 0
	global_load_dwordx4 v[132:135], v[132:133], off offset:512 nt
	v_lshlrev_b64 v[192:193], 12, v[162:163]
	s_lshl_b32 s26, s6, 2
	v_cndmask_b32_e64 v175, 0, 1, s[10:11]
	v_lshl_add_u64 v[192:193], s[22:23], 0, v[192:193]
	s_ashr_i32 s27, s26, 31
	v_cmp_ne_u32_e64 s[6:7], 1, v175
	s_andn2_b64 vcc, exec, s[10:11]
	v_lshl_add_u64 v[192:193], v[160:161], 1, v[192:193]
	s_waitcnt vmcnt(0)
	v_pk_add_f32 v[126:127], v[126:127], v[178:179]
	v_pk_add_f32 v[124:125], v[124:125], v[176:177]
	v_pk_add_f32 v[122:123], v[122:123], v[182:183]
	v_pk_add_f32 v[120:121], v[120:121], v[180:181]
	v_pk_add_f32 v[118:119], v[118:119], v[186:187]
	v_pk_add_f32 v[116:117], v[116:117], v[184:185]
	v_pk_add_f32 v[114:115], v[114:115], v[190:191]
	v_pk_add_f32 v[112:113], v[112:113], v[188:189]
	v_cvt_pk_bf16_f32 v176, v124, v125
	v_cvt_pk_bf16_f32 v177, v126, v127
	v_cvt_pk_bf16_f32 v178, v120, v121
	v_cvt_pk_bf16_f32 v179, v122, v123
	v_cvt_pk_bf16_f32 v180, v116, v117
	v_cvt_pk_bf16_f32 v181, v118, v119
	v_cvt_pk_bf16_f32 v182, v112, v113
	v_cvt_pk_bf16_f32 v183, v114, v115
	global_store_dwordx4 v[192:193], v[176:179], off sc0 sc1
	global_store_dwordx4 v[192:193], v[180:183], off offset:256 sc0 sc1
	s_cbranch_vccnz .LBB0_597
	v_mul_f32_e32 v115, v115, v115
	v_fmac_f32_e32 v115, v114, v114
	v_mul_f32_e32 v114, v117, v117
	v_mul_f32_e32 v123, v123, v123
	v_fmac_f32_e32 v114, v116, v116
	v_mul_f32_e32 v116, v119, v119
	v_fmac_f32_e32 v123, v122, v122
	v_mul_f32_e32 v122, v125, v125
	v_fmac_f32_e32 v116, v118, v118
	v_mul_f32_e32 v113, v113, v113
	v_fmac_f32_e32 v122, v124, v124
	v_mul_f32_e32 v124, v127, v127
	v_add_f32_e32 v114, v114, v116
	v_fmac_f32_e32 v113, v112, v112
	v_fmac_f32_e32 v124, v126, v126
	v_mul_f32_e32 v121, v121, v121
	v_add_f32_e32 v112, v114, v113
	v_and_b32_e32 v114, 64, v174
	v_add_f32_e32 v122, v122, v124
	v_fmac_f32_e32 v121, v120, v120
	v_xor_b32_e32 v113, 16, v174
	v_add_u32_e32 v114, 64, v114
	v_add_f32_e32 v120, v122, v121
	v_cmp_lt_i32_e32 vcc, v113, v114
	v_add_f32_e32 v120, v123, v120
	v_add_f32_e32 v112, v115, v112
	v_cndmask_b32_e32 v113, v174, v113, vcc
	v_add_f32_e32 v112, v120, v112
	v_lshlrev_b32_e32 v113, 2, v113
	ds_bpermute_b32 v113, v113, v112
	s_waitcnt lgkmcnt(0)
	v_add_f32_e32 v112, v112, v113
	v_xor_b32_e32 v113, 32, v174
	v_cmp_lt_i32_e32 vcc, v113, v114
	s_nop 1
	v_cndmask_b32_e32 v113, v174, v113, vcc
	v_lshlrev_b32_e32 v113, 2, v113
	ds_bpermute_b32 v113, v113, v112
	s_and_saveexec_b64 s[28:29], s[0:1]
	s_cbranch_execz .LBB0_596
	v_lshlrev_b64 v[114:115], 7, v[162:163]
	v_lshl_add_u64 v[114:115], s[24:25], 0, v[114:115]
	v_lshl_add_u64 v[114:115], s[26:27], 2, v[114:115]
	s_lshl_b32 s8, s41, 2
	v_lshl_add_u64 v[114:115], v[114:115], 0, s[8:9]
	s_waitcnt lgkmcnt(0)
	v_add_f32_e32 v112, v112, v113
	global_store_dword v[114:115], v112, off

;     __device__ __forceinline__ void operator()(const f32x4 (&acc)[2][2][4][2], const Unit& u, int wr, int wc, int fr, int fq) const {
;     ...
;                 for (int m = 0; m < 4; m += 2) {
;                     f32x4 bs[2][2][2];
; #pragma unroll
;                     for (int mm = 0; mm < 2; ++mm) { const size_t off = (size_t)(row0 + ai * HALF + (m + mm) * 16) * DM + col0;
; #pragma unroll
;                         for (int bj = 0; bj < 2; ++bj)
; #pragma unroll
;                             for (int n = 0; n < 2; ++n) bs[mm][bj][n] = *(const f32x4*)(basef + off + bj * HALF + n * 4); }
; #pragma unroll
;                     for (int mm = 0; mm < 2; ++mm) { const size_t off = (size_t)(row0 + ai * HALF + (m + mm) * 16) * DM + col0;
;                         float ss = 0.f;
; #pragma unroll
;                         for (int bj = 0; bj < 2; ++bj) { const f32x4 v0 = bs[mm][bj][0] + acc[ai][bj][m + mm][0], v1 = bs[mm][bj][1] + acc[ai][bj][m + mm][1];
;                             ss += (v0[0] * v0[0] + v0[1] * v0[1]) + (v0[2] * v0[2] + v0[3] * v0[3]) + (v1[0] * v1[0] + v1[1] * v1[1]) + (v1[2] * v1[2] + v1[3] * v1[3]);
;                             u32x4 w; w.x = pk2(v0[0], v0[1]); w.y = pk2(v0[2], v0[3]); w.z = pk2(v1[0], v1[1]); w.w = pk2(v1[2], v1[3]);
;                             *(u32x4*)(out + off + bj * HALF) = w; }
;                         if (ssqp) { ss += __shfl_xor(ss, 16); ss += __shfl_xor(ss, 32); if (fq == 0) ssqp[(size_t)(row0 + ai * HALF + (m + mm) * 16) * 32 + u.pn * 4 + wc] = ss; } }
.LBB0_601:
	s_nop 0
	v_or_b32_e32 v114, 32, v162
	v_ashrrev_i32_e32 v115, 31, v114
	s_waitcnt lgkmcnt(0)
	v_lshlrev_b64 v[96:97], 13, v[114:115]
	v_or_b32_e32 v112, 48, v162
	v_lshl_add_u64 v[96:97], v[164:165], 0, v[96:97]
	v_ashrrev_i32_e32 v113, 31, v112
	global_load_dwordx4 v[116:119], v[96:97], off nt
	global_load_dwordx4 v[120:123], v[96:97], off offset:16 nt
	global_load_dwordx4 v[124:127], v[96:97], off offset:512 nt
	global_load_dwordx4 v[128:131], v[96:97], off offset:528 nt
	v_lshlrev_b64 v[96:97], 13, v[112:113]
	v_lshl_add_u64 v[100:101], v[164:165], 0, v[96:97]
	global_load_dwordx4 v[104:107], v[100:101], off offset:16 nt
	global_load_dwordx4 v[108:111], v[100:101], off nt
	global_load_dwordx4 v[96:99], v[100:101], off offset:528 nt
	s_nop 0
	global_load_dwordx4 v[100:103], v[100:101], off offset:512 nt
	v_lshlrev_b64 v[132:133], 12, v[114:115]
	v_lshl_add_u64 v[132:133], s[22:23], 0, v[132:133]
	s_and_b64 vcc, exec, s[6:7]
	v_lshl_add_u64 v[132:133], v[160:161], 1, v[132:133]
	s_waitcnt vmcnt(7)
	v_pk_add_f32 v[94:95], v[94:95], v[118:119]
	v_pk_add_f32 v[92:93], v[92:93], v[116:117]
	s_waitcnt vmcnt(6)
	v_pk_add_f32 v[90:91], v[90:91], v[122:123]
	v_pk_add_f32 v[88:89], v[88:89], v[120:121]
	s_waitcnt vmcnt(5)
	v_pk_add_f32 v[86:87], v[86:87], v[126:127]
	v_pk_add_f32 v[84:85], v[84:85], v[124:125]
	s_waitcnt vmcnt(4)
	v_pk_add_f32 v[82:83], v[82:83], v[130:131]
	v_pk_add_f32 v[80:81], v[80:81], v[128:129]
	v_cvt_pk_bf16_f32 v116, v92, v93
	v_cvt_pk_bf16_f32 v117, v94, v95
	v_cvt_pk_bf16_f32 v118, v88, v89
	v_cvt_pk_bf16_f32 v119, v90, v91
	v_cvt_pk_bf16_f32 v120, v84, v85
	v_cvt_pk_bf16_f32 v121, v86, v87
	v_cvt_pk_bf16_f32 v122, v80, v81
	v_cvt_pk_bf16_f32 v123, v82, v83
	global_store_dwordx4 v[132:133], v[116:119], off sc0 sc1
	global_store_dwordx4 v[132:133], v[120:123], off offset:256 sc0 sc1
	s_cbranch_vccnz .LBB0_605
	v_mul_f32_e32 v83, v83, v83
	v_fmac_f32_e32 v83, v82, v82
	v_mul_f32_e32 v82, v85, v85
	v_mul_f32_e32 v91, v91, v91
	v_fmac_f32_e32 v82, v84, v84
	v_mul_f32_e32 v84, v87, v87
	v_fmac_f32_e32 v91, v90, v90
	v_mul_f32_e32 v90, v93, v93
	v_fmac_f32_e32 v84, v86, v86
	v_mul_f32_e32 v81, v81, v81
	v_fmac_f32_e32 v90, v92, v92
	v_mul_f32_e32 v92, v95, v95
	v_add_f32_e32 v82, v82, v84
	v_fmac_f32_e32 v81, v80, v80
	v_fmac_f32_e32 v92, v94, v94
	v_mul_f32_e32 v89, v89, v89
	v_add_f32_e32 v80, v82, v81
	v_and_b32_e32 v82, 64, v174
	v_add_f32_e32 v90, v90, v92
	v_fmac_f32_e32 v89, v88, v88
	v_xor_b32_e32 v81, 16, v174
	v_add_u32_e32 v82, 64, v82
	v_add_f32_e32 v88, v90, v89
	v_cmp_lt_i32_e32 vcc, v81, v82
	v_add_f32_e32 v88, v91, v88
	v_add_f32_e32 v80, v83, v80
	v_cndmask_b32_e32 v81, v174, v81, vcc
	v_add_f32_e32 v80, v88, v80
	v_lshlrev_b32_e32 v81, 2, v81
	ds_bpermute_b32 v81, v81, v80
	s_waitcnt lgkmcnt(0)
	v_add_f32_e32 v80, v80, v81
	v_xor_b32_e32 v81, 32, v174
	v_cmp_lt_i32_e32 vcc, v81, v82
	s_nop 1
	v_cndmask_b32_e32 v81, v174, v81, vcc
	v_lshlrev_b32_e32 v81, 2, v81
	ds_bpermute_b32 v81, v81, v80
	s_and_saveexec_b64 s[28:29], s[0:1]
	s_cbranch_execz .LBB0_604
	v_lshlrev_b64 v[82:83], 7, v[114:115]
	v_lshl_add_u64 v[82:83], s[24:25], 0, v[82:83]
	v_lshl_add_u64 v[82:83], s[26:27], 2, v[82:83]
	s_lshl_b32 s8, s41, 2
	v_lshl_add_u64 v[82:83], v[82:83], 0, s[8:9]
	s_waitcnt lgkmcnt(0)
	v_add_f32_e32 v80, v80, v81
	global_store_dword v[82:83], v80, off

;     __device__ __forceinline__ void operator()(const f32x4 (&acc)[2][2][4][2], const Unit& u, int wr, int wc, int fr, int fq) const {
;     ...
;         for (int ai = 0; ai < 2; ++ai) {
;             if (BASE_F32) {
; #pragma unroll
;                 for (int m = 0; m < 4; m += 2) {
;                     f32x4 bs[2][2][2];
; #pragma unroll
;                     for (int mm = 0; mm < 2; ++mm) { const size_t off = (size_t)(row0 + ai * HALF + (m + mm) * 16) * DM + col0;
; #pragma unroll
;                         for (int bj = 0; bj < 2; ++bj)
; #pragma unroll
;                             for (int n = 0; n < 2; ++n) bs[mm][bj][n] = *(const f32x4*)(basef + off + bj * HALF + n * 4); }
; #pragma unroll
;                     for (int mm = 0; mm < 2; ++mm) { const size_t off = (size_t)(row0 + ai * HALF + (m + mm) * 16) * DM + col0;
;                         float ss = 0.f;
; #pragma unroll
;                         for (int bj = 0; bj < 2; ++bj) { const f32x4 v0 = bs[mm][bj][0] + acc[ai][bj][m + mm][0], v1 = bs[mm][bj][1] + acc[ai][bj][m + mm][1];
;                             ss += (v0[0] * v0[0] + v0[1] * v0[1]) + (v0[2] * v0[2] + v0[3] * v0[3]) + (v1[0] * v1[0] + v1[1] * v1[1]) + (v1[2] * v1[2] + v1[3] * v1[3]);
;                             u32x4 w; w.x = pk2(v0[0], v0[1]); w.y = pk2(v0[2], v0[3]); w.z = pk2(v1[0], v1[1]); w.w = pk2(v1[2], v1[3]);
;                             *(u32x4*)(out + off + bj * HALF) = w; }
;                         if (ssqp) { ss += __shfl_xor(ss, 16); ss += __shfl_xor(ss, 32); if (fq == 0) ssqp[(size_t)(row0 + ai * HALF + (m + mm) * 16) * 32 + u.pn * 4 + wc] = ss; } }
.LBB0_609:
	s_nop 0
	v_add_u32_e32 v82, 0x80, v162
	v_ashrrev_i32_e32 v83, 31, v82
	s_waitcnt lgkmcnt(0)
	v_lshlrev_b64 v[64:65], 13, v[82:83]
	v_add_u32_e32 v80, 0x90, v162
	v_lshl_add_u64 v[64:65], v[164:165], 0, v[64:65]
	v_ashrrev_i32_e32 v81, 31, v80
	global_load_dwordx4 v[84:87], v[64:65], off nt
	global_load_dwordx4 v[88:91], v[64:65], off offset:16 nt
	global_load_dwordx4 v[92:95], v[64:65], off offset:512 nt
	global_load_dwordx4 v[96:99], v[64:65], off offset:528 nt
	v_lshlrev_b64 v[64:65], 13, v[80:81]
	v_lshl_add_u64 v[68:69], v[164:165], 0, v[64:65]
	global_load_dwordx4 v[72:75], v[68:69], off offset:16 nt
	global_load_dwordx4 v[76:79], v[68:69], off nt
	global_load_dwordx4 v[64:67], v[68:69], off offset:528 nt
	s_nop 0
	global_load_dwordx4 v[68:71], v[68:69], off offset:512 nt
	v_lshlrev_b64 v[100:101], 12, v[82:83]
	v_lshl_add_u64 v[100:101], s[22:23], 0, v[100:101]
	s_and_b64 vcc, exec, s[6:7]
	v_lshl_add_u64 v[100:101], v[160:161], 1, v[100:101]
	s_waitcnt vmcnt(7)
	v_pk_add_f32 v[62:63], v[62:63], v[86:87]
	v_pk_add_f32 v[60:61], v[60:61], v[84:85]
	s_waitcnt vmcnt(6)
	v_pk_add_f32 v[58:59], v[58:59], v[90:91]
	v_pk_add_f32 v[56:57], v[56:57], v[88:89]
	s_waitcnt vmcnt(5)
	v_pk_add_f32 v[54:55], v[54:55], v[94:95]
	v_pk_add_f32 v[52:53], v[52:53], v[92:93]
	s_waitcnt vmcnt(4)
	v_pk_add_f32 v[50:51], v[50:51], v[98:99]
	v_pk_add_f32 v[48:49], v[48:49], v[96:97]
	v_cvt_pk_bf16_f32 v84, v60, v61
	v_cvt_pk_bf16_f32 v85, v62, v63
	v_cvt_pk_bf16_f32 v86, v56, v57
	v_cvt_pk_bf16_f32 v87, v58, v59
	v_cvt_pk_bf16_f32 v88, v52, v53
	v_cvt_pk_bf16_f32 v89, v54, v55
	v_cvt_pk_bf16_f32 v90, v48, v49
	v_cvt_pk_bf16_f32 v91, v50, v51
	global_store_dwordx4 v[100:101], v[84:87], off sc0 sc1
	global_store_dwordx4 v[100:101], v[88:91], off offset:256 sc0 sc1
	s_cbranch_vccnz .LBB0_613
	v_mul_f32_e32 v51, v51, v51
	v_fmac_f32_e32 v51, v50, v50
	v_mul_f32_e32 v50, v53, v53
	v_mul_f32_e32 v59, v59, v59
	v_fmac_f32_e32 v50, v52, v52
	v_mul_f32_e32 v52, v55, v55
	v_fmac_f32_e32 v59, v58, v58
	v_mul_f32_e32 v58, v61, v61
	v_fmac_f32_e32 v52, v54, v54
	v_mul_f32_e32 v49, v49, v49
	v_fmac_f32_e32 v58, v60, v60
	v_mul_f32_e32 v60, v63, v63
	v_add_f32_e32 v50, v50, v52
	v_fmac_f32_e32 v49, v48, v48
	v_fmac_f32_e32 v60, v62, v62
	v_mul_f32_e32 v57, v57, v57
	v_add_f32_e32 v48, v50, v49
	v_and_b32_e32 v50, 64, v174
	v_add_f32_e32 v58, v58, v60
	v_fmac_f32_e32 v57, v56, v56
	v_xor_b32_e32 v49, 16, v174
	v_add_u32_e32 v50, 64, v50
	v_add_f32_e32 v56, v58, v57
	v_cmp_lt_i32_e32 vcc, v49, v50
	v_add_f32_e32 v56, v59, v56
	v_add_f32_e32 v48, v51, v48
	v_cndmask_b32_e32 v49, v174, v49, vcc
	v_add_f32_e32 v48, v56, v48
	v_lshlrev_b32_e32 v49, 2, v49
	ds_bpermute_b32 v49, v49, v48
	s_waitcnt lgkmcnt(0)
	v_add_f32_e32 v48, v48, v49
	v_xor_b32_e32 v49, 32, v174
	v_cmp_lt_i32_e32 vcc, v49, v50
	s_nop 1
	v_cndmask_b32_e32 v49, v174, v49, vcc
	v_lshlrev_b32_e32 v49, 2, v49
	ds_bpermute_b32 v49, v49, v48
	s_and_saveexec_b64 s[28:29], s[0:1]
	s_cbranch_execz .LBB0_612
	v_lshlrev_b64 v[50:51], 7, v[82:83]
	v_lshl_add_u64 v[50:51], s[24:25], 0, v[50:51]
	v_lshl_add_u64 v[50:51], s[26:27], 2, v[50:51]
	s_lshl_b32 s8, s41, 2
	v_lshl_add_u64 v[50:51], v[50:51], 0, s[8:9]
	s_waitcnt lgkmcnt(0)
	v_add_f32_e32 v48, v48, v49
	global_store_dword v[50:51], v48, off

;     __device__ __forceinline__ void operator()(const f32x4 (&acc)[2][2][4][2], const Unit& u, int wr, int wc, int fr, int fq) const {
;     ...
;                 for (int m = 0; m < 4; m += 2) {
;                     f32x4 bs[2][2][2];
; #pragma unroll
;                     for (int mm = 0; mm < 2; ++mm) { const size_t off = (size_t)(row0 + ai * HALF + (m + mm) * 16) * DM + col0;
; #pragma unroll
;                         for (int bj = 0; bj < 2; ++bj)
; #pragma unroll
;                             for (int n = 0; n < 2; ++n) bs[mm][bj][n] = *(const f32x4*)(basef + off + bj * HALF + n * 4); }
; #pragma unroll
;                     for (int mm = 0; mm < 2; ++mm) { const size_t off = (size_t)(row0 + ai * HALF + (m + mm) * 16) * DM + col0;
;                         float ss = 0.f;
; #pragma unroll
;                         for (int bj = 0; bj < 2; ++bj) { const f32x4 v0 = bs[mm][bj][0] + acc[ai][bj][m + mm][0], v1 = bs[mm][bj][1] + acc[ai][bj][m + mm][1];
;                             ss += (v0[0] * v0[0] + v0[1] * v0[1]) + (v0[2] * v0[2] + v0[3] * v0[3]) + (v1[0] * v1[0] + v1[1] * v1[1]) + (v1[2] * v1[2] + v1[3] * v1[3]);
;                             u32x4 w; w.x = pk2(v0[0], v0[1]); w.y = pk2(v0[2], v0[3]); w.z = pk2(v1[0], v1[1]); w.w = pk2(v1[2], v1[3]);
;                             *(u32x4*)(out + off + bj * HALF) = w; }
;                         if (ssqp) { ss += __shfl_xor(ss, 16); ss += __shfl_xor(ss, 32); if (fq == 0) ssqp[(size_t)(row0 + ai * HALF + (m + mm) * 16) * 32 + u.pn * 4 + wc] = ss; } }
.LBB0_617:
	s_nop 0
	v_add_u32_e32 v50, 0xa0, v162
	v_ashrrev_i32_e32 v51, 31, v50
	s_waitcnt lgkmcnt(0)
	v_lshlrev_b64 v[32:33], 13, v[50:51]
	v_add_u32_e32 v48, 0xb0, v162
	v_lshl_add_u64 v[32:33], v[164:165], 0, v[32:33]
	v_ashrrev_i32_e32 v49, 31, v48
	global_load_dwordx4 v[52:55], v[32:33], off nt
	global_load_dwordx4 v[56:59], v[32:33], off offset:16 nt
	global_load_dwordx4 v[60:63], v[32:33], off offset:512 nt
	global_load_dwordx4 v[64:67], v[32:33], off offset:528 nt
	v_lshlrev_b64 v[32:33], 13, v[48:49]
	v_lshl_add_u64 v[36:37], v[164:165], 0, v[32:33]
	global_load_dwordx4 v[40:43], v[36:37], off offset:16 nt
	global_load_dwordx4 v[44:47], v[36:37], off nt
	global_load_dwordx4 v[32:35], v[36:37], off offset:528 nt
	s_nop 0
	global_load_dwordx4 v[36:39], v[36:37], off offset:512 nt
	v_lshlrev_b64 v[68:69], 12, v[50:51]
	v_lshl_add_u64 v[68:69], s[22:23], 0, v[68:69]
	s_and_b64 vcc, exec, s[6:7]
	v_lshl_add_u64 v[68:69], v[160:161], 1, v[68:69]
	s_waitcnt vmcnt(7)
	v_pk_add_f32 v[30:31], v[30:31], v[54:55]
	v_pk_add_f32 v[28:29], v[28:29], v[52:53]
	s_waitcnt vmcnt(6)
	v_pk_add_f32 v[26:27], v[26:27], v[58:59]
	v_pk_add_f32 v[24:25], v[24:25], v[56:57]
	s_waitcnt vmcnt(5)
	v_pk_add_f32 v[22:23], v[22:23], v[62:63]
	v_pk_add_f32 v[20:21], v[20:21], v[60:61]
	s_waitcnt vmcnt(4)
	v_pk_add_f32 v[18:19], v[18:19], v[66:67]
	v_pk_add_f32 v[16:17], v[16:17], v[64:65]
	v_cvt_pk_bf16_f32 v52, v28, v29
	v_cvt_pk_bf16_f32 v53, v30, v31
	v_cvt_pk_bf16_f32 v54, v24, v25
	v_cvt_pk_bf16_f32 v55, v26, v27
	v_cvt_pk_bf16_f32 v56, v20, v21
	v_cvt_pk_bf16_f32 v57, v22, v23
	v_cvt_pk_bf16_f32 v58, v16, v17
	v_cvt_pk_bf16_f32 v59, v18, v19
	global_store_dwordx4 v[68:69], v[52:55], off sc0 sc1
	global_store_dwordx4 v[68:69], v[56:59], off offset:256 sc0 sc1
	s_cbranch_vccnz .LBB0_621
	v_mul_f32_e32 v19, v19, v19
	v_fmac_f32_e32 v19, v18, v18
	v_mul_f32_e32 v18, v21, v21
	v_mul_f32_e32 v27, v27, v27
	v_fmac_f32_e32 v18, v20, v20
	v_mul_f32_e32 v20, v23, v23
	v_fmac_f32_e32 v27, v26, v26
	v_mul_f32_e32 v26, v29, v29
	v_fmac_f32_e32 v20, v22, v22
	v_mul_f32_e32 v17, v17, v17
	v_fmac_f32_e32 v26, v28, v28
	v_mul_f32_e32 v28, v31, v31
	v_add_f32_e32 v18, v18, v20
	v_fmac_f32_e32 v17, v16, v16
	v_fmac_f32_e32 v28, v30, v30
	v_mul_f32_e32 v25, v25, v25
	v_add_f32_e32 v16, v18, v17
	v_and_b32_e32 v18, 64, v174
	v_add_f32_e32 v26, v26, v28
	v_fmac_f32_e32 v25, v24, v24
	v_xor_b32_e32 v17, 16, v174
	v_add_u32_e32 v18, 64, v18
	v_add_f32_e32 v24, v26, v25
	v_cmp_lt_i32_e32 vcc, v17, v18
	v_add_f32_e32 v24, v27, v24
	v_add_f32_e32 v16, v19, v16
	v_cndmask_b32_e32 v17, v174, v17, vcc
	v_add_f32_e32 v16, v24, v16
	v_lshlrev_b32_e32 v17, 2, v17
	ds_bpermute_b32 v17, v17, v16
	s_waitcnt lgkmcnt(0)
	v_add_f32_e32 v16, v16, v17
	v_xor_b32_e32 v17, 32, v174
	v_cmp_lt_i32_e32 vcc, v17, v18
	s_nop 1
	v_cndmask_b32_e32 v17, v174, v17, vcc
	v_lshlrev_b32_e32 v17, 2, v17
	ds_bpermute_b32 v17, v17, v16
	s_and_saveexec_b64 s[28:29], s[0:1]
	s_cbranch_execz .LBB0_620
	v_lshlrev_b64 v[18:19], 7, v[50:51]
	v_lshl_add_u64 v[18:19], s[24:25], 0, v[18:19]
	v_lshl_add_u64 v[18:19], s[26:27], 2, v[18:19]
	s_lshl_b32 s8, s41, 2
	v_lshl_add_u64 v[18:19], v[18:19], 0, s[8:9]
	s_waitcnt lgkmcnt(0)
	v_add_f32_e32 v16, v16, v17
	global_store_dword v[18:19], v16, off

; #define PG8_STAGE(bufoff, gbase, voff) do { _Pragma("unroll") for (int _i = 0; _i < 2; ++_i) \
;         __builtin_amdgcn_global_load_lds((const unsigned*)((const char*)(gbase) + (voff)[_i]), (LAS unsigned*)(lds + (bufoff) + ldsw + _i * 8192), 16, 0, 0); } while (0)
; #define PG8_LDA(dst, b, h) do { _Pragma("unroll") for (int m = 0; m < 4; ++m) _Pragma("unroll") for (int k = 0; k < 2; ++k) dst[m][k] = *(const LAS bf16x8*)(lds + PG8_SA(b, h) + aoff + m * 2048 + k * 1024); } while (0)
; #define PG8_LDB(dst, b, h) do { _Pragma("unroll") for (int n = 0; n < 2; ++n) _Pragma("unroll") for (int k = 0; k < 2; ++k) dst[n][k] = *(const LAS bf16x8*)(lds + PG8_SB(b, h) + boff + n * 2048 + k * 1024); } while (0)
; #define PG8_MMA(ai, bj, At, Bt) do { __builtin_amdgcn_s_setprio(1); _Pragma("unroll") for (int m = 0; m < 4; ++m) _Pragma("unroll") for (int n = 0; n < 2; ++n) _Pragma("unroll") for (int k = 0; k < 2; ++k) \
;         acc[ai][bj][m][n] = __builtin_amdgcn_mfma_f32_16x16x32_bf16(Bt[n][k], At[m][k], acc[ai][bj][m][n], 0, 0, 0); __builtin_amdgcn_s_setprio(0); } while (0)
; #define PG8_WAIT_L(n) asm volatile("s_waitcnt lgkmcnt(" #n ")" ::: "memory")
; #define PG8_BAR __builtin_amdgcn_s_barrier()
; #define PG8_SCHED __builtin_amdgcn_sched_barrier(0)
; template <class Epi>
; __device__ __forceinline__ void gemm_phase(LAS unsigned char* lds, const Gemm g, const Order& S, const Epi& E, const int tid) {
;     ...
;         for (int t = 0; t < nt; t += 2) {
;             const bool last = (t == nt - 2);
;             const char* a1 = cA + (size_t)(t + 1) * kstep;
;             const char* a2 = last ? nA : cA + (size_t)(t + 2) * kstep; const char* b2 = last ? nB : cB + (size_t)(t + 2) * kstep;
;             const char* a3 = a2 + kstep; const char* b3 = b2 + kstep;
;             PG8_LDB(B0, 0, 0); PG8_SCHED; PG8_LDA(At, 0, 0); PG8_STAGE(PG8_SA(1, 1), a1 + hstepA, voffA);
;             PG8_WAIT_L(8); PG8_BAR; PG8_WAIT_L(0); PG8_MMA(0, 0, At, B0); PG8_BAR; PG8_SCHED;
;             PG8_LDB(B1, 0, 1); PG8_STAGE(PG8_SB(0, 0), b2, voffB);
;             PG8_BAR; PG8_WAIT_L(0); PG8_MMA(0, 1, At, B1); PG8_BAR;
;             PG8_LDA(At, 0, 1); PG8_STAGE(PG8_SA(0, 0), a2, voffA);
;             PG8_BAR; PG8_WAIT_L(0); PG8_MMA(1, 0, At, B0); PG8_BAR; PG8_SCHED;
.LBB0_688:
	ds_read_b128 v[128:131], v189
	ds_read_b128 v[132:135], v189 offset:1024
	ds_read_b128 v[136:139], v189 offset:2048
	ds_read_b128 v[140:143], v189 offset:3072
	s_add_u32 s28, s26, 0xffe00080
	s_addc_u32 s29, s27, -1
	s_cmpk_eq_i32 s51, 0x7c
	s_cselect_b32 s31, s7, s29
	s_cselect_b32 s30, s15, s28
	s_cselect_b32 s29, s17, s50
	s_cselect_b32 s28, s48, s49
	v_lshl_add_u64 v[184:185], s[26:27], 0, v[160:161]
	s_add_i32 m0, s34, 0xc000
	ds_read_b128 v[144:147], v190
	ds_read_b128 v[148:151], v190 offset:1024
	ds_read_b128 v[168:171], v190 offset:2048
	ds_read_b128 v[172:175], v190 offset:3072
	ds_read_b128 v[176:179], v190 offset:4096
	ds_read_b128 v[180:183], v190 offset:5120
	ds_read_b128 v[194:197], v190 offset:6144
	ds_read_b128 v[198:201], v190 offset:7168
	global_load_lds_dwordx4 v[184:185], off
	v_lshl_add_u64 v[184:185], s[26:27], 0, v[162:163]
	s_add_i32 m0, s34, 0xe000
	s_nop 0
	global_load_lds_dwordx4 v[184:185], off
	s_waitcnt lgkmcnt(8)
	s_barrier
	s_waitcnt lgkmcnt(0)
	s_setprio 1
	s_waitcnt lgkmcnt(0)
	v_mfma_f32_16x16x32_bf16 v[124:127], v[128:131], v[144:147], v[124:127]
	v_mfma_f32_16x16x32_bf16 v[120:123], v[136:139], v[144:147], v[120:123]
	v_mfma_f32_16x16x32_bf16 v[108:111], v[128:131], v[168:171], v[108:111]
	v_mfma_f32_16x16x32_bf16 v[104:107], v[136:139], v[168:171], v[104:107]
	v_mfma_f32_16x16x32_bf16 v[92:95], v[128:131], v[176:179], v[92:95]
	v_mfma_f32_16x16x32_bf16 v[88:91], v[136:139], v[176:179], v[88:91]
	v_mfma_f32_16x16x32_bf16 v[76:79], v[128:131], v[194:197], v[76:79]
	v_mfma_f32_16x16x32_bf16 v[72:75], v[136:139], v[194:197], v[72:75]
	v_mfma_f32_16x16x32_bf16 v[124:127], v[132:135], v[148:151], v[124:127]
	v_mfma_f32_16x16x32_bf16 v[120:123], v[140:143], v[148:151], v[120:123]
	v_mfma_f32_16x16x32_bf16 v[108:111], v[132:135], v[172:175], v[108:111]
	v_mfma_f32_16x16x32_bf16 v[104:107], v[140:143], v[172:175], v[104:107]
	v_mfma_f32_16x16x32_bf16 v[92:95], v[132:135], v[180:183], v[92:95]
	v_mfma_f32_16x16x32_bf16 v[88:91], v[140:143], v[180:183], v[88:91]
	v_mfma_f32_16x16x32_bf16 v[76:79], v[132:135], v[198:201], v[76:79]
	v_mfma_f32_16x16x32_bf16 v[72:75], v[140:143], v[198:201], v[72:75]
	s_setprio 0
	s_barrier
	s_add_i32 s52, s45, s33
	v_lshl_add_u64 v[184:185], s[28:29], 0, v[154:155]
	s_mov_b32 m0, s52
	ds_read_b128 v[202:205], v191
	ds_read_b128 v[206:209], v191 offset:1024
	ds_read_b128 v[210:213], v191 offset:2048
	ds_read_b128 v[214:217], v191 offset:3072
	global_load_lds_dwordx4 v[184:185], off
	v_lshl_add_u64 v[218:219], s[28:29], 0, v[158:159]
	s_add_i32 m0, s52, 0x2000
	s_nop 0
	global_load_lds_dwordx4 v[218:219], off
	s_barrier
	s_waitcnt lgkmcnt(0)
	s_setprio 1
	s_waitcnt lgkmcnt(0)
	v_mfma_f32_16x16x32_bf16 v[116:119], v[202:205], v[144:147], v[116:119]
	v_mfma_f32_16x16x32_bf16 v[112:115], v[210:213], v[144:147], v[112:115]
	v_mfma_f32_16x16x32_bf16 v[100:103], v[202:205], v[168:171], v[100:103]
	v_mfma_f32_16x16x32_bf16 v[96:99], v[210:213], v[168:171], v[96:99]
	v_mfma_f32_16x16x32_bf16 v[84:87], v[202:205], v[176:179], v[84:87]
	v_mfma_f32_16x16x32_bf16 v[80:83], v[210:213], v[176:179], v[80:83]
	v_mfma_f32_16x16x32_bf16 v[68:71], v[202:205], v[194:197], v[68:71]
	v_mfma_f32_16x16x32_bf16 v[64:67], v[210:213], v[194:197], v[64:67]
	v_mfma_f32_16x16x32_bf16 v[116:119], v[206:209], v[148:151], v[116:119]
	v_mfma_f32_16x16x32_bf16 v[112:115], v[214:217], v[148:151], v[112:115]
	v_mfma_f32_16x16x32_bf16 v[100:103], v[206:209], v[172:175], v[100:103]
	v_mfma_f32_16x16x32_bf16 v[96:99], v[214:217], v[172:175], v[96:99]
	v_mfma_f32_16x16x32_bf16 v[84:87], v[206:209], v[180:183], v[84:87]
	v_mfma_f32_16x16x32_bf16 v[80:83], v[214:217], v[180:183], v[80:83]
	v_mfma_f32_16x16x32_bf16 v[68:71], v[206:209], v[198:201], v[68:71]
	v_mfma_f32_16x16x32_bf16 v[64:67], v[214:217], v[198:201], v[64:67]
	s_setprio 0
	s_mov_b32 m0, s34
	v_lshl_add_u64 v[220:221], s[30:31], 0, v[152:153]
	s_barrier
	ds_read_b128 v[144:147], v190 offset:16384
	ds_read_b128 v[148:151], v190 offset:17408
	ds_read_b128 v[168:171], v190 offset:18432
	ds_read_b128 v[172:175], v190 offset:19456
	ds_read_b128 v[176:179], v190 offset:20480
	ds_read_b128 v[180:183], v190 offset:21504
	ds_read_b128 v[194:197], v190 offset:22528
	ds_read_b128 v[198:201], v190 offset:23552
	global_load_lds_dwordx4 v[220:221], off
	v_lshl_add_u64 v[222:223], s[30:31], 0, v[156:157]
	s_mov_b32 m0, s35
	s_nop 0
	global_load_lds_dwordx4 v[222:223], off
	s_barrier
	s_waitcnt lgkmcnt(0)
	s_setprio 1
	s_waitcnt lgkmcnt(0)
	v_mfma_f32_16x16x32_bf16 v[60:63], v[128:131], v[144:147], v[60:63]
	v_mfma_f32_16x16x32_bf16 v[56:59], v[136:139], v[144:147], v[56:59]
	v_mfma_f32_16x16x32_bf16 v[44:47], v[128:131], v[168:171], v[44:47]
	v_mfma_f32_16x16x32_bf16 v[40:43], v[136:139], v[168:171], v[40:43]
	v_mfma_f32_16x16x32_bf16 v[28:31], v[128:131], v[176:179], v[28:31]
	v_mfma_f32_16x16x32_bf16 v[24:27], v[136:139], v[176:179], v[24:27]
	v_mfma_f32_16x16x32_bf16 v[12:15], v[128:131], v[194:197], v[12:15]
	v_mfma_f32_16x16x32_bf16 v[8:11], v[136:139], v[194:197], v[8:11]
	v_mfma_f32_16x16x32_bf16 v[60:63], v[132:135], v[148:151], v[60:63]
	v_mfma_f32_16x16x32_bf16 v[56:59], v[140:143], v[148:151], v[56:59]
	v_mfma_f32_16x16x32_bf16 v[44:47], v[132:135], v[172:175], v[44:47]
	v_mfma_f32_16x16x32_bf16 v[40:43], v[140:143], v[172:175], v[40:43]
	v_mfma_f32_16x16x32_bf16 v[28:31], v[132:135], v[180:183], v[28:31]
	v_mfma_f32_16x16x32_bf16 v[24:27], v[140:143], v[180:183], v[24:27]
	v_mfma_f32_16x16x32_bf16 v[12:15], v[132:135], v[198:201], v[12:15]
	v_mfma_f32_16x16x32_bf16 v[8:11], v[140:143], v[198:201], v[8:11]
	s_setprio 0
	s_barrier
; #define PG8_STAGE(bufoff, gbase, voff) do { _Pragma("unroll") for (int _i = 0; _i < 2; ++_i) \
;         __builtin_amdgcn_global_load_lds((const unsigned*)((const char*)(gbase) + (voff)[_i]), (LAS unsigned*)(lds + (bufoff) + ldsw + _i * 8192), 16, 0, 0); } while (0)
; #define PG8_LDA(dst, b, h) do { _Pragma("unroll") for (int m = 0; m < 4; ++m) _Pragma("unroll") for (int k = 0; k < 2; ++k) dst[m][k] = *(const LAS bf16x8*)(lds + PG8_SA(b, h) + aoff + m * 2048 + k * 1024); } while (0)
; #define PG8_LDB(dst, b, h) do { _Pragma("unroll") for (int n = 0; n < 2; ++n) _Pragma("unroll") for (int k = 0; k < 2; ++k) dst[n][k] = *(const LAS bf16x8*)(lds + PG8_SB(b, h) + boff + n * 2048 + k * 1024); } while (0)
; #define PG8_MMA(ai, bj, At, Bt) do { __builtin_amdgcn_s_setprio(1); _Pragma("unroll") for (int m = 0; m < 4; ++m) _Pragma("unroll") for (int n = 0; n < 2; ++n) _Pragma("unroll") for (int k = 0; k < 2; ++k) \
;         acc[ai][bj][m][n] = __builtin_amdgcn_mfma_f32_16x16x32_bf16(Bt[n][k], At[m][k], acc[ai][bj][m][n], 0, 0, 0); __builtin_amdgcn_s_setprio(0); } while (0)
; #define PG8_WAIT_V(n) asm volatile("s_waitcnt vmcnt(" #n ")" ::: "memory")
; #define PG8_WAIT_L(n) asm volatile("s_waitcnt lgkmcnt(" #n ")" ::: "memory")
; #define PG8_BAR __builtin_amdgcn_s_barrier()
; #define PG8_SCHED __builtin_amdgcn_sched_barrier(0)
; template <class Epi>
; __device__ __forceinline__ void gemm_phase(LAS unsigned char* lds, const Gemm g, const Order& S, const Epi& E, const int tid) {
;     ...
;             PG8_STAGE(PG8_SB(0, 1), b2 + hstepB, voffB);
;             PG8_WAIT_V(6); PG8_BAR; PG8_MMA(1, 1, At, B1); PG8_BAR;
;             PG8_LDB(B0, 1, 0); PG8_SCHED; PG8_LDA(At, 1, 0); PG8_STAGE(PG8_SA(0, 1), a2 + hstepA, voffA);
;             PG8_WAIT_L(8); PG8_BAR; PG8_WAIT_L(0); PG8_MMA(0, 0, At, B0); PG8_BAR; PG8_SCHED;
;             PG8_LDB(B1, 1, 1); PG8_STAGE(PG8_SB(1, 0), b3, voffB);
;             PG8_BAR; PG8_WAIT_L(0); PG8_MMA(0, 1, At, B1); PG8_BAR;
;             PG8_LDA(At, 1, 1); PG8_STAGE(PG8_SA(1, 0), a3, voffA);
	s_add_u32 s52, s28, 0x200000
	s_addc_u32 s53, s29, 0
	s_add_i32 s55, s46, s33
	v_lshl_add_u64 v[128:129], s[52:53], 0, v[154:155]
	s_mov_b32 m0, s55
	s_nop 0
	global_load_lds_dwordx4 v[128:129], off
	v_lshl_add_u64 v[128:129], s[52:53], 0, v[158:159]
	s_add_i32 m0, s55, 0x2000
	s_nop 0
	global_load_lds_dwordx4 v[128:129], off
	s_waitcnt vmcnt(6)
	s_barrier
	s_setprio 1
	v_mfma_f32_16x16x32_bf16 v[52:55], v[202:205], v[144:147], v[52:55]
	v_mfma_f32_16x16x32_bf16 v[48:51], v[210:213], v[144:147], v[48:51]
	v_mfma_f32_16x16x32_bf16 v[36:39], v[202:205], v[168:171], v[36:39]
	v_mfma_f32_16x16x32_bf16 v[32:35], v[210:213], v[168:171], v[32:35]
	v_mfma_f32_16x16x32_bf16 v[20:23], v[202:205], v[176:179], v[20:23]
	v_mfma_f32_16x16x32_bf16 v[16:19], v[210:213], v[176:179], v[16:19]
	v_mfma_f32_16x16x32_bf16 v[4:7], v[202:205], v[194:197], v[4:7]
	v_mfma_f32_16x16x32_bf16 v[0:3], v[210:213], v[194:197], v[0:3]
	v_mfma_f32_16x16x32_bf16 v[52:55], v[206:209], v[148:151], v[52:55]
	v_mfma_f32_16x16x32_bf16 v[48:51], v[214:217], v[148:151], v[48:51]
	v_mfma_f32_16x16x32_bf16 v[36:39], v[206:209], v[172:175], v[36:39]
	v_mfma_f32_16x16x32_bf16 v[32:35], v[214:217], v[172:175], v[32:35]
	v_mfma_f32_16x16x32_bf16 v[20:23], v[206:209], v[180:183], v[20:23]
	v_mfma_f32_16x16x32_bf16 v[16:19], v[214:217], v[180:183], v[16:19]
	v_mfma_f32_16x16x32_bf16 v[4:7], v[206:209], v[198:201], v[4:7]
	v_mfma_f32_16x16x32_bf16 v[0:3], v[214:217], v[198:201], v[0:3]
	s_setprio 0
	s_add_i32 s52, 0, 0x18000
	v_add_u32_e32 v140, s52, v187
	s_barrier
	ds_read_b128 v[128:131], v140
	ds_read_b128 v[132:135], v140 offset:1024
	ds_read_b128 v[136:139], v140 offset:2048
	ds_read_b128 v[140:143], v140 offset:3072
	s_add_u32 s30, s30, 0x200000
	s_addc_u32 s31, s31, 0
	s_mov_b32 m0, s39
	v_lshl_add_u64 v[202:203], s[30:31], 0, v[152:153]
	ds_read_b128 v[144:147], v190 offset:32768
	ds_read_b128 v[148:151], v190 offset:33792
	ds_read_b128 v[168:171], v190 offset:34816
	ds_read_b128 v[172:175], v190 offset:35840
	ds_read_b128 v[176:179], v190 offset:36864
	ds_read_b128 v[180:183], v190 offset:37888
	ds_read_b128 v[194:197], v190 offset:38912
	ds_read_b128 v[198:201], v190 offset:39936
	global_load_lds_dwordx4 v[202:203], off
	v_lshl_add_u64 v[202:203], s[30:31], 0, v[156:157]
	s_mov_b32 m0, s40
	s_nop 0
	global_load_lds_dwordx4 v[202:203], off
	s_waitcnt lgkmcnt(8)
	s_barrier
	s_waitcnt lgkmcnt(0)
	s_setprio 1
	s_waitcnt lgkmcnt(0)
	v_mfma_f32_16x16x32_bf16 v[124:127], v[128:131], v[144:147], v[124:127]
	v_mfma_f32_16x16x32_bf16 v[120:123], v[136:139], v[144:147], v[120:123]
	v_mfma_f32_16x16x32_bf16 v[108:111], v[128:131], v[168:171], v[108:111]
	v_mfma_f32_16x16x32_bf16 v[104:107], v[136:139], v[168:171], v[104:107]
	v_mfma_f32_16x16x32_bf16 v[92:95], v[128:131], v[176:179], v[92:95]
	v_mfma_f32_16x16x32_bf16 v[88:91], v[136:139], v[176:179], v[88:91]
	v_mfma_f32_16x16x32_bf16 v[76:79], v[128:131], v[194:197], v[76:79]
	v_mfma_f32_16x16x32_bf16 v[72:75], v[136:139], v[194:197], v[72:75]
	v_mfma_f32_16x16x32_bf16 v[124:127], v[132:135], v[148:151], v[124:127]
	v_mfma_f32_16x16x32_bf16 v[120:123], v[140:143], v[148:151], v[120:123]
	v_mfma_f32_16x16x32_bf16 v[108:111], v[132:135], v[172:175], v[108:111]
	v_mfma_f32_16x16x32_bf16 v[104:107], v[140:143], v[172:175], v[104:107]
	v_mfma_f32_16x16x32_bf16 v[92:95], v[132:135], v[180:183], v[92:95]
	v_mfma_f32_16x16x32_bf16 v[88:91], v[140:143], v[180:183], v[88:91]
	v_mfma_f32_16x16x32_bf16 v[76:79], v[132:135], v[198:201], v[76:79]
	v_mfma_f32_16x16x32_bf16 v[72:75], v[140:143], v[198:201], v[72:75]
	s_setprio 0
	s_barrier
	s_add_i32 s30, 0, 0x1c000
	s_add_i32 s31, s52, s33
	v_add_u32_e32 v193, s30, v187
	v_lshl_add_u64 v[184:185], v[184:185], 0, s[12:13]
	s_mov_b32 m0, s31
	ds_read_b128 v[202:205], v193
	ds_read_b128 v[206:209], v193 offset:1024
	ds_read_b128 v[210:213], v193 offset:2048
	ds_read_b128 v[214:217], v193 offset:3072
	global_load_lds_dwordx4 v[184:185], off
	v_lshl_add_u64 v[184:185], v[218:219], 0, s[12:13]
	s_add_i32 m0, s31, 0x2000
	s_nop 0
	global_load_lds_dwordx4 v[184:185], off
	s_barrier
	s_waitcnt lgkmcnt(0)
	s_setprio 1
	s_waitcnt lgkmcnt(0)
	v_mfma_f32_16x16x32_bf16 v[116:119], v[202:205], v[144:147], v[116:119]
	v_mfma_f32_16x16x32_bf16 v[112:115], v[210:213], v[144:147], v[112:115]
	v_mfma_f32_16x16x32_bf16 v[100:103], v[202:205], v[168:171], v[100:103]
	v_mfma_f32_16x16x32_bf16 v[96:99], v[210:213], v[168:171], v[96:99]
	v_mfma_f32_16x16x32_bf16 v[84:87], v[202:205], v[176:179], v[84:87]
	v_mfma_f32_16x16x32_bf16 v[80:83], v[210:213], v[176:179], v[80:83]
	v_mfma_f32_16x16x32_bf16 v[68:71], v[202:205], v[194:197], v[68:71]
	v_mfma_f32_16x16x32_bf16 v[64:67], v[210:213], v[194:197], v[64:67]
	v_mfma_f32_16x16x32_bf16 v[116:119], v[206:209], v[148:151], v[116:119]
	v_mfma_f32_16x16x32_bf16 v[112:115], v[214:217], v[148:151], v[112:115]
	v_mfma_f32_16x16x32_bf16 v[100:103], v[206:209], v[172:175], v[100:103]
	v_mfma_f32_16x16x32_bf16 v[96:99], v[214:217], v[172:175], v[96:99]
	v_mfma_f32_16x16x32_bf16 v[84:87], v[206:209], v[180:183], v[84:87]
	v_mfma_f32_16x16x32_bf16 v[80:83], v[214:217], v[180:183], v[80:83]
	v_mfma_f32_16x16x32_bf16 v[68:71], v[206:209], v[198:201], v[68:71]
	v_mfma_f32_16x16x32_bf16 v[64:67], v[214:217], v[198:201], v[64:67]
	s_setprio 0
	s_mov_b32 m0, s43
	v_lshl_add_u64 v[184:185], v[220:221], 0, s[12:13]
	s_barrier
	ds_read_b128 v[144:147], v190 offset:49152
	ds_read_b128 v[148:151], v190 offset:50176
	ds_read_b128 v[168:171], v190 offset:51200
	ds_read_b128 v[172:175], v190 offset:52224
	ds_read_b128 v[176:179], v190 offset:53248
	ds_read_b128 v[180:183], v190 offset:54272
	ds_read_b128 v[194:197], v190 offset:55296
	ds_read_b128 v[198:201], v190 offset:56320
	global_load_lds_dwordx4 v[184:185], off
	v_lshl_add_u64 v[184:185], v[222:223], 0, s[12:13]
	s_mov_b32 m0, s44
	s_nop 0
	global_load_lds_dwordx4 v[184:185], off
	s_barrier
; #define PG8_STAGE(bufoff, gbase, voff) do { _Pragma("unroll") for (int _i = 0; _i < 2; ++_i) \
;         __builtin_amdgcn_global_load_lds((const unsigned*)((const char*)(gbase) + (voff)[_i]), (LAS unsigned*)(lds + (bufoff) + ldsw + _i * 8192), 16, 0, 0); } while (0)
; #define PG8_MMA(ai, bj, At, Bt) do { __builtin_amdgcn_s_setprio(1); _Pragma("unroll") for (int m = 0; m < 4; ++m) _Pragma("unroll") for (int n = 0; n < 2; ++n) _Pragma("unroll") for (int k = 0; k < 2; ++k) \
;         acc[ai][bj][m][n] = __builtin_amdgcn_mfma_f32_16x16x32_bf16(Bt[n][k], At[m][k], acc[ai][bj][m][n], 0, 0, 0); __builtin_amdgcn_s_setprio(0); } while (0)
; #define PG8_WAIT_V(n) asm volatile("s_waitcnt vmcnt(" #n ")" ::: "memory")
; #define PG8_WAIT_L(n) asm volatile("s_waitcnt lgkmcnt(" #n ")" ::: "memory")
; #define PG8_BAR __builtin_amdgcn_s_barrier()
; #define PG8_SCHED __builtin_amdgcn_sched_barrier(0)
; template <class Epi>
; __device__ __forceinline__ void gemm_phase(LAS unsigned char* lds, const Gemm g, const Order& S, const Epi& E, const int tid) {
;     ...
;             PG8_BAR; PG8_WAIT_L(0); PG8_MMA(1, 0, At, B0); PG8_BAR; PG8_SCHED;
;             PG8_STAGE(PG8_SB(1, 1), b3 + hstepB, voffB);
;             PG8_WAIT_V(6); PG8_BAR; PG8_MMA(1, 1, At, B1); PG8_BAR;
	s_waitcnt lgkmcnt(0)
	s_setprio 1
	s_waitcnt lgkmcnt(0)
	v_mfma_f32_16x16x32_bf16 v[60:63], v[128:131], v[144:147], v[60:63]
	v_mfma_f32_16x16x32_bf16 v[56:59], v[136:139], v[144:147], v[56:59]
	v_mfma_f32_16x16x32_bf16 v[44:47], v[128:131], v[168:171], v[44:47]
	v_mfma_f32_16x16x32_bf16 v[40:43], v[136:139], v[168:171], v[40:43]
	v_mfma_f32_16x16x32_bf16 v[28:31], v[128:131], v[176:179], v[28:31]
	v_mfma_f32_16x16x32_bf16 v[24:27], v[136:139], v[176:179], v[24:27]
	v_mfma_f32_16x16x32_bf16 v[12:15], v[128:131], v[194:197], v[12:15]
	v_mfma_f32_16x16x32_bf16 v[8:11], v[136:139], v[194:197], v[8:11]
	v_mfma_f32_16x16x32_bf16 v[60:63], v[132:135], v[148:151], v[60:63]
	v_mfma_f32_16x16x32_bf16 v[56:59], v[140:143], v[148:151], v[56:59]
	v_mfma_f32_16x16x32_bf16 v[44:47], v[132:135], v[172:175], v[44:47]
	v_mfma_f32_16x16x32_bf16 v[40:43], v[140:143], v[172:175], v[40:43]
	v_mfma_f32_16x16x32_bf16 v[28:31], v[132:135], v[180:183], v[28:31]
	v_mfma_f32_16x16x32_bf16 v[24:27], v[140:143], v[180:183], v[24:27]
	v_mfma_f32_16x16x32_bf16 v[12:15], v[132:135], v[198:201], v[12:15]
	v_mfma_f32_16x16x32_bf16 v[8:11], v[140:143], v[198:201], v[8:11]
	s_setprio 0
	s_barrier
	s_add_u32 s28, s28, 0x200080
	s_addc_u32 s29, s29, 0
	s_add_i32 s30, s30, s33
	v_lshl_add_u64 v[128:129], s[28:29], 0, v[154:155]
	s_mov_b32 m0, s30
	s_nop 0
	global_load_lds_dwordx4 v[128:129], off
	v_lshl_add_u64 v[128:129], s[28:29], 0, v[158:159]
	s_add_i32 m0, s30, 0x2000
	s_nop 0
	global_load_lds_dwordx4 v[128:129], off
	s_waitcnt vmcnt(6)
	s_barrier
	s_setprio 1
	v_mfma_f32_16x16x32_bf16 v[52:55], v[202:205], v[144:147], v[52:55]
	v_mfma_f32_16x16x32_bf16 v[48:51], v[210:213], v[144:147], v[48:51]
	v_mfma_f32_16x16x32_bf16 v[36:39], v[202:205], v[168:171], v[36:39]
	v_mfma_f32_16x16x32_bf16 v[32:35], v[210:213], v[168:171], v[32:35]
	v_mfma_f32_16x16x32_bf16 v[20:23], v[202:205], v[176:179], v[20:23]
	v_mfma_f32_16x16x32_bf16 v[16:19], v[210:213], v[176:179], v[16:19]
	v_mfma_f32_16x16x32_bf16 v[4:7], v[202:205], v[194:197], v[4:7]
	v_mfma_f32_16x16x32_bf16 v[0:3], v[210:213], v[194:197], v[0:3]
	v_mfma_f32_16x16x32_bf16 v[52:55], v[206:209], v[148:151], v[52:55]
	v_mfma_f32_16x16x32_bf16 v[48:51], v[214:217], v[148:151], v[48:51]
	v_mfma_f32_16x16x32_bf16 v[36:39], v[206:209], v[172:175], v[36:39]
	v_mfma_f32_16x16x32_bf16 v[32:35], v[214:217], v[172:175], v[32:35]
	v_mfma_f32_16x16x32_bf16 v[20:23], v[206:209], v[180:183], v[20:23]
	v_mfma_f32_16x16x32_bf16 v[16:19], v[214:217], v[180:183], v[16:19]
	v_mfma_f32_16x16x32_bf16 v[4:7], v[206:209], v[198:201], v[4:7]
	v_mfma_f32_16x16x32_bf16 v[0:3], v[214:217], v[198:201], v[0:3]
	s_setprio 0
	s_add_i32 s51, s51, 2
	s_add_u32 s26, s26, 0x100
	s_addc_u32 s27, s27, 0
	s_add_u32 s49, s49, 0x100
	s_addc_u32 s50, s50, 0
	s_cmpk_gt_u32 s51, 0x7d
	s_barrier
	s_cbranch_scc0 .LBB0_688
; __device__ __forceinline__ float bflo(unsigned w) { return __uint_as_float(w << 16); }
; __device__ __forceinline__ float bfhi(unsigned w) { return __uint_as_float(w & 0xffff0000u); }
;     __device__ __forceinline__ void operator()(const f32x4 (&acc)[2][2][4][2], const Unit& u, int wr, int wc, int fr, int fq) const {
;     ...
;                 u32x4 bs[4][2];
; #pragma unroll
;                 for (int m = 0; m < 4; ++m) { const size_t off = (size_t)(row0 + ai * HALF + m * 16) * DM + col0;
; #pragma unroll
;                     for (int bj = 0; bj < 2; ++bj) bs[m][bj] = *(const u32x4*)(baseb + off + bj * HALF); }
; #pragma unroll
;                 for (int m = 0; m < 4; ++m) { const size_t off = (size_t)(row0 + ai * HALF + m * 16) * DM + col0;
;                     float ss = 0.f;
; #pragma unroll
;                     for (int bj = 0; bj < 2; ++bj) { const u32x4 q = bs[m][bj]; const f32x4 a0 = acc[ai][bj][m][0], a1 = acc[ai][bj][m][1];
;                         const float h0 = bflo(q.x) + a0[0], h1 = bfhi(q.x) + a0[1], h2 = bflo(q.y) + a0[2], h3 = bfhi(q.y) + a0[3], h4 = bflo(q.z) + a1[0], h5 = bfhi(q.z) + a1[1], h6 = bflo(q.w) + a1[2], h7 = bfhi(q.w) + a1[3];
;                         ss += (h0 * h0 + h1 * h1) + (h2 * h2 + h3 * h3) + (h4 * h4 + h5 * h5) + (h6 * h6 + h7 * h7);
;                         u32x4 w; w.x = pk2(h0, h1); w.y = pk2(h2, h3); w.z = pk2(h4, h5); w.w = pk2(h6, h7);
;                         *(u32x4*)(out + off + bj * HALF) = w; }
;                     if (ssqp) { ss += __shfl_xor(ss, 16); ss += __shfl_xor(ss, 32); if (fq == 0) ssqp[(size_t)(row0 + ai * HALF + m * 16) * 32 + u.pn * 4 + wc] = ss; } }
	v_lshl_or_b32 v168, s6, 8, v188
	v_lshl_add_u32 v172, s8, 8, v186
	v_ashrrev_i32_e32 v169, 31, v168
	v_lshlrev_b64 v[202:203], 1, v[168:169]
	v_ashrrev_i32_e32 v173, 31, v172
	v_or_b32_e32 v182, 16, v172
	v_or_b32_e32 v178, 32, v172
	v_lshl_add_u64 v[170:171], s[22:23], 0, v[202:203]
	v_lshlrev_b64 v[204:205], 12, v[172:173]
	v_or_b32_e32 v174, 48, v172
	v_ashrrev_i32_e32 v183, 31, v182
	v_ashrrev_i32_e32 v179, 31, v178
	v_lshl_add_u64 v[128:129], v[170:171], 0, v[204:205]
	v_ashrrev_i32_e32 v175, 31, v174
	v_lshlrev_b64 v[184:185], 12, v[182:183]
	v_lshlrev_b64 v[180:181], 12, v[178:179]
	global_load_dwordx4 v[194:197], v[128:129], off nt
	global_load_dwordx4 v[198:201], v[128:129], off offset:256 nt
	v_lshlrev_b64 v[176:177], 12, v[174:175]
	v_lshl_add_u64 v[128:129], v[170:171], 0, v[184:185]
	v_lshl_add_u64 v[130:131], v[170:171], 0, v[180:181]
	v_lshl_add_u64 v[206:207], v[170:171], 0, v[176:177]
	global_load_dwordx4 v[148:151], v[128:129], off nt
	global_load_dwordx4 v[144:147], v[128:129], off offset:256 nt
	global_load_dwordx4 v[140:143], v[130:131], off nt
	global_load_dwordx4 v[136:139], v[130:131], off offset:256 nt
	global_load_dwordx4 v[132:135], v[206:207], off nt
	s_nop 0
	global_load_dwordx4 v[128:131], v[206:207], off offset:256 nt
	v_cndmask_b32_e64 v193, 0, 1, s[10:11]
	v_lshl_add_u64 v[204:205], s[22:23], 0, v[204:205]
	s_lshl_b32 s26, s6, 2
	v_cmp_ne_u32_e64 s[6:7], 1, v193
	v_lshl_add_u64 v[204:205], v[204:205], 0, v[202:203]
	s_ashr_i32 s27, s26, 31
	s_andn2_b64 vcc, exec, s[10:11]
	s_waitcnt vmcnt(0)
	v_lshlrev_b32_e32 v193, 16, v194
	v_and_b32_e32 v194, 0xffff0000, v194
	v_lshlrev_b32_e32 v202, 16, v195
	v_and_b32_e32 v195, 0xffff0000, v195
	v_lshlrev_b32_e32 v203, 16, v196
	v_and_b32_e32 v196, 0xffff0000, v196
	v_lshlrev_b32_e32 v206, 16, v197
	v_and_b32_e32 v197, 0xffff0000, v197
	v_lshlrev_b32_e32 v207, 16, v198
	v_and_b32_e32 v198, 0xffff0000, v198
	v_lshlrev_b32_e32 v208, 16, v199
	v_and_b32_e32 v199, 0xffff0000, v199
	v_lshlrev_b32_e32 v209, 16, v200
	v_and_b32_e32 v200, 0xffff0000, v200
	v_lshlrev_b32_e32 v210, 16, v201
	v_and_b32_e32 v201, 0xffff0000, v201
	v_add_f32_e32 v193, v124, v193
	v_add_f32_e32 v194, v125, v194
	v_add_f32_e32 v124, v126, v202
	v_add_f32_e32 v125, v127, v195
	v_add_f32_e32 v126, v120, v203
	v_add_f32_e32 v127, v121, v196
	v_add_f32_e32 v122, v122, v206
	v_add_f32_e32 v123, v123, v197
	v_add_f32_e32 v120, v116, v207
	v_add_f32_e32 v121, v117, v198
	v_add_f32_e32 v116, v118, v208
	v_add_f32_e32 v117, v119, v199
	v_add_f32_e32 v112, v112, v209
	v_add_f32_e32 v113, v113, v200
	v_add_f32_e32 v114, v114, v210
	v_add_f32_e32 v115, v115, v201
	v_cvt_pk_bf16_f32 v196, v193, v194
	v_cvt_pk_bf16_f32 v197, v124, v125
	v_cvt_pk_bf16_f32 v198, v126, v127
	v_cvt_pk_bf16_f32 v199, v122, v123
	v_cvt_pk_bf16_f32 v200, v120, v121
	v_cvt_pk_bf16_f32 v201, v116, v117
	v_cvt_pk_bf16_f32 v202, v112, v113
	v_cvt_pk_bf16_f32 v203, v114, v115
	global_store_dwordx4 v[204:205], v[196:199], off sc0 sc1
	global_store_dwordx4 v[204:205], v[200:203], off offset:256 sc0 sc1
	s_cbranch_vccnz .LBB0_693
	v_mul_f32_e32 v115, v115, v115
	v_mul_f32_e32 v113, v113, v113
	v_mul_f32_e32 v118, v123, v123
	v_fmac_f32_e32 v115, v114, v114
	v_fmac_f32_e32 v113, v112, v112
	v_mul_f32_e32 v112, v121, v121
	v_mul_f32_e32 v114, v117, v117
	v_fmac_f32_e32 v118, v122, v122
	v_mul_f32_e32 v122, v194, v194
	v_mul_f32_e32 v123, v125, v125
	v_fmac_f32_e32 v112, v120, v120
	v_fmac_f32_e32 v114, v116, v116
	v_mul_f32_e32 v119, v127, v127
	v_fmac_f32_e32 v122, v193, v193
	v_fmac_f32_e32 v123, v124, v124
	v_add_f32_e32 v112, v112, v114
	v_and_b32_e32 v114, 64, v192
	v_fmac_f32_e32 v119, v126, v126
	v_add_f32_e32 v122, v122, v123
	v_add_f32_e32 v112, v113, v112
	v_xor_b32_e32 v113, 16, v192
	v_add_u32_e32 v114, 64, v114
	v_add_f32_e32 v119, v119, v122
	v_cmp_lt_i32_e32 vcc, v113, v114
	v_add_f32_e32 v118, v118, v119
	v_add_f32_e32 v112, v115, v112
	v_cndmask_b32_e32 v113, v192, v113, vcc
	v_add_f32_e32 v112, v118, v112
	v_lshlrev_b32_e32 v113, 2, v113
	ds_bpermute_b32 v113, v113, v112
	s_waitcnt lgkmcnt(0)
	v_add_f32_e32 v112, v112, v113
	v_xor_b32_e32 v113, 32, v192
	v_cmp_lt_i32_e32 vcc, v113, v114
	s_nop 1
	v_cndmask_b32_e32 v113, v192, v113, vcc
	v_lshlrev_b32_e32 v113, 2, v113
	ds_bpermute_b32 v113, v113, v112
	s_and_saveexec_b64 s[28:29], s[0:1]
	s_cbranch_execz .LBB0_692
	v_lshlrev_b64 v[114:115], 7, v[172:173]
	v_lshl_add_u64 v[114:115], s[24:25], 0, v[114:115]
	v_lshl_add_u64 v[114:115], s[26:27], 2, v[114:115]
	s_lshl_b32 s8, s41, 2
	v_lshl_add_u64 v[114:115], v[114:115], 0, s[8:9]
	s_waitcnt lgkmcnt(0)
	v_add_f32_e32 v112, v112, v113
	global_store_dword v[114:115], v112, off

; __device__ __forceinline__ float bflo(unsigned w) { return __uint_as_float(w << 16); }
; __device__ __forceinline__ float bfhi(unsigned w) { return __uint_as_float(w & 0xffff0000u); }
;     __device__ __forceinline__ void operator()(const f32x4 (&acc)[2][2][4][2], const Unit& u, int wr, int wc, int fr, int fq) const {
;     ...
;                 u32x4 bs[4][2];
; #pragma unroll
;                 for (int m = 0; m < 4; ++m) { const size_t off = (size_t)(row0 + ai * HALF + m * 16) * DM + col0;
; #pragma unroll
;                     for (int bj = 0; bj < 2; ++bj) bs[m][bj] = *(const u32x4*)(baseb + off + bj * HALF); }
; #pragma unroll
;                 for (int m = 0; m < 4; ++m) { const size_t off = (size_t)(row0 + ai * HALF + m * 16) * DM + col0;
;                     float ss = 0.f;
; #pragma unroll
;                     for (int bj = 0; bj < 2; ++bj) { const u32x4 q = bs[m][bj]; const f32x4 a0 = acc[ai][bj][m][0], a1 = acc[ai][bj][m][1];
;                         const float h0 = bflo(q.x) + a0[0], h1 = bfhi(q.x) + a0[1], h2 = bflo(q.y) + a0[2], h3 = bfhi(q.y) + a0[3], h4 = bflo(q.z) + a1[0], h5 = bfhi(q.z) + a1[1], h6 = bflo(q.w) + a1[2], h7 = bfhi(q.w) + a1[3];
;                         ss += (h0 * h0 + h1 * h1) + (h2 * h2 + h3 * h3) + (h4 * h4 + h5 * h5) + (h6 * h6 + h7 * h7);
;                         u32x4 w; w.x = pk2(h0, h1); w.y = pk2(h2, h3); w.z = pk2(h4, h5); w.w = pk2(h6, h7);
;                         *(u32x4*)(out + off + bj * HALF) = w; }
;                     if (ssqp) { ss += __shfl_xor(ss, 16); ss += __shfl_xor(ss, 32); if (fq == 0) ssqp[(size_t)(row0 + ai * HALF + m * 16) * 32 + u.pn * 4 + wc] = ss; } }
.LBB0_705:
	v_add_u32_e32 v100, 0x80, v172
	v_ashrrev_i32_e32 v101, 31, v100
	v_add_u32_e32 v96, 0x90, v172
	v_add_u32_e32 v92, 0xa0, v172
	v_lshlrev_b64 v[110:111], 12, v[100:101]
	v_add_u32_e32 v88, 0xb0, v172
	s_waitcnt lgkmcnt(0)
	v_ashrrev_i32_e32 v97, 31, v96
	v_ashrrev_i32_e32 v93, 31, v92
	v_lshl_add_u64 v[64:65], v[170:171], 0, v[110:111]
	v_ashrrev_i32_e32 v89, 31, v88
	v_lshlrev_b64 v[98:99], 12, v[96:97]
	v_lshlrev_b64 v[94:95], 12, v[92:93]
	global_load_dwordx4 v[102:105], v[64:65], off nt
	global_load_dwordx4 v[106:109], v[64:65], off offset:256 nt
	v_lshlrev_b64 v[90:91], 12, v[88:89]
	v_lshl_add_u64 v[64:65], v[170:171], 0, v[98:99]
	v_lshl_add_u64 v[66:67], v[170:171], 0, v[94:95]
	v_lshl_add_u64 v[112:113], v[170:171], 0, v[90:91]
	global_load_dwordx4 v[84:87], v[64:65], off nt
	global_load_dwordx4 v[80:83], v[64:65], off offset:256 nt
	global_load_dwordx4 v[76:79], v[66:67], off nt
	global_load_dwordx4 v[72:75], v[66:67], off offset:256 nt
	global_load_dwordx4 v[68:71], v[112:113], off nt
	s_nop 0
	global_load_dwordx4 v[64:67], v[112:113], off offset:256 nt
	v_lshl_add_u64 v[110:111], s[22:23], 0, v[110:111]
	v_lshl_add_u64 v[112:113], v[168:169], 1, v[110:111]
	s_and_b64 vcc, exec, s[6:7]
	s_waitcnt vmcnt(7)
	v_lshlrev_b32_e32 v110, 16, v102
	v_and_b32_e32 v111, 0xffff0000, v102
	v_lshlrev_b32_e32 v114, 16, v103
	v_and_b32_e32 v115, 0xffff0000, v103
	v_lshlrev_b32_e32 v116, 16, v104
	v_and_b32_e32 v104, 0xffff0000, v104
	v_lshlrev_b32_e32 v117, 16, v105
	v_and_b32_e32 v105, 0xffff0000, v105
	s_waitcnt vmcnt(6)
	v_lshlrev_b32_e32 v118, 16, v106
	v_and_b32_e32 v106, 0xffff0000, v106
	v_lshlrev_b32_e32 v119, 16, v107
	v_and_b32_e32 v107, 0xffff0000, v107
	v_lshlrev_b32_e32 v120, 16, v108
	v_and_b32_e32 v108, 0xffff0000, v108
	v_lshlrev_b32_e32 v121, 16, v109
	v_and_b32_e32 v109, 0xffff0000, v109
	v_add_f32_e32 v102, v60, v110
	v_add_f32_e32 v103, v61, v111
	v_add_f32_e32 v60, v62, v114
	v_add_f32_e32 v61, v63, v115
	v_add_f32_e32 v62, v56, v116
	v_add_f32_e32 v63, v57, v104
	v_add_f32_e32 v58, v58, v117
	v_add_f32_e32 v59, v59, v105
	v_add_f32_e32 v56, v52, v118
	v_add_f32_e32 v57, v53, v106
	v_add_f32_e32 v52, v54, v119
	v_add_f32_e32 v53, v55, v107
	v_add_f32_e32 v48, v48, v120
	v_add_f32_e32 v49, v49, v108
	v_add_f32_e32 v50, v50, v121
	v_add_f32_e32 v51, v51, v109
	v_cvt_pk_bf16_f32 v104, v102, v103
	v_cvt_pk_bf16_f32 v105, v60, v61
	v_cvt_pk_bf16_f32 v106, v62, v63
	v_cvt_pk_bf16_f32 v107, v58, v59
	v_cvt_pk_bf16_f32 v108, v56, v57
	v_cvt_pk_bf16_f32 v109, v52, v53
	v_cvt_pk_bf16_f32 v110, v48, v49
	v_cvt_pk_bf16_f32 v111, v50, v51
	global_store_dwordx4 v[112:113], v[104:107], off sc0 sc1
	global_store_dwordx4 v[112:113], v[108:111], off offset:256 sc0 sc1
	s_cbranch_vccnz .LBB0_709
	v_mul_f32_e32 v51, v51, v51
	v_mul_f32_e32 v49, v49, v49
	v_mul_f32_e32 v54, v59, v59
	v_fmac_f32_e32 v51, v50, v50
	v_fmac_f32_e32 v49, v48, v48
	v_mul_f32_e32 v48, v57, v57
	v_mul_f32_e32 v50, v53, v53
	v_fmac_f32_e32 v54, v58, v58
	v_mul_f32_e32 v58, v103, v103
	v_mul_f32_e32 v59, v61, v61
	v_fmac_f32_e32 v48, v56, v56
	v_fmac_f32_e32 v50, v52, v52
	v_mul_f32_e32 v55, v63, v63
	v_fmac_f32_e32 v58, v102, v102
	v_fmac_f32_e32 v59, v60, v60
	v_add_f32_e32 v48, v48, v50
	v_and_b32_e32 v50, 64, v192
	v_fmac_f32_e32 v55, v62, v62
	v_add_f32_e32 v58, v58, v59
	v_add_f32_e32 v48, v49, v48
	v_xor_b32_e32 v49, 16, v192
	v_add_u32_e32 v50, 64, v50
	v_add_f32_e32 v55, v55, v58
	v_cmp_lt_i32_e32 vcc, v49, v50
	v_add_f32_e32 v54, v54, v55
	v_add_f32_e32 v48, v51, v48
	v_cndmask_b32_e32 v49, v192, v49, vcc
	v_add_f32_e32 v48, v54, v48
	v_lshlrev_b32_e32 v49, 2, v49
	ds_bpermute_b32 v49, v49, v48
	s_waitcnt lgkmcnt(0)
	v_add_f32_e32 v48, v48, v49
	v_xor_b32_e32 v49, 32, v192
	v_cmp_lt_i32_e32 vcc, v49, v50
	s_nop 1
	v_cndmask_b32_e32 v49, v192, v49, vcc
	v_lshlrev_b32_e32 v49, 2, v49
	ds_bpermute_b32 v49, v49, v48
	s_and_saveexec_b64 s[28:29], s[0:1]
	s_cbranch_execz .LBB0_708
	v_lshlrev_b64 v[50:51], 7, v[100:101]
	v_lshl_add_u64 v[50:51], s[24:25], 0, v[50:51]
	v_lshl_add_u64 v[50:51], s[26:27], 2, v[50:51]
	s_lshl_b32 s8, s41, 2
	v_lshl_add_u64 v[50:51], v[50:51], 0, s[8:9]
	s_waitcnt lgkmcnt(0)
	v_add_f32_e32 v48, v48, v49
	global_store_dword v[50:51], v48, off

; #define PG8_STAGE(bufoff, gbase, voff) do { _Pragma("unroll") for (int _i = 0; _i < 2; ++_i) \
;         __builtin_amdgcn_global_load_lds((const unsigned*)((const char*)(gbase) + (voff)[_i]), (LAS unsigned*)(lds + (bufoff) + ldsw + _i * 8192), 16, 0, 0); } while (0)
; #define PG8_LDA(dst, b, h) do { _Pragma("unroll") for (int m = 0; m < 4; ++m) _Pragma("unroll") for (int k = 0; k < 2; ++k) dst[m][k] = *(const LAS bf16x8*)(lds + PG8_SA(b, h) + aoff + m * 2048 + k * 1024); } while (0)
; #define PG8_LDB(dst, b, h) do { _Pragma("unroll") for (int n = 0; n < 2; ++n) _Pragma("unroll") for (int k = 0; k < 2; ++k) dst[n][k] = *(const LAS bf16x8*)(lds + PG8_SB(b, h) + boff + n * 2048 + k * 1024); } while (0)
; #define PG8_MMA(ai, bj, At, Bt) do { __builtin_amdgcn_s_setprio(1); _Pragma("unroll") for (int m = 0; m < 4; ++m) _Pragma("unroll") for (int n = 0; n < 2; ++n) _Pragma("unroll") for (int k = 0; k < 2; ++k) \
;         acc[ai][bj][m][n] = __builtin_amdgcn_mfma_f32_16x16x32_bf16(Bt[n][k], At[m][k], acc[ai][bj][m][n], 0, 0, 0); __builtin_amdgcn_s_setprio(0); } while (0)
; #define PG8_WAIT_L(n) asm volatile("s_waitcnt lgkmcnt(" #n ")" ::: "memory")
; #define PG8_BAR __builtin_amdgcn_s_barrier()
; #define PG8_SCHED __builtin_amdgcn_sched_barrier(0)
; template <class Epi>
; __device__ __forceinline__ void gemm_phase(LAS unsigned char* lds, const Gemm g, const Order& S, const Epi& E, const int tid) {
;     ...
;         for (int t = 0; t < nt; t += 2) {
;             const bool last = (t == nt - 2);
;             const char* a1 = cA + (size_t)(t + 1) * kstep;
;             const char* a2 = last ? nA : cA + (size_t)(t + 2) * kstep; const char* b2 = last ? nB : cB + (size_t)(t + 2) * kstep;
;             const char* a3 = a2 + kstep; const char* b3 = b2 + kstep;
;             PG8_LDB(B0, 0, 0); PG8_SCHED; PG8_LDA(At, 0, 0); PG8_STAGE(PG8_SA(1, 1), a1 + hstepA, voffA);
;             PG8_WAIT_L(8); PG8_BAR; PG8_WAIT_L(0); PG8_MMA(0, 0, At, B0); PG8_BAR; PG8_SCHED;
;             PG8_LDB(B1, 0, 1); PG8_STAGE(PG8_SB(0, 0), b2, voffB);
;             PG8_BAR; PG8_WAIT_L(0); PG8_MMA(0, 1, At, B1); PG8_BAR;
;             PG8_LDA(At, 0, 1); PG8_STAGE(PG8_SA(0, 0), a2, voffA);
;             PG8_BAR; PG8_WAIT_L(0); PG8_MMA(1, 0, At, B0); PG8_BAR; PG8_SCHED;
.LBB0_846:
	ds_read_b128 v[128:131], v189
	ds_read_b128 v[132:135], v189 offset:1024
	ds_read_b128 v[136:139], v189 offset:2048
	ds_read_b128 v[140:143], v189 offset:3072
	s_add_u32 s28, s26, 0xfff80080
	s_addc_u32 s29, s27, -1
	s_cmp_eq_u32 s50, 28
	s_cselect_b32 s31, s7, s29
	s_cselect_b32 s30, s15, s28
	s_cselect_b32 s29, s17, s49
	s_cselect_b32 s28, s47, s48
	v_lshl_add_u64 v[184:185], s[26:27], 0, v[160:161]
	s_add_i32 m0, s34, 0xc000
	ds_read_b128 v[144:147], v190
	ds_read_b128 v[148:151], v190 offset:1024
	ds_read_b128 v[168:171], v190 offset:2048
	ds_read_b128 v[172:175], v190 offset:3072
	ds_read_b128 v[176:179], v190 offset:4096
	ds_read_b128 v[180:183], v190 offset:5120
	ds_read_b128 v[194:197], v190 offset:6144
	ds_read_b128 v[198:201], v190 offset:7168
	global_load_lds_dwordx4 v[184:185], off
	v_lshl_add_u64 v[184:185], s[26:27], 0, v[162:163]
	s_add_i32 m0, s34, 0xe000
	s_nop 0
	global_load_lds_dwordx4 v[184:185], off
	s_waitcnt lgkmcnt(8)
	s_barrier
	s_waitcnt lgkmcnt(0)
	s_setprio 1
	s_waitcnt lgkmcnt(0)
	v_mfma_f32_16x16x32_bf16 v[124:127], v[128:131], v[144:147], v[124:127]
	v_mfma_f32_16x16x32_bf16 v[120:123], v[136:139], v[144:147], v[120:123]
	v_mfma_f32_16x16x32_bf16 v[108:111], v[128:131], v[168:171], v[108:111]
	v_mfma_f32_16x16x32_bf16 v[104:107], v[136:139], v[168:171], v[104:107]
	v_mfma_f32_16x16x32_bf16 v[92:95], v[128:131], v[176:179], v[92:95]
	v_mfma_f32_16x16x32_bf16 v[88:91], v[136:139], v[176:179], v[88:91]
	v_mfma_f32_16x16x32_bf16 v[76:79], v[128:131], v[194:197], v[76:79]
	v_mfma_f32_16x16x32_bf16 v[72:75], v[136:139], v[194:197], v[72:75]
	v_mfma_f32_16x16x32_bf16 v[124:127], v[132:135], v[148:151], v[124:127]
	v_mfma_f32_16x16x32_bf16 v[120:123], v[140:143], v[148:151], v[120:123]
	v_mfma_f32_16x16x32_bf16 v[108:111], v[132:135], v[172:175], v[108:111]
	v_mfma_f32_16x16x32_bf16 v[104:107], v[140:143], v[172:175], v[104:107]
	v_mfma_f32_16x16x32_bf16 v[92:95], v[132:135], v[180:183], v[92:95]
	v_mfma_f32_16x16x32_bf16 v[88:91], v[140:143], v[180:183], v[88:91]
	v_mfma_f32_16x16x32_bf16 v[76:79], v[132:135], v[198:201], v[76:79]
	v_mfma_f32_16x16x32_bf16 v[72:75], v[140:143], v[198:201], v[72:75]
	s_setprio 0
	s_barrier
	s_add_i32 s51, s44, s33
	v_lshl_add_u64 v[184:185], s[28:29], 0, v[154:155]
	s_mov_b32 m0, s51
	ds_read_b128 v[202:205], v191
	ds_read_b128 v[206:209], v191 offset:1024
	ds_read_b128 v[210:213], v191 offset:2048
	ds_read_b128 v[214:217], v191 offset:3072
	global_load_lds_dwordx4 v[184:185], off
	v_lshl_add_u64 v[218:219], s[28:29], 0, v[158:159]
	s_add_i32 m0, s51, 0x2000
	s_nop 0
	global_load_lds_dwordx4 v[218:219], off
	s_barrier
	s_waitcnt lgkmcnt(0)
	s_setprio 1
	s_waitcnt lgkmcnt(0)
	v_mfma_f32_16x16x32_bf16 v[116:119], v[202:205], v[144:147], v[116:119]
	v_mfma_f32_16x16x32_bf16 v[112:115], v[210:213], v[144:147], v[112:115]
	v_mfma_f32_16x16x32_bf16 v[100:103], v[202:205], v[168:171], v[100:103]
	v_mfma_f32_16x16x32_bf16 v[96:99], v[210:213], v[168:171], v[96:99]
	v_mfma_f32_16x16x32_bf16 v[84:87], v[202:205], v[176:179], v[84:87]
	v_mfma_f32_16x16x32_bf16 v[80:83], v[210:213], v[176:179], v[80:83]
	v_mfma_f32_16x16x32_bf16 v[68:71], v[202:205], v[194:197], v[68:71]
	v_mfma_f32_16x16x32_bf16 v[64:67], v[210:213], v[194:197], v[64:67]
	v_mfma_f32_16x16x32_bf16 v[116:119], v[206:209], v[148:151], v[116:119]
	v_mfma_f32_16x16x32_bf16 v[112:115], v[214:217], v[148:151], v[112:115]
	v_mfma_f32_16x16x32_bf16 v[100:103], v[206:209], v[172:175], v[100:103]
	v_mfma_f32_16x16x32_bf16 v[96:99], v[214:217], v[172:175], v[96:99]
	v_mfma_f32_16x16x32_bf16 v[84:87], v[206:209], v[180:183], v[84:87]
	v_mfma_f32_16x16x32_bf16 v[80:83], v[214:217], v[180:183], v[80:83]
	v_mfma_f32_16x16x32_bf16 v[68:71], v[206:209], v[198:201], v[68:71]
	v_mfma_f32_16x16x32_bf16 v[64:67], v[214:217], v[198:201], v[64:67]
	s_setprio 0
	s_mov_b32 m0, s34
	v_lshl_add_u64 v[220:221], s[30:31], 0, v[152:153]
	s_barrier
	ds_read_b128 v[144:147], v190 offset:16384
	ds_read_b128 v[148:151], v190 offset:17408
	ds_read_b128 v[168:171], v190 offset:18432
	ds_read_b128 v[172:175], v190 offset:19456
	ds_read_b128 v[176:179], v190 offset:20480
	ds_read_b128 v[180:183], v190 offset:21504
	ds_read_b128 v[194:197], v190 offset:22528
	ds_read_b128 v[198:201], v190 offset:23552
	global_load_lds_dwordx4 v[220:221], off
	v_lshl_add_u64 v[222:223], s[30:31], 0, v[156:157]
	s_mov_b32 m0, s35
	s_nop 0
	global_load_lds_dwordx4 v[222:223], off
	s_barrier
	s_waitcnt lgkmcnt(0)
	s_setprio 1
	s_waitcnt lgkmcnt(0)
	v_mfma_f32_16x16x32_bf16 v[60:63], v[128:131], v[144:147], v[60:63]
	v_mfma_f32_16x16x32_bf16 v[56:59], v[136:139], v[144:147], v[56:59]
	v_mfma_f32_16x16x32_bf16 v[44:47], v[128:131], v[168:171], v[44:47]
	v_mfma_f32_16x16x32_bf16 v[40:43], v[136:139], v[168:171], v[40:43]
	v_mfma_f32_16x16x32_bf16 v[28:31], v[128:131], v[176:179], v[28:31]
	v_mfma_f32_16x16x32_bf16 v[24:27], v[136:139], v[176:179], v[24:27]
	v_mfma_f32_16x16x32_bf16 v[12:15], v[128:131], v[194:197], v[12:15]
	v_mfma_f32_16x16x32_bf16 v[8:11], v[136:139], v[194:197], v[8:11]
	v_mfma_f32_16x16x32_bf16 v[60:63], v[132:135], v[148:151], v[60:63]
	v_mfma_f32_16x16x32_bf16 v[56:59], v[140:143], v[148:151], v[56:59]
	v_mfma_f32_16x16x32_bf16 v[44:47], v[132:135], v[172:175], v[44:47]
	v_mfma_f32_16x16x32_bf16 v[40:43], v[140:143], v[172:175], v[40:43]
	v_mfma_f32_16x16x32_bf16 v[28:31], v[132:135], v[180:183], v[28:31]
	v_mfma_f32_16x16x32_bf16 v[24:27], v[140:143], v[180:183], v[24:27]
	v_mfma_f32_16x16x32_bf16 v[12:15], v[132:135], v[198:201], v[12:15]
	v_mfma_f32_16x16x32_bf16 v[8:11], v[140:143], v[198:201], v[8:11]
	s_setprio 0
	s_barrier
; #define PG8_STAGE(bufoff, gbase, voff) do { _Pragma("unroll") for (int _i = 0; _i < 2; ++_i) \
;         __builtin_amdgcn_global_load_lds((const unsigned*)((const char*)(gbase) + (voff)[_i]), (LAS unsigned*)(lds + (bufoff) + ldsw + _i * 8192), 16, 0, 0); } while (0)
; #define PG8_LDA(dst, b, h) do { _Pragma("unroll") for (int m = 0; m < 4; ++m) _Pragma("unroll") for (int k = 0; k < 2; ++k) dst[m][k] = *(const LAS bf16x8*)(lds + PG8_SA(b, h) + aoff + m * 2048 + k * 1024); } while (0)
; #define PG8_LDB(dst, b, h) do { _Pragma("unroll") for (int n = 0; n < 2; ++n) _Pragma("unroll") for (int k = 0; k < 2; ++k) dst[n][k] = *(const LAS bf16x8*)(lds + PG8_SB(b, h) + boff + n * 2048 + k * 1024); } while (0)
; #define PG8_MMA(ai, bj, At, Bt) do { __builtin_amdgcn_s_setprio(1); _Pragma("unroll") for (int m = 0; m < 4; ++m) _Pragma("unroll") for (int n = 0; n < 2; ++n) _Pragma("unroll") for (int k = 0; k < 2; ++k) \
;         acc[ai][bj][m][n] = __builtin_amdgcn_mfma_f32_16x16x32_bf16(Bt[n][k], At[m][k], acc[ai][bj][m][n], 0, 0, 0); __builtin_amdgcn_s_setprio(0); } while (0)
; #define PG8_WAIT_V(n) asm volatile("s_waitcnt vmcnt(" #n ")" ::: "memory")
; #define PG8_WAIT_L(n) asm volatile("s_waitcnt lgkmcnt(" #n ")" ::: "memory")
; #define PG8_BAR __builtin_amdgcn_s_barrier()
; #define PG8_SCHED __builtin_amdgcn_sched_barrier(0)
; template <class Epi>
; __device__ __forceinline__ void gemm_phase(LAS unsigned char* lds, const Gemm g, const Order& S, const Epi& E, const int tid) {
;     ...
;             PG8_STAGE(PG8_SB(0, 1), b2 + hstepB, voffB);
;             PG8_WAIT_V(6); PG8_BAR; PG8_MMA(1, 1, At, B1); PG8_BAR;
;             PG8_LDB(B0, 1, 0); PG8_SCHED; PG8_LDA(At, 1, 0); PG8_STAGE(PG8_SA(0, 1), a2 + hstepA, voffA);
;             PG8_WAIT_L(8); PG8_BAR; PG8_WAIT_L(0); PG8_MMA(0, 0, At, B0); PG8_BAR; PG8_SCHED;
;             PG8_LDB(B1, 1, 1); PG8_STAGE(PG8_SB(1, 0), b3, voffB);
;             PG8_BAR; PG8_WAIT_L(0); PG8_MMA(0, 1, At, B1); PG8_BAR;
;             PG8_LDA(At, 1, 1); PG8_STAGE(PG8_SA(1, 0), a3, voffA);
	s_add_u32 s52, s28, 0x80000
	s_addc_u32 s53, s29, 0
	s_add_i32 s51, s45, s33
	v_lshl_add_u64 v[128:129], s[52:53], 0, v[154:155]
	s_mov_b32 m0, s51
	s_nop 0
	global_load_lds_dwordx4 v[128:129], off
	v_lshl_add_u64 v[128:129], s[52:53], 0, v[158:159]
	s_add_i32 m0, s51, 0x2000
	s_nop 0
	global_load_lds_dwordx4 v[128:129], off
	s_waitcnt vmcnt(6)
	s_barrier
	s_setprio 1
	v_mfma_f32_16x16x32_bf16 v[52:55], v[202:205], v[144:147], v[52:55]
	v_mfma_f32_16x16x32_bf16 v[48:51], v[210:213], v[144:147], v[48:51]
	v_mfma_f32_16x16x32_bf16 v[36:39], v[202:205], v[168:171], v[36:39]
	v_mfma_f32_16x16x32_bf16 v[32:35], v[210:213], v[168:171], v[32:35]
	v_mfma_f32_16x16x32_bf16 v[20:23], v[202:205], v[176:179], v[20:23]
	v_mfma_f32_16x16x32_bf16 v[16:19], v[210:213], v[176:179], v[16:19]
	v_mfma_f32_16x16x32_bf16 v[4:7], v[202:205], v[194:197], v[4:7]
	v_mfma_f32_16x16x32_bf16 v[0:3], v[210:213], v[194:197], v[0:3]
	v_mfma_f32_16x16x32_bf16 v[52:55], v[206:209], v[148:151], v[52:55]
	v_mfma_f32_16x16x32_bf16 v[48:51], v[214:217], v[148:151], v[48:51]
	v_mfma_f32_16x16x32_bf16 v[36:39], v[206:209], v[172:175], v[36:39]
	v_mfma_f32_16x16x32_bf16 v[32:35], v[214:217], v[172:175], v[32:35]
	v_mfma_f32_16x16x32_bf16 v[20:23], v[206:209], v[180:183], v[20:23]
	v_mfma_f32_16x16x32_bf16 v[16:19], v[214:217], v[180:183], v[16:19]
	v_mfma_f32_16x16x32_bf16 v[4:7], v[206:209], v[198:201], v[4:7]
	v_mfma_f32_16x16x32_bf16 v[0:3], v[214:217], v[198:201], v[0:3]
	s_setprio 0
	s_add_i32 s51, 0, 0x18000
	v_add_u32_e32 v140, s51, v187
	s_barrier
	ds_read_b128 v[128:131], v140
	ds_read_b128 v[132:135], v140 offset:1024
	ds_read_b128 v[136:139], v140 offset:2048
	ds_read_b128 v[140:143], v140 offset:3072
	s_add_u32 s30, s30, 0x80000
	s_addc_u32 s31, s31, 0
	s_mov_b32 m0, s38
	v_lshl_add_u64 v[202:203], s[30:31], 0, v[152:153]
	ds_read_b128 v[144:147], v190 offset:32768
	ds_read_b128 v[148:151], v190 offset:33792
	ds_read_b128 v[168:171], v190 offset:34816
	ds_read_b128 v[172:175], v190 offset:35840
	ds_read_b128 v[176:179], v190 offset:36864
	ds_read_b128 v[180:183], v190 offset:37888
	ds_read_b128 v[194:197], v190 offset:38912
	ds_read_b128 v[198:201], v190 offset:39936
	global_load_lds_dwordx4 v[202:203], off
	v_lshl_add_u64 v[202:203], s[30:31], 0, v[156:157]
	s_mov_b32 m0, s39
	s_nop 0
	global_load_lds_dwordx4 v[202:203], off
	s_waitcnt lgkmcnt(8)
	s_barrier
	s_waitcnt lgkmcnt(0)
	s_setprio 1
	s_waitcnt lgkmcnt(0)
	v_mfma_f32_16x16x32_bf16 v[124:127], v[128:131], v[144:147], v[124:127]
	v_mfma_f32_16x16x32_bf16 v[120:123], v[136:139], v[144:147], v[120:123]
	v_mfma_f32_16x16x32_bf16 v[108:111], v[128:131], v[168:171], v[108:111]
	v_mfma_f32_16x16x32_bf16 v[104:107], v[136:139], v[168:171], v[104:107]
	v_mfma_f32_16x16x32_bf16 v[92:95], v[128:131], v[176:179], v[92:95]
	v_mfma_f32_16x16x32_bf16 v[88:91], v[136:139], v[176:179], v[88:91]
	v_mfma_f32_16x16x32_bf16 v[76:79], v[128:131], v[194:197], v[76:79]
	v_mfma_f32_16x16x32_bf16 v[72:75], v[136:139], v[194:197], v[72:75]
	v_mfma_f32_16x16x32_bf16 v[124:127], v[132:135], v[148:151], v[124:127]
	v_mfma_f32_16x16x32_bf16 v[120:123], v[140:143], v[148:151], v[120:123]
	v_mfma_f32_16x16x32_bf16 v[108:111], v[132:135], v[172:175], v[108:111]
	v_mfma_f32_16x16x32_bf16 v[104:107], v[140:143], v[172:175], v[104:107]
	v_mfma_f32_16x16x32_bf16 v[92:95], v[132:135], v[180:183], v[92:95]
	v_mfma_f32_16x16x32_bf16 v[88:91], v[140:143], v[180:183], v[88:91]
	v_mfma_f32_16x16x32_bf16 v[76:79], v[132:135], v[198:201], v[76:79]
	v_mfma_f32_16x16x32_bf16 v[72:75], v[140:143], v[198:201], v[72:75]
	s_setprio 0
	s_barrier
	s_add_i32 s30, 0, 0x1c000
	s_add_i32 s31, s51, s33
	v_add_u32_e32 v193, s30, v187
	v_lshl_add_u64 v[184:185], v[184:185], 0, s[12:13]
	s_mov_b32 m0, s31
	ds_read_b128 v[202:205], v193
	ds_read_b128 v[206:209], v193 offset:1024
	ds_read_b128 v[210:213], v193 offset:2048
	ds_read_b128 v[214:217], v193 offset:3072
	global_load_lds_dwordx4 v[184:185], off
	v_lshl_add_u64 v[184:185], v[218:219], 0, s[12:13]
	s_add_i32 m0, s31, 0x2000
	s_nop 0
	global_load_lds_dwordx4 v[184:185], off
	s_barrier
	s_waitcnt lgkmcnt(0)
	s_setprio 1
	s_waitcnt lgkmcnt(0)
	v_mfma_f32_16x16x32_bf16 v[116:119], v[202:205], v[144:147], v[116:119]
	v_mfma_f32_16x16x32_bf16 v[112:115], v[210:213], v[144:147], v[112:115]
	v_mfma_f32_16x16x32_bf16 v[100:103], v[202:205], v[168:171], v[100:103]
	v_mfma_f32_16x16x32_bf16 v[96:99], v[210:213], v[168:171], v[96:99]
	v_mfma_f32_16x16x32_bf16 v[84:87], v[202:205], v[176:179], v[84:87]
	v_mfma_f32_16x16x32_bf16 v[80:83], v[210:213], v[176:179], v[80:83]
	v_mfma_f32_16x16x32_bf16 v[68:71], v[202:205], v[194:197], v[68:71]
	v_mfma_f32_16x16x32_bf16 v[64:67], v[210:213], v[194:197], v[64:67]
	v_mfma_f32_16x16x32_bf16 v[116:119], v[206:209], v[148:151], v[116:119]
	v_mfma_f32_16x16x32_bf16 v[112:115], v[214:217], v[148:151], v[112:115]
	v_mfma_f32_16x16x32_bf16 v[100:103], v[206:209], v[172:175], v[100:103]
	v_mfma_f32_16x16x32_bf16 v[96:99], v[214:217], v[172:175], v[96:99]
	v_mfma_f32_16x16x32_bf16 v[84:87], v[206:209], v[180:183], v[84:87]
	v_mfma_f32_16x16x32_bf16 v[80:83], v[214:217], v[180:183], v[80:83]
	v_mfma_f32_16x16x32_bf16 v[68:71], v[206:209], v[198:201], v[68:71]
	v_mfma_f32_16x16x32_bf16 v[64:67], v[214:217], v[198:201], v[64:67]
	s_setprio 0
	s_mov_b32 m0, s42
	v_lshl_add_u64 v[184:185], v[220:221], 0, s[12:13]
	s_barrier
	ds_read_b128 v[144:147], v190 offset:49152
	ds_read_b128 v[148:151], v190 offset:50176
	ds_read_b128 v[168:171], v190 offset:51200
	ds_read_b128 v[172:175], v190 offset:52224
	ds_read_b128 v[176:179], v190 offset:53248
	ds_read_b128 v[180:183], v190 offset:54272
	ds_read_b128 v[194:197], v190 offset:55296
	ds_read_b128 v[198:201], v190 offset:56320
	global_load_lds_dwordx4 v[184:185], off
	v_lshl_add_u64 v[184:185], v[222:223], 0, s[12:13]
	s_mov_b32 m0, s43
	s_nop 0
	global_load_lds_dwordx4 v[184:185], off
	s_barrier
; #define PG8_STAGE(bufoff, gbase, voff) do { _Pragma("unroll") for (int _i = 0; _i < 2; ++_i) \
;         __builtin_amdgcn_global_load_lds((const unsigned*)((const char*)(gbase) + (voff)[_i]), (LAS unsigned*)(lds + (bufoff) + ldsw + _i * 8192), 16, 0, 0); } while (0)
; #define PG8_MMA(ai, bj, At, Bt) do { __builtin_amdgcn_s_setprio(1); _Pragma("unroll") for (int m = 0; m < 4; ++m) _Pragma("unroll") for (int n = 0; n < 2; ++n) _Pragma("unroll") for (int k = 0; k < 2; ++k) \
;         acc[ai][bj][m][n] = __builtin_amdgcn_mfma_f32_16x16x32_bf16(Bt[n][k], At[m][k], acc[ai][bj][m][n], 0, 0, 0); __builtin_amdgcn_s_setprio(0); } while (0)
; #define PG8_WAIT_V(n) asm volatile("s_waitcnt vmcnt(" #n ")" ::: "memory")
; #define PG8_WAIT_L(n) asm volatile("s_waitcnt lgkmcnt(" #n ")" ::: "memory")
; #define PG8_BAR __builtin_amdgcn_s_barrier()
; #define PG8_SCHED __builtin_amdgcn_sched_barrier(0)
; template <class Epi>
; __device__ __forceinline__ void gemm_phase(LAS unsigned char* lds, const Gemm g, const Order& S, const Epi& E, const int tid) {
;     ...
;             PG8_BAR; PG8_WAIT_L(0); PG8_MMA(1, 0, At, B0); PG8_BAR; PG8_SCHED;
;             PG8_STAGE(PG8_SB(1, 1), b3 + hstepB, voffB);
;             PG8_WAIT_V(6); PG8_BAR; PG8_MMA(1, 1, At, B1); PG8_BAR;
	s_waitcnt lgkmcnt(0)
	s_setprio 1
	s_waitcnt lgkmcnt(0)
	v_mfma_f32_16x16x32_bf16 v[60:63], v[128:131], v[144:147], v[60:63]
	v_mfma_f32_16x16x32_bf16 v[56:59], v[136:139], v[144:147], v[56:59]
	v_mfma_f32_16x16x32_bf16 v[44:47], v[128:131], v[168:171], v[44:47]
	v_mfma_f32_16x16x32_bf16 v[40:43], v[136:139], v[168:171], v[40:43]
	v_mfma_f32_16x16x32_bf16 v[28:31], v[128:131], v[176:179], v[28:31]
	v_mfma_f32_16x16x32_bf16 v[24:27], v[136:139], v[176:179], v[24:27]
	v_mfma_f32_16x16x32_bf16 v[12:15], v[128:131], v[194:197], v[12:15]
	v_mfma_f32_16x16x32_bf16 v[8:11], v[136:139], v[194:197], v[8:11]
	v_mfma_f32_16x16x32_bf16 v[60:63], v[132:135], v[148:151], v[60:63]
	v_mfma_f32_16x16x32_bf16 v[56:59], v[140:143], v[148:151], v[56:59]
	v_mfma_f32_16x16x32_bf16 v[44:47], v[132:135], v[172:175], v[44:47]
	v_mfma_f32_16x16x32_bf16 v[40:43], v[140:143], v[172:175], v[40:43]
	v_mfma_f32_16x16x32_bf16 v[28:31], v[132:135], v[180:183], v[28:31]
	v_mfma_f32_16x16x32_bf16 v[24:27], v[140:143], v[180:183], v[24:27]
	v_mfma_f32_16x16x32_bf16 v[12:15], v[132:135], v[198:201], v[12:15]
	v_mfma_f32_16x16x32_bf16 v[8:11], v[140:143], v[198:201], v[8:11]
	s_setprio 0
	s_barrier
	s_add_u32 s28, s28, 0x80080
	s_addc_u32 s29, s29, 0
	s_add_i32 s30, s30, s33
	v_lshl_add_u64 v[128:129], s[28:29], 0, v[154:155]
	s_mov_b32 m0, s30
	s_nop 0
	global_load_lds_dwordx4 v[128:129], off
	v_lshl_add_u64 v[128:129], s[28:29], 0, v[158:159]
	s_add_i32 m0, s30, 0x2000
	s_nop 0
	global_load_lds_dwordx4 v[128:129], off
	s_waitcnt vmcnt(6)
	s_barrier
	s_setprio 1
	v_mfma_f32_16x16x32_bf16 v[52:55], v[202:205], v[144:147], v[52:55]
	v_mfma_f32_16x16x32_bf16 v[48:51], v[210:213], v[144:147], v[48:51]
	v_mfma_f32_16x16x32_bf16 v[36:39], v[202:205], v[168:171], v[36:39]
	v_mfma_f32_16x16x32_bf16 v[32:35], v[210:213], v[168:171], v[32:35]
	v_mfma_f32_16x16x32_bf16 v[20:23], v[202:205], v[176:179], v[20:23]
	v_mfma_f32_16x16x32_bf16 v[16:19], v[210:213], v[176:179], v[16:19]
	v_mfma_f32_16x16x32_bf16 v[4:7], v[202:205], v[194:197], v[4:7]
	v_mfma_f32_16x16x32_bf16 v[0:3], v[210:213], v[194:197], v[0:3]
	v_mfma_f32_16x16x32_bf16 v[52:55], v[206:209], v[148:151], v[52:55]
	v_mfma_f32_16x16x32_bf16 v[48:51], v[214:217], v[148:151], v[48:51]
	v_mfma_f32_16x16x32_bf16 v[36:39], v[206:209], v[172:175], v[36:39]
	v_mfma_f32_16x16x32_bf16 v[32:35], v[214:217], v[172:175], v[32:35]
	v_mfma_f32_16x16x32_bf16 v[20:23], v[206:209], v[180:183], v[20:23]
	v_mfma_f32_16x16x32_bf16 v[16:19], v[214:217], v[180:183], v[16:19]
	v_mfma_f32_16x16x32_bf16 v[4:7], v[206:209], v[198:201], v[4:7]
	v_mfma_f32_16x16x32_bf16 v[0:3], v[214:217], v[198:201], v[0:3]
	s_setprio 0
	s_add_i32 s50, s50, 2
	s_add_u32 s26, s26, 0x100
	s_addc_u32 s27, s27, 0
	s_add_u32 s48, s48, 0x100
	s_addc_u32 s49, s49, 0
	s_cmp_gt_u32 s50, 29
	s_barrier
	s_cbranch_scc0 .LBB0_846
; __device__ __forceinline__ float bflo(unsigned w) { return __uint_as_float(w << 16); }
; __device__ __forceinline__ float bfhi(unsigned w) { return __uint_as_float(w & 0xffff0000u); }
;     __device__ __forceinline__ void operator()(const f32x4 (&acc)[2][2][4][2], const Unit& u, int wr, int wc, int fr, int fq) const {
;     ...
;                 u32x4 bs[4][2];
; #pragma unroll
;                 for (int m = 0; m < 4; ++m) { const size_t off = (size_t)(row0 + ai * HALF + m * 16) * DM + col0;
; #pragma unroll
;                     for (int bj = 0; bj < 2; ++bj) bs[m][bj] = *(const u32x4*)(baseb + off + bj * HALF); }
; #pragma unroll
;                 for (int m = 0; m < 4; ++m) { const size_t off = (size_t)(row0 + ai * HALF + m * 16) * DM + col0;
;                     float ss = 0.f;
; #pragma unroll
;                     for (int bj = 0; bj < 2; ++bj) { const u32x4 q = bs[m][bj]; const f32x4 a0 = acc[ai][bj][m][0], a1 = acc[ai][bj][m][1];
;                         const float h0 = bflo(q.x) + a0[0], h1 = bfhi(q.x) + a0[1], h2 = bflo(q.y) + a0[2], h3 = bfhi(q.y) + a0[3], h4 = bflo(q.z) + a1[0], h5 = bfhi(q.z) + a1[1], h6 = bflo(q.w) + a1[2], h7 = bfhi(q.w) + a1[3];
;                         ss += (h0 * h0 + h1 * h1) + (h2 * h2 + h3 * h3) + (h4 * h4 + h5 * h5) + (h6 * h6 + h7 * h7);
;                         u32x4 w; w.x = pk2(h0, h1); w.y = pk2(h2, h3); w.z = pk2(h4, h5); w.w = pk2(h6, h7);
;                         *(u32x4*)(out + off + bj * HALF) = w; }
;                     if (ssqp) { ss += __shfl_xor(ss, 16); ss += __shfl_xor(ss, 32); if (fq == 0) ssqp[(size_t)(row0 + ai * HALF + m * 16) * 32 + u.pn * 4 + wc] = ss; } }
	v_lshl_or_b32 v168, s6, 8, v188
	v_lshl_add_u32 v172, s8, 8, v186
	v_ashrrev_i32_e32 v169, 31, v168
	v_lshlrev_b64 v[202:203], 1, v[168:169]
	v_ashrrev_i32_e32 v173, 31, v172
	v_or_b32_e32 v182, 16, v172
	v_or_b32_e32 v178, 32, v172
	v_lshl_add_u64 v[170:171], s[22:23], 0, v[202:203]
	v_lshlrev_b64 v[204:205], 12, v[172:173]
	v_or_b32_e32 v174, 48, v172
	v_ashrrev_i32_e32 v183, 31, v182
	v_ashrrev_i32_e32 v179, 31, v178
	v_lshl_add_u64 v[128:129], v[170:171], 0, v[204:205]
	v_ashrrev_i32_e32 v175, 31, v174
	v_lshlrev_b64 v[184:185], 12, v[182:183]
	v_lshlrev_b64 v[180:181], 12, v[178:179]
	global_load_dwordx4 v[194:197], v[128:129], off nt
	global_load_dwordx4 v[198:201], v[128:129], off offset:256 nt
	v_lshlrev_b64 v[176:177], 12, v[174:175]
	v_lshl_add_u64 v[128:129], v[170:171], 0, v[184:185]
	v_lshl_add_u64 v[130:131], v[170:171], 0, v[180:181]
	v_lshl_add_u64 v[206:207], v[170:171], 0, v[176:177]
	global_load_dwordx4 v[148:151], v[128:129], off nt
	global_load_dwordx4 v[144:147], v[128:129], off offset:256 nt
	global_load_dwordx4 v[140:143], v[130:131], off nt
	global_load_dwordx4 v[136:139], v[130:131], off offset:256 nt
	global_load_dwordx4 v[132:135], v[206:207], off nt
	s_nop 0
	global_load_dwordx4 v[128:131], v[206:207], off offset:256 nt
	v_cndmask_b32_e64 v193, 0, 1, s[10:11]
	v_lshl_add_u64 v[204:205], s[22:23], 0, v[204:205]
	s_lshl_b32 s26, s6, 2
	v_cmp_ne_u32_e64 s[6:7], 1, v193
	v_lshl_add_u64 v[204:205], v[204:205], 0, v[202:203]
	s_ashr_i32 s27, s26, 31
	s_andn2_b64 vcc, exec, s[10:11]
	s_waitcnt vmcnt(0)
	v_lshlrev_b32_e32 v193, 16, v194
	v_and_b32_e32 v194, 0xffff0000, v194
	v_lshlrev_b32_e32 v202, 16, v195
	v_and_b32_e32 v195, 0xffff0000, v195
	v_lshlrev_b32_e32 v203, 16, v196
	v_and_b32_e32 v196, 0xffff0000, v196
	v_lshlrev_b32_e32 v206, 16, v197
	v_and_b32_e32 v197, 0xffff0000, v197
	v_lshlrev_b32_e32 v207, 16, v198
	v_and_b32_e32 v198, 0xffff0000, v198
	v_lshlrev_b32_e32 v208, 16, v199
	v_and_b32_e32 v199, 0xffff0000, v199
	v_lshlrev_b32_e32 v209, 16, v200
	v_and_b32_e32 v200, 0xffff0000, v200
	v_lshlrev_b32_e32 v210, 16, v201
	v_and_b32_e32 v201, 0xffff0000, v201
	v_add_f32_e32 v193, v124, v193
	v_add_f32_e32 v194, v125, v194
	v_add_f32_e32 v124, v126, v202
	v_add_f32_e32 v125, v127, v195
	v_add_f32_e32 v126, v120, v203
	v_add_f32_e32 v127, v121, v196
	v_add_f32_e32 v122, v122, v206
	v_add_f32_e32 v123, v123, v197
	v_add_f32_e32 v120, v116, v207
	v_add_f32_e32 v121, v117, v198
	v_add_f32_e32 v116, v118, v208
	v_add_f32_e32 v117, v119, v199
	v_add_f32_e32 v112, v112, v209
	v_add_f32_e32 v113, v113, v200
	v_add_f32_e32 v114, v114, v210
	v_add_f32_e32 v115, v115, v201
	v_cvt_pk_bf16_f32 v196, v193, v194
	v_cvt_pk_bf16_f32 v197, v124, v125
	v_cvt_pk_bf16_f32 v198, v126, v127
	v_cvt_pk_bf16_f32 v199, v122, v123
	v_cvt_pk_bf16_f32 v200, v120, v121
	v_cvt_pk_bf16_f32 v201, v116, v117
	v_cvt_pk_bf16_f32 v202, v112, v113
	v_cvt_pk_bf16_f32 v203, v114, v115
	global_store_dwordx4 v[204:205], v[196:199], off sc0 sc1
	global_store_dwordx4 v[204:205], v[200:203], off offset:256 sc0 sc1
	s_cbranch_vccnz .LBB0_851
	v_mul_f32_e32 v115, v115, v115
	v_mul_f32_e32 v113, v113, v113
	v_mul_f32_e32 v118, v123, v123
	v_fmac_f32_e32 v115, v114, v114
	v_fmac_f32_e32 v113, v112, v112
	v_mul_f32_e32 v112, v121, v121
	v_mul_f32_e32 v114, v117, v117
	v_fmac_f32_e32 v118, v122, v122
	v_mul_f32_e32 v122, v194, v194
	v_mul_f32_e32 v123, v125, v125
	v_fmac_f32_e32 v112, v120, v120
	v_fmac_f32_e32 v114, v116, v116
	v_mul_f32_e32 v119, v127, v127
	v_fmac_f32_e32 v122, v193, v193
	v_fmac_f32_e32 v123, v124, v124
	v_add_f32_e32 v112, v112, v114
	v_and_b32_e32 v114, 64, v192
	v_fmac_f32_e32 v119, v126, v126
	v_add_f32_e32 v122, v122, v123
	v_add_f32_e32 v112, v113, v112
	v_xor_b32_e32 v113, 16, v192
	v_add_u32_e32 v114, 64, v114
	v_add_f32_e32 v119, v119, v122
	v_cmp_lt_i32_e32 vcc, v113, v114
	v_add_f32_e32 v118, v118, v119
	v_add_f32_e32 v112, v115, v112
	v_cndmask_b32_e32 v113, v192, v113, vcc
	v_add_f32_e32 v112, v118, v112
	v_lshlrev_b32_e32 v113, 2, v113
	ds_bpermute_b32 v113, v113, v112
	s_waitcnt lgkmcnt(0)
	v_add_f32_e32 v112, v112, v113
	v_xor_b32_e32 v113, 32, v192
	v_cmp_lt_i32_e32 vcc, v113, v114
	s_nop 1
	v_cndmask_b32_e32 v113, v192, v113, vcc
	v_lshlrev_b32_e32 v113, 2, v113
	ds_bpermute_b32 v113, v113, v112
	s_and_saveexec_b64 s[28:29], s[0:1]
	s_cbranch_execz .LBB0_850
	v_lshlrev_b64 v[114:115], 7, v[172:173]
	v_lshl_add_u64 v[114:115], s[24:25], 0, v[114:115]
	v_lshl_add_u64 v[114:115], s[26:27], 2, v[114:115]
	s_lshl_b32 s8, s40, 2
	v_lshl_add_u64 v[114:115], v[114:115], 0, s[8:9]
	s_waitcnt lgkmcnt(0)
	v_add_f32_e32 v112, v112, v113
	global_store_dword v[114:115], v112, off

; __device__ __forceinline__ float bflo(unsigned w) { return __uint_as_float(w << 16); }
; __device__ __forceinline__ float bfhi(unsigned w) { return __uint_as_float(w & 0xffff0000u); }
;     __device__ __forceinline__ void operator()(const f32x4 (&acc)[2][2][4][2], const Unit& u, int wr, int wc, int fr, int fq) const {
;     ...
;                 u32x4 bs[4][2];
; #pragma unroll
;                 for (int m = 0; m < 4; ++m) { const size_t off = (size_t)(row0 + ai * HALF + m * 16) * DM + col0;
; #pragma unroll
;                     for (int bj = 0; bj < 2; ++bj) bs[m][bj] = *(const u32x4*)(baseb + off + bj * HALF); }
; #pragma unroll
;                 for (int m = 0; m < 4; ++m) { const size_t off = (size_t)(row0 + ai * HALF + m * 16) * DM + col0;
;                     float ss = 0.f;
; #pragma unroll
;                     for (int bj = 0; bj < 2; ++bj) { const u32x4 q = bs[m][bj]; const f32x4 a0 = acc[ai][bj][m][0], a1 = acc[ai][bj][m][1];
;                         const float h0 = bflo(q.x) + a0[0], h1 = bfhi(q.x) + a0[1], h2 = bflo(q.y) + a0[2], h3 = bfhi(q.y) + a0[3], h4 = bflo(q.z) + a1[0], h5 = bfhi(q.z) + a1[1], h6 = bflo(q.w) + a1[2], h7 = bfhi(q.w) + a1[3];
;                         ss += (h0 * h0 + h1 * h1) + (h2 * h2 + h3 * h3) + (h4 * h4 + h5 * h5) + (h6 * h6 + h7 * h7);
;                         u32x4 w; w.x = pk2(h0, h1); w.y = pk2(h2, h3); w.z = pk2(h4, h5); w.w = pk2(h6, h7);
;                         *(u32x4*)(out + off + bj * HALF) = w; }
;                     if (ssqp) { ss += __shfl_xor(ss, 16); ss += __shfl_xor(ss, 32); if (fq == 0) ssqp[(size_t)(row0 + ai * HALF + m * 16) * 32 + u.pn * 4 + wc] = ss; } }
.LBB0_863:
	v_add_u32_e32 v100, 0x80, v172
	v_ashrrev_i32_e32 v101, 31, v100
	v_add_u32_e32 v96, 0x90, v172
	v_add_u32_e32 v92, 0xa0, v172
	v_lshlrev_b64 v[110:111], 12, v[100:101]
	v_add_u32_e32 v88, 0xb0, v172
	s_waitcnt lgkmcnt(0)
	v_ashrrev_i32_e32 v97, 31, v96
	v_ashrrev_i32_e32 v93, 31, v92
	v_lshl_add_u64 v[64:65], v[170:171], 0, v[110:111]
	v_ashrrev_i32_e32 v89, 31, v88
	v_lshlrev_b64 v[98:99], 12, v[96:97]
	v_lshlrev_b64 v[94:95], 12, v[92:93]
	global_load_dwordx4 v[102:105], v[64:65], off nt
	global_load_dwordx4 v[106:109], v[64:65], off offset:256 nt
	v_lshlrev_b64 v[90:91], 12, v[88:89]
	v_lshl_add_u64 v[64:65], v[170:171], 0, v[98:99]
	v_lshl_add_u64 v[66:67], v[170:171], 0, v[94:95]
	v_lshl_add_u64 v[112:113], v[170:171], 0, v[90:91]
	global_load_dwordx4 v[84:87], v[64:65], off nt
	global_load_dwordx4 v[80:83], v[64:65], off offset:256 nt
	global_load_dwordx4 v[76:79], v[66:67], off nt
	global_load_dwordx4 v[72:75], v[66:67], off offset:256 nt
	global_load_dwordx4 v[68:71], v[112:113], off nt
	s_nop 0
	global_load_dwordx4 v[64:67], v[112:113], off offset:256 nt
	v_lshl_add_u64 v[110:111], s[22:23], 0, v[110:111]
	v_lshl_add_u64 v[112:113], v[168:169], 1, v[110:111]
	s_and_b64 vcc, exec, s[6:7]
	s_waitcnt vmcnt(7)
	v_lshlrev_b32_e32 v110, 16, v102
	v_and_b32_e32 v111, 0xffff0000, v102
	v_lshlrev_b32_e32 v114, 16, v103
	v_and_b32_e32 v115, 0xffff0000, v103
	v_lshlrev_b32_e32 v116, 16, v104
	v_and_b32_e32 v104, 0xffff0000, v104
	v_lshlrev_b32_e32 v117, 16, v105
	v_and_b32_e32 v105, 0xffff0000, v105
	s_waitcnt vmcnt(6)
	v_lshlrev_b32_e32 v118, 16, v106
	v_and_b32_e32 v106, 0xffff0000, v106
	v_lshlrev_b32_e32 v119, 16, v107
	v_and_b32_e32 v107, 0xffff0000, v107
	v_lshlrev_b32_e32 v120, 16, v108
	v_and_b32_e32 v108, 0xffff0000, v108
	v_lshlrev_b32_e32 v121, 16, v109
	v_and_b32_e32 v109, 0xffff0000, v109
	v_add_f32_e32 v102, v60, v110
	v_add_f32_e32 v103, v61, v111
	v_add_f32_e32 v60, v62, v114
	v_add_f32_e32 v61, v63, v115
	v_add_f32_e32 v62, v56, v116
	v_add_f32_e32 v63, v57, v104
	v_add_f32_e32 v58, v58, v117
	v_add_f32_e32 v59, v59, v105
	v_add_f32_e32 v56, v52, v118
	v_add_f32_e32 v57, v53, v106
	v_add_f32_e32 v52, v54, v119
	v_add_f32_e32 v53, v55, v107
	v_add_f32_e32 v48, v48, v120
	v_add_f32_e32 v49, v49, v108
	v_add_f32_e32 v50, v50, v121
	v_add_f32_e32 v51, v51, v109
	v_cvt_pk_bf16_f32 v104, v102, v103
	v_cvt_pk_bf16_f32 v105, v60, v61
	v_cvt_pk_bf16_f32 v106, v62, v63
	v_cvt_pk_bf16_f32 v107, v58, v59
	v_cvt_pk_bf16_f32 v108, v56, v57
	v_cvt_pk_bf16_f32 v109, v52, v53
	v_cvt_pk_bf16_f32 v110, v48, v49
	v_cvt_pk_bf16_f32 v111, v50, v51
	global_store_dwordx4 v[112:113], v[104:107], off sc0 sc1
	global_store_dwordx4 v[112:113], v[108:111], off offset:256 sc0 sc1
	s_cbranch_vccnz .LBB0_867
	v_mul_f32_e32 v51, v51, v51
	v_mul_f32_e32 v49, v49, v49
	v_mul_f32_e32 v54, v59, v59
	v_fmac_f32_e32 v51, v50, v50
	v_fmac_f32_e32 v49, v48, v48
	v_mul_f32_e32 v48, v57, v57
	v_mul_f32_e32 v50, v53, v53
	v_fmac_f32_e32 v54, v58, v58
	v_mul_f32_e32 v58, v103, v103
	v_mul_f32_e32 v59, v61, v61
	v_fmac_f32_e32 v48, v56, v56
	v_fmac_f32_e32 v50, v52, v52
	v_mul_f32_e32 v55, v63, v63
	v_fmac_f32_e32 v58, v102, v102
	v_fmac_f32_e32 v59, v60, v60
	v_add_f32_e32 v48, v48, v50
	v_and_b32_e32 v50, 64, v192
	v_fmac_f32_e32 v55, v62, v62
	v_add_f32_e32 v58, v58, v59
	v_add_f32_e32 v48, v49, v48
	v_xor_b32_e32 v49, 16, v192
	v_add_u32_e32 v50, 64, v50
	v_add_f32_e32 v55, v55, v58
	v_cmp_lt_i32_e32 vcc, v49, v50
	v_add_f32_e32 v54, v54, v55
	v_add_f32_e32 v48, v51, v48
	v_cndmask_b32_e32 v49, v192, v49, vcc
	v_add_f32_e32 v48, v54, v48
	v_lshlrev_b32_e32 v49, 2, v49
	ds_bpermute_b32 v49, v49, v48
	s_waitcnt lgkmcnt(0)
	v_add_f32_e32 v48, v48, v49
	v_xor_b32_e32 v49, 32, v192
	v_cmp_lt_i32_e32 vcc, v49, v50
	s_nop 1
	v_cndmask_b32_e32 v49, v192, v49, vcc
	v_lshlrev_b32_e32 v49, 2, v49
	ds_bpermute_b32 v49, v49, v48
	s_and_saveexec_b64 s[28:29], s[0:1]
	s_cbranch_execz .LBB0_866
	v_lshlrev_b64 v[50:51], 7, v[100:101]
	v_lshl_add_u64 v[50:51], s[24:25], 0, v[50:51]
	v_lshl_add_u64 v[50:51], s[26:27], 2, v[50:51]
	s_lshl_b32 s8, s40, 2
	v_lshl_add_u64 v[50:51], v[50:51], 0, s[8:9]
	s_waitcnt lgkmcnt(0)
	v_add_f32_e32 v48, v48, v49
	global_store_dword v[50:51], v48, off

; #define PG8_STAGE(bufoff, gbase, voff) do { _Pragma("unroll") for (int _i = 0; _i < 2; ++_i) \
;         __builtin_amdgcn_global_load_lds((const unsigned*)((const char*)(gbase) + (voff)[_i]), (LAS unsigned*)(lds + (bufoff) + ldsw + _i * 8192), 16, 0, 0); } while (0)
; #define PG8_LDA(dst, b, h) do { _Pragma("unroll") for (int m = 0; m < 4; ++m) _Pragma("unroll") for (int k = 0; k < 2; ++k) dst[m][k] = *(const LAS bf16x8*)(lds + PG8_SA(b, h) + aoff + m * 2048 + k * 1024); } while (0)
; #define PG8_LDB(dst, b, h) do { _Pragma("unroll") for (int n = 0; n < 2; ++n) _Pragma("unroll") for (int k = 0; k < 2; ++k) dst[n][k] = *(const LAS bf16x8*)(lds + PG8_SB(b, h) + boff + n * 2048 + k * 1024); } while (0)
; #define PG8_MMA(ai, bj, At, Bt) do { __builtin_amdgcn_s_setprio(1); _Pragma("unroll") for (int m = 0; m < 4; ++m) _Pragma("unroll") for (int n = 0; n < 2; ++n) _Pragma("unroll") for (int k = 0; k < 2; ++k) \
;         acc[ai][bj][m][n] = __builtin_amdgcn_mfma_f32_16x16x32_bf16(Bt[n][k], At[m][k], acc[ai][bj][m][n], 0, 0, 0); __builtin_amdgcn_s_setprio(0); } while (0)
; #define PG8_WAIT_L(n) asm volatile("s_waitcnt lgkmcnt(" #n ")" ::: "memory")
; #define PG8_BAR __builtin_amdgcn_s_barrier()
; #define PG8_SCHED __builtin_amdgcn_sched_barrier(0)
; template <class Epi>
; __device__ __forceinline__ void gemm_phase(LAS unsigned char* lds, const Gemm g, const Order& S, const Epi& E, const int tid) {
;     ...
;         for (int t = 0; t < nt; t += 2) {
;             const bool last = (t == nt - 2);
;             const char* a1 = cA + (size_t)(t + 1) * kstep;
;             const char* a2 = last ? nA : cA + (size_t)(t + 2) * kstep; const char* b2 = last ? nB : cB + (size_t)(t + 2) * kstep;
;             const char* a3 = a2 + kstep; const char* b3 = b2 + kstep;
;             PG8_LDB(B0, 0, 0); PG8_SCHED; PG8_LDA(At, 0, 0); PG8_STAGE(PG8_SA(1, 1), a1 + hstepA, voffA);
;             PG8_WAIT_L(8); PG8_BAR; PG8_WAIT_L(0); PG8_MMA(0, 0, At, B0); PG8_BAR; PG8_SCHED;
;             PG8_LDB(B1, 0, 1); PG8_STAGE(PG8_SB(0, 0), b2, voffB);
;             PG8_BAR; PG8_WAIT_L(0); PG8_MMA(0, 1, At, B1); PG8_BAR;
;             PG8_LDA(At, 0, 1); PG8_STAGE(PG8_SA(0, 0), a2, voffA);
;             PG8_BAR; PG8_WAIT_L(0); PG8_MMA(1, 0, At, B0); PG8_BAR; PG8_SCHED;
.LBB0_938:
	ds_read_b128 v[144:147], v153
	ds_read_b128 v[156:159], v153 offset:1024
	ds_read_b128 v[160:163], v153 offset:2048
	ds_read_b128 v[164:167], v153 offset:3072
	s_add_u32 s28, s26, 0xffe00080
	s_addc_u32 s29, s27, -1
	s_cmpk_eq_i32 s48, 0x7c
	s_cselect_b32 s31, s15, s29
	s_cselect_b32 s30, s44, s28
	s_cselect_b32 s29, s17, s47
	s_cselect_b32 s28, s45, s46
	v_lshl_add_u64 v[148:149], s[26:27], 0, v[136:137]
	s_add_i32 m0, s25, 0xc000
	ds_read_b128 v[168:171], v154
	ds_read_b128 v[172:175], v154 offset:1024
	ds_read_b128 v[176:179], v154 offset:2048
	ds_read_b128 v[180:183], v154 offset:3072
	ds_read_b128 v[184:187], v154 offset:4096
	ds_read_b128 v[188:191], v154 offset:5120
	ds_read_b128 v[192:195], v154 offset:6144
	ds_read_b128 v[196:199], v154 offset:7168
	global_load_lds_dwordx4 v[148:149], off
	v_lshl_add_u64 v[148:149], s[26:27], 0, v[138:139]
	s_add_i32 m0, s25, 0xe000
	s_nop 0
	global_load_lds_dwordx4 v[148:149], off
	s_waitcnt lgkmcnt(8)
	s_barrier
	s_waitcnt lgkmcnt(0)
	s_setprio 1
	s_waitcnt lgkmcnt(0)
	v_mfma_f32_16x16x32_bf16 v[124:127], v[144:147], v[168:171], v[124:127]
	v_mfma_f32_16x16x32_bf16 v[120:123], v[160:163], v[168:171], v[120:123]
	v_mfma_f32_16x16x32_bf16 v[116:119], v[144:147], v[176:179], v[116:119]
	v_mfma_f32_16x16x32_bf16 v[112:115], v[160:163], v[176:179], v[112:115]
	v_mfma_f32_16x16x32_bf16 v[96:99], v[144:147], v[184:187], v[96:99]
	v_mfma_f32_16x16x32_bf16 v[88:91], v[160:163], v[184:187], v[88:91]
	v_mfma_f32_16x16x32_bf16 v[80:83], v[144:147], v[192:195], v[80:83]
	v_mfma_f32_16x16x32_bf16 v[72:75], v[160:163], v[192:195], v[72:75]
	v_mfma_f32_16x16x32_bf16 v[124:127], v[156:159], v[172:175], v[124:127]
	v_mfma_f32_16x16x32_bf16 v[120:123], v[164:167], v[172:175], v[120:123]
	v_mfma_f32_16x16x32_bf16 v[116:119], v[156:159], v[180:183], v[116:119]
	v_mfma_f32_16x16x32_bf16 v[112:115], v[164:167], v[180:183], v[112:115]
	v_mfma_f32_16x16x32_bf16 v[96:99], v[156:159], v[188:191], v[96:99]
	v_mfma_f32_16x16x32_bf16 v[88:91], v[164:167], v[188:191], v[88:91]
	v_mfma_f32_16x16x32_bf16 v[80:83], v[156:159], v[196:199], v[80:83]
	v_mfma_f32_16x16x32_bf16 v[72:75], v[164:167], v[196:199], v[72:75]
	s_setprio 0
	s_barrier
	s_add_i32 s49, s41, s33
	v_lshl_add_u64 v[148:149], s[28:29], 0, v[132:133]
	s_mov_b32 m0, s49
	ds_read_b128 v[200:203], v155
	ds_read_b128 v[204:207], v155 offset:1024
	ds_read_b128 v[208:211], v155 offset:2048
	ds_read_b128 v[212:215], v155 offset:3072
	global_load_lds_dwordx4 v[148:149], off
	v_lshl_add_u64 v[216:217], s[28:29], 0, v[128:129]
	s_add_i32 m0, s49, 0x2000
	s_nop 0
	global_load_lds_dwordx4 v[216:217], off
	s_barrier
	s_waitcnt lgkmcnt(0)
	s_setprio 1
	s_waitcnt lgkmcnt(0)
	v_mfma_f32_16x16x32_bf16 v[108:111], v[200:203], v[168:171], v[108:111]
	v_mfma_f32_16x16x32_bf16 v[104:107], v[208:211], v[168:171], v[104:107]
	v_mfma_f32_16x16x32_bf16 v[100:103], v[200:203], v[176:179], v[100:103]
	v_mfma_f32_16x16x32_bf16 v[92:95], v[208:211], v[176:179], v[92:95]
	v_mfma_f32_16x16x32_bf16 v[84:87], v[200:203], v[184:187], v[84:87]
	v_mfma_f32_16x16x32_bf16 v[76:79], v[208:211], v[184:187], v[76:79]
	v_mfma_f32_16x16x32_bf16 v[68:71], v[200:203], v[192:195], v[68:71]
	v_mfma_f32_16x16x32_bf16 v[64:67], v[208:211], v[192:195], v[64:67]
	v_mfma_f32_16x16x32_bf16 v[108:111], v[204:207], v[172:175], v[108:111]
	v_mfma_f32_16x16x32_bf16 v[104:107], v[212:215], v[172:175], v[104:107]
	v_mfma_f32_16x16x32_bf16 v[100:103], v[204:207], v[180:183], v[100:103]
	v_mfma_f32_16x16x32_bf16 v[92:95], v[212:215], v[180:183], v[92:95]
	v_mfma_f32_16x16x32_bf16 v[84:87], v[204:207], v[188:191], v[84:87]
	v_mfma_f32_16x16x32_bf16 v[76:79], v[212:215], v[188:191], v[76:79]
	v_mfma_f32_16x16x32_bf16 v[68:71], v[204:207], v[196:199], v[68:71]
	v_mfma_f32_16x16x32_bf16 v[64:67], v[212:215], v[196:199], v[64:67]
	s_setprio 0
	s_mov_b32 m0, s25
	v_lshl_add_u64 v[218:219], s[30:31], 0, v[134:135]
	s_barrier
	ds_read_b128 v[168:171], v154 offset:16384
	ds_read_b128 v[172:175], v154 offset:17408
	ds_read_b128 v[176:179], v154 offset:18432
	ds_read_b128 v[180:183], v154 offset:19456
	ds_read_b128 v[184:187], v154 offset:20480
	ds_read_b128 v[188:191], v154 offset:21504
	ds_read_b128 v[192:195], v154 offset:22528
	ds_read_b128 v[196:199], v154 offset:23552
	global_load_lds_dwordx4 v[218:219], off
	v_lshl_add_u64 v[220:221], s[30:31], 0, v[130:131]
	s_mov_b32 m0, s35
	s_nop 0
	global_load_lds_dwordx4 v[220:221], off
	s_barrier
	s_waitcnt lgkmcnt(0)
	s_setprio 1
	s_waitcnt lgkmcnt(0)
	v_mfma_f32_16x16x32_bf16 v[60:63], v[144:147], v[168:171], v[60:63]
	v_mfma_f32_16x16x32_bf16 v[56:59], v[160:163], v[168:171], v[56:59]
	v_mfma_f32_16x16x32_bf16 v[48:51], v[144:147], v[176:179], v[48:51]
	v_mfma_f32_16x16x32_bf16 v[40:43], v[160:163], v[176:179], v[40:43]
	v_mfma_f32_16x16x32_bf16 v[32:35], v[144:147], v[184:187], v[32:35]
	v_mfma_f32_16x16x32_bf16 v[24:27], v[160:163], v[184:187], v[24:27]
	v_mfma_f32_16x16x32_bf16 v[16:19], v[144:147], v[192:195], v[16:19]
	v_mfma_f32_16x16x32_bf16 v[8:11], v[160:163], v[192:195], v[8:11]
	v_mfma_f32_16x16x32_bf16 v[60:63], v[156:159], v[172:175], v[60:63]
	v_mfma_f32_16x16x32_bf16 v[56:59], v[164:167], v[172:175], v[56:59]
	v_mfma_f32_16x16x32_bf16 v[48:51], v[156:159], v[180:183], v[48:51]
	v_mfma_f32_16x16x32_bf16 v[40:43], v[164:167], v[180:183], v[40:43]
	v_mfma_f32_16x16x32_bf16 v[32:35], v[156:159], v[188:191], v[32:35]
	v_mfma_f32_16x16x32_bf16 v[24:27], v[164:167], v[188:191], v[24:27]
	v_mfma_f32_16x16x32_bf16 v[16:19], v[156:159], v[196:199], v[16:19]
	v_mfma_f32_16x16x32_bf16 v[8:11], v[164:167], v[196:199], v[8:11]
	s_setprio 0
	s_barrier
; #define PG8_STAGE(bufoff, gbase, voff) do { _Pragma("unroll") for (int _i = 0; _i < 2; ++_i) \
;         __builtin_amdgcn_global_load_lds((const unsigned*)((const char*)(gbase) + (voff)[_i]), (LAS unsigned*)(lds + (bufoff) + ldsw + _i * 8192), 16, 0, 0); } while (0)
; #define PG8_LDA(dst, b, h) do { _Pragma("unroll") for (int m = 0; m < 4; ++m) _Pragma("unroll") for (int k = 0; k < 2; ++k) dst[m][k] = *(const LAS bf16x8*)(lds + PG8_SA(b, h) + aoff + m * 2048 + k * 1024); } while (0)
; #define PG8_LDB(dst, b, h) do { _Pragma("unroll") for (int n = 0; n < 2; ++n) _Pragma("unroll") for (int k = 0; k < 2; ++k) dst[n][k] = *(const LAS bf16x8*)(lds + PG8_SB(b, h) + boff + n * 2048 + k * 1024); } while (0)
; #define PG8_MMA(ai, bj, At, Bt) do { __builtin_amdgcn_s_setprio(1); _Pragma("unroll") for (int m = 0; m < 4; ++m) _Pragma("unroll") for (int n = 0; n < 2; ++n) _Pragma("unroll") for (int k = 0; k < 2; ++k) \
;         acc[ai][bj][m][n] = __builtin_amdgcn_mfma_f32_16x16x32_bf16(Bt[n][k], At[m][k], acc[ai][bj][m][n], 0, 0, 0); __builtin_amdgcn_s_setprio(0); } while (0)
; #define PG8_WAIT_V(n) asm volatile("s_waitcnt vmcnt(" #n ")" ::: "memory")
; #define PG8_WAIT_L(n) asm volatile("s_waitcnt lgkmcnt(" #n ")" ::: "memory")
; #define PG8_BAR __builtin_amdgcn_s_barrier()
; #define PG8_SCHED __builtin_amdgcn_sched_barrier(0)
; template <class Epi>
; __device__ __forceinline__ void gemm_phase(LAS unsigned char* lds, const Gemm g, const Order& S, const Epi& E, const int tid) {
;     ...
;             PG8_STAGE(PG8_SB(0, 1), b2 + hstepB, voffB);
;             PG8_WAIT_V(6); PG8_BAR; PG8_MMA(1, 1, At, B1); PG8_BAR;
;             PG8_LDB(B0, 1, 0); PG8_SCHED; PG8_LDA(At, 1, 0); PG8_STAGE(PG8_SA(0, 1), a2 + hstepA, voffA);
;             PG8_WAIT_L(8); PG8_BAR; PG8_WAIT_L(0); PG8_MMA(0, 0, At, B0); PG8_BAR; PG8_SCHED;
;             PG8_LDB(B1, 1, 1); PG8_STAGE(PG8_SB(1, 0), b3, voffB);
;             PG8_BAR; PG8_WAIT_L(0); PG8_MMA(0, 1, At, B1); PG8_BAR;
;             PG8_LDA(At, 1, 1); PG8_STAGE(PG8_SA(1, 0), a3, voffA);
;             PG8_BAR; PG8_WAIT_L(0); PG8_MMA(1, 0, At, B0); PG8_BAR; PG8_SCHED;
;             PG8_STAGE(PG8_SB(1, 1), b3 + hstepB, voffB);
;             PG8_WAIT_V(6); PG8_BAR; PG8_MMA(1, 1, At, B1); PG8_BAR;
	s_add_u32 s50, s28, 0x200000
	s_addc_u32 s51, s29, 0
	s_add_i32 s49, s42, s33
	v_lshl_add_u64 v[144:145], s[50:51], 0, v[132:133]
	s_mov_b32 m0, s49
	s_nop 0
	global_load_lds_dwordx4 v[144:145], off
	v_lshl_add_u64 v[144:145], s[50:51], 0, v[128:129]
	s_add_i32 m0, s49, 0x2000
	s_nop 0
	global_load_lds_dwordx4 v[144:145], off
	s_waitcnt vmcnt(6)
	s_barrier
	s_setprio 1
	v_mfma_f32_16x16x32_bf16 v[52:55], v[200:203], v[168:171], v[52:55]
	v_mfma_f32_16x16x32_bf16 v[44:47], v[208:211], v[168:171], v[44:47]
	v_mfma_f32_16x16x32_bf16 v[36:39], v[200:203], v[176:179], v[36:39]
	v_mfma_f32_16x16x32_bf16 v[28:31], v[208:211], v[176:179], v[28:31]
	v_mfma_f32_16x16x32_bf16 v[20:23], v[200:203], v[184:187], v[20:23]
	v_mfma_f32_16x16x32_bf16 v[12:15], v[208:211], v[184:187], v[12:15]
	v_mfma_f32_16x16x32_bf16 v[4:7], v[200:203], v[192:195], v[4:7]
	v_mfma_f32_16x16x32_bf16 v[0:3], v[208:211], v[192:195], v[0:3]
	v_mfma_f32_16x16x32_bf16 v[52:55], v[204:207], v[172:175], v[52:55]
	v_mfma_f32_16x16x32_bf16 v[44:47], v[212:215], v[172:175], v[44:47]
	v_mfma_f32_16x16x32_bf16 v[36:39], v[204:207], v[180:183], v[36:39]
	v_mfma_f32_16x16x32_bf16 v[28:31], v[212:215], v[180:183], v[28:31]
	v_mfma_f32_16x16x32_bf16 v[20:23], v[204:207], v[188:191], v[20:23]
	v_mfma_f32_16x16x32_bf16 v[12:15], v[212:215], v[188:191], v[12:15]
	v_mfma_f32_16x16x32_bf16 v[4:7], v[204:207], v[196:199], v[4:7]
	v_mfma_f32_16x16x32_bf16 v[0:3], v[212:215], v[196:199], v[0:3]
	s_setprio 0
	s_add_i32 s49, 0, 0x18000
	v_add_u32_e32 v164, s49, v151
	s_barrier
	ds_read_b128 v[144:147], v164
	ds_read_b128 v[156:159], v164 offset:1024
	ds_read_b128 v[160:163], v164 offset:2048
	ds_read_b128 v[164:167], v164 offset:3072
	s_add_u32 s30, s30, 0x200000
	s_addc_u32 s31, s31, 0
	s_mov_b32 m0, s36
	v_lshl_add_u64 v[200:201], s[30:31], 0, v[134:135]
	ds_read_b128 v[168:171], v154 offset:32768
	ds_read_b128 v[172:175], v154 offset:33792
	ds_read_b128 v[176:179], v154 offset:34816
	ds_read_b128 v[180:183], v154 offset:35840
	ds_read_b128 v[184:187], v154 offset:36864
	ds_read_b128 v[188:191], v154 offset:37888
	ds_read_b128 v[192:195], v154 offset:38912
	ds_read_b128 v[196:199], v154 offset:39936
	global_load_lds_dwordx4 v[200:201], off
	v_lshl_add_u64 v[200:201], s[30:31], 0, v[130:131]
	s_mov_b32 m0, s37
	s_nop 0
	global_load_lds_dwordx4 v[200:201], off
	s_waitcnt lgkmcnt(8)
	s_barrier
	s_waitcnt lgkmcnt(0)
	s_setprio 1
	s_waitcnt lgkmcnt(0)
	v_mfma_f32_16x16x32_bf16 v[124:127], v[144:147], v[168:171], v[124:127]
	v_mfma_f32_16x16x32_bf16 v[120:123], v[160:163], v[168:171], v[120:123]
	v_mfma_f32_16x16x32_bf16 v[116:119], v[144:147], v[176:179], v[116:119]
	v_mfma_f32_16x16x32_bf16 v[112:115], v[160:163], v[176:179], v[112:115]
	v_mfma_f32_16x16x32_bf16 v[96:99], v[144:147], v[184:187], v[96:99]
	v_mfma_f32_16x16x32_bf16 v[88:91], v[160:163], v[184:187], v[88:91]
	v_mfma_f32_16x16x32_bf16 v[80:83], v[144:147], v[192:195], v[80:83]
	v_mfma_f32_16x16x32_bf16 v[72:75], v[160:163], v[192:195], v[72:75]
	v_mfma_f32_16x16x32_bf16 v[124:127], v[156:159], v[172:175], v[124:127]
	v_mfma_f32_16x16x32_bf16 v[120:123], v[164:167], v[172:175], v[120:123]
	v_mfma_f32_16x16x32_bf16 v[116:119], v[156:159], v[180:183], v[116:119]
	v_mfma_f32_16x16x32_bf16 v[112:115], v[164:167], v[180:183], v[112:115]
	v_mfma_f32_16x16x32_bf16 v[96:99], v[156:159], v[188:191], v[96:99]
	v_mfma_f32_16x16x32_bf16 v[88:91], v[164:167], v[188:191], v[88:91]
	v_mfma_f32_16x16x32_bf16 v[80:83], v[156:159], v[196:199], v[80:83]
	v_mfma_f32_16x16x32_bf16 v[72:75], v[164:167], v[196:199], v[72:75]
	s_setprio 0
	s_barrier
	s_add_i32 s30, 0, 0x1c000
	s_add_i32 s31, s49, s33
	v_add_u32_e32 v212, s30, v151
	v_lshl_add_u64 v[148:149], v[148:149], 0, s[4:5]
	s_mov_b32 m0, s31
	ds_read_b128 v[200:203], v212
	ds_read_b128 v[204:207], v212 offset:1024
	ds_read_b128 v[208:211], v212 offset:2048
	ds_read_b128 v[212:215], v212 offset:3072
	global_load_lds_dwordx4 v[148:149], off
	v_lshl_add_u64 v[148:149], v[216:217], 0, s[4:5]
	s_add_i32 m0, s31, 0x2000
	s_nop 0
	global_load_lds_dwordx4 v[148:149], off
	s_barrier
	s_waitcnt lgkmcnt(0)
	s_setprio 1
	s_waitcnt lgkmcnt(0)
	v_mfma_f32_16x16x32_bf16 v[108:111], v[200:203], v[168:171], v[108:111]
	v_mfma_f32_16x16x32_bf16 v[104:107], v[208:211], v[168:171], v[104:107]
	v_mfma_f32_16x16x32_bf16 v[100:103], v[200:203], v[176:179], v[100:103]
	v_mfma_f32_16x16x32_bf16 v[92:95], v[208:211], v[176:179], v[92:95]
	v_mfma_f32_16x16x32_bf16 v[84:87], v[200:203], v[184:187], v[84:87]
	v_mfma_f32_16x16x32_bf16 v[76:79], v[208:211], v[184:187], v[76:79]
	v_mfma_f32_16x16x32_bf16 v[68:71], v[200:203], v[192:195], v[68:71]
	v_mfma_f32_16x16x32_bf16 v[64:67], v[208:211], v[192:195], v[64:67]
	v_mfma_f32_16x16x32_bf16 v[108:111], v[204:207], v[172:175], v[108:111]
	v_mfma_f32_16x16x32_bf16 v[104:107], v[212:215], v[172:175], v[104:107]
	v_mfma_f32_16x16x32_bf16 v[100:103], v[204:207], v[180:183], v[100:103]
	v_mfma_f32_16x16x32_bf16 v[92:95], v[212:215], v[180:183], v[92:95]
	v_mfma_f32_16x16x32_bf16 v[84:87], v[204:207], v[188:191], v[84:87]
	v_mfma_f32_16x16x32_bf16 v[76:79], v[212:215], v[188:191], v[76:79]
	v_mfma_f32_16x16x32_bf16 v[68:71], v[204:207], v[196:199], v[68:71]
	v_mfma_f32_16x16x32_bf16 v[64:67], v[212:215], v[196:199], v[64:67]
	s_setprio 0
	s_mov_b32 m0, s39
	v_lshl_add_u64 v[148:149], v[218:219], 0, s[4:5]
	s_barrier
	ds_read_b128 v[168:171], v154 offset:49152
	ds_read_b128 v[172:175], v154 offset:50176
	ds_read_b128 v[176:179], v154 offset:51200
	ds_read_b128 v[180:183], v154 offset:52224
	ds_read_b128 v[184:187], v154 offset:53248
	ds_read_b128 v[188:191], v154 offset:54272
	ds_read_b128 v[192:195], v154 offset:55296
	ds_read_b128 v[196:199], v154 offset:56320
	global_load_lds_dwordx4 v[148:149], off
	v_lshl_add_u64 v[148:149], v[220:221], 0, s[4:5]
	s_mov_b32 m0, s40
	s_nop 0
	global_load_lds_dwordx4 v[148:149], off
	s_barrier
; #define PG8_STAGE(bufoff, gbase, voff) do { _Pragma("unroll") for (int _i = 0; _i < 2; ++_i) \
;         __builtin_amdgcn_global_load_lds((const unsigned*)((const char*)(gbase) + (voff)[_i]), (LAS unsigned*)(lds + (bufoff) + ldsw + _i * 8192), 16, 0, 0); } while (0)
; #define PG8_MMA(ai, bj, At, Bt) do { __builtin_amdgcn_s_setprio(1); _Pragma("unroll") for (int m = 0; m < 4; ++m) _Pragma("unroll") for (int n = 0; n < 2; ++n) _Pragma("unroll") for (int k = 0; k < 2; ++k) \
;         acc[ai][bj][m][n] = __builtin_amdgcn_mfma_f32_16x16x32_bf16(Bt[n][k], At[m][k], acc[ai][bj][m][n], 0, 0, 0); __builtin_amdgcn_s_setprio(0); } while (0)
; #define PG8_WAIT_V(n) asm volatile("s_waitcnt vmcnt(" #n ")" ::: "memory")
; #define PG8_WAIT_L(n) asm volatile("s_waitcnt lgkmcnt(" #n ")" ::: "memory")
; #define PG8_BAR __builtin_amdgcn_s_barrier()
; #define PG8_SCHED __builtin_amdgcn_sched_barrier(0)
; template <class Epi>
; __device__ __forceinline__ void gemm_phase(LAS unsigned char* lds, const Gemm g, const Order& S, const Epi& E, const int tid) {
;     ...
;             PG8_BAR; PG8_WAIT_L(0); PG8_MMA(1, 0, At, B0); PG8_BAR; PG8_SCHED;
;             PG8_STAGE(PG8_SB(1, 1), b3 + hstepB, voffB);
;             PG8_WAIT_V(6); PG8_BAR; PG8_MMA(1, 1, At, B1); PG8_BAR;
;     __device__ __forceinline__ void operator()(const f32x4 (&acc)[2][2][4][2], const Unit& u, int wr, int wc, int fr, int fq) const {
;     ...
;                 u32x4 bs[4][2];
; #pragma unroll
;                 for (int m = 0; m < 4; ++m) { const size_t off = (size_t)(row0 + ai * HALF + m * 16) * DM + col0;
; #pragma unroll
;                     for (int bj = 0; bj < 2; ++bj) bs[m][bj] = *(const u32x4*)(baseb + off + bj * HALF); }
	s_waitcnt lgkmcnt(0)
	s_setprio 1
	s_waitcnt lgkmcnt(0)
	v_mfma_f32_16x16x32_bf16 v[60:63], v[144:147], v[168:171], v[60:63]
	v_mfma_f32_16x16x32_bf16 v[56:59], v[160:163], v[168:171], v[56:59]
	v_mfma_f32_16x16x32_bf16 v[48:51], v[144:147], v[176:179], v[48:51]
	v_mfma_f32_16x16x32_bf16 v[40:43], v[160:163], v[176:179], v[40:43]
	v_mfma_f32_16x16x32_bf16 v[32:35], v[144:147], v[184:187], v[32:35]
	v_mfma_f32_16x16x32_bf16 v[24:27], v[160:163], v[184:187], v[24:27]
	v_mfma_f32_16x16x32_bf16 v[16:19], v[144:147], v[192:195], v[16:19]
	v_mfma_f32_16x16x32_bf16 v[8:11], v[160:163], v[192:195], v[8:11]
	v_mfma_f32_16x16x32_bf16 v[60:63], v[156:159], v[172:175], v[60:63]
	v_mfma_f32_16x16x32_bf16 v[56:59], v[164:167], v[172:175], v[56:59]
	v_mfma_f32_16x16x32_bf16 v[48:51], v[156:159], v[180:183], v[48:51]
	v_mfma_f32_16x16x32_bf16 v[40:43], v[164:167], v[180:183], v[40:43]
	v_mfma_f32_16x16x32_bf16 v[32:35], v[156:159], v[188:191], v[32:35]
	v_mfma_f32_16x16x32_bf16 v[24:27], v[164:167], v[188:191], v[24:27]
	v_mfma_f32_16x16x32_bf16 v[16:19], v[156:159], v[196:199], v[16:19]
	v_mfma_f32_16x16x32_bf16 v[8:11], v[164:167], v[196:199], v[8:11]
	s_setprio 0
	s_barrier
	s_add_u32 s28, s28, 0x200080
	s_addc_u32 s29, s29, 0
	s_add_i32 s30, s30, s33
	v_lshl_add_u64 v[144:145], s[28:29], 0, v[132:133]
	s_mov_b32 m0, s30
	s_nop 0
	global_load_lds_dwordx4 v[144:145], off
	v_lshl_add_u64 v[144:145], s[28:29], 0, v[128:129]
	s_add_i32 m0, s30, 0x2000
	s_nop 0
	global_load_lds_dwordx4 v[144:145], off
	s_waitcnt vmcnt(6)
	s_barrier
	s_setprio 1
	v_mfma_f32_16x16x32_bf16 v[52:55], v[200:203], v[168:171], v[52:55]
	v_mfma_f32_16x16x32_bf16 v[44:47], v[208:211], v[168:171], v[44:47]
	v_mfma_f32_16x16x32_bf16 v[36:39], v[200:203], v[176:179], v[36:39]
	v_mfma_f32_16x16x32_bf16 v[28:31], v[208:211], v[176:179], v[28:31]
	v_mfma_f32_16x16x32_bf16 v[20:23], v[200:203], v[184:187], v[20:23]
	v_mfma_f32_16x16x32_bf16 v[12:15], v[208:211], v[184:187], v[12:15]
	v_mfma_f32_16x16x32_bf16 v[4:7], v[200:203], v[192:195], v[4:7]
	v_mfma_f32_16x16x32_bf16 v[0:3], v[208:211], v[192:195], v[0:3]
	v_mfma_f32_16x16x32_bf16 v[52:55], v[204:207], v[172:175], v[52:55]
	v_mfma_f32_16x16x32_bf16 v[44:47], v[212:215], v[172:175], v[44:47]
	v_mfma_f32_16x16x32_bf16 v[36:39], v[204:207], v[180:183], v[36:39]
	v_mfma_f32_16x16x32_bf16 v[28:31], v[212:215], v[180:183], v[28:31]
	v_mfma_f32_16x16x32_bf16 v[20:23], v[204:207], v[188:191], v[20:23]
	v_mfma_f32_16x16x32_bf16 v[12:15], v[212:215], v[188:191], v[12:15]
	v_mfma_f32_16x16x32_bf16 v[4:7], v[204:207], v[196:199], v[4:7]
	v_mfma_f32_16x16x32_bf16 v[0:3], v[212:215], v[196:199], v[0:3]
	s_setprio 0
	s_add_i32 s48, s48, 2
	s_add_u32 s26, s26, 0x100
	s_addc_u32 s27, s27, 0
	s_add_u32 s46, s46, 0x100
	s_addc_u32 s47, s47, 0
	s_cmpk_gt_u32 s48, 0x7d
	s_barrier
	s_cbranch_scc0 .LBB0_938
	v_lshl_or_b32 v144, s43, 8, v152
	v_lshl_add_u32 v172, s24, 8, v150
	v_ashrrev_i32_e32 v145, 31, v144
	v_lshlrev_b64 v[144:145], 1, v[144:145]
	v_ashrrev_i32_e32 v173, 31, v172
	v_lshl_add_u64 v[146:147], s[22:23], 0, v[144:145]
	v_lshlrev_b64 v[148:149], 12, v[172:173]
	v_or_b32_e32 v164, 16, v172
	v_lshl_add_u64 v[160:161], v[146:147], 0, v[148:149]
	v_ashrrev_i32_e32 v165, 31, v164
	global_load_dwordx4 v[156:159], v[160:161], off nt
	s_nop 0
	global_load_dwordx4 v[160:163], v[160:161], off offset:256 nt
	v_lshlrev_b64 v[188:189], 12, v[164:165]
	v_lshl_add_u64 v[168:169], v[146:147], 0, v[188:189]
	global_load_dwordx4 v[164:167], v[168:169], off nt
	s_nop 0
	global_load_dwordx4 v[168:171], v[168:169], off offset:256 nt
	v_or_b32_e32 v174, 32, v172
	v_or_b32_e32 v172, 48, v172
	v_ashrrev_i32_e32 v175, 31, v174
	v_ashrrev_i32_e32 v173, 31, v172
	v_lshlrev_b64 v[190:191], 12, v[174:175]
	v_lshlrev_b64 v[192:193], 12, v[172:173]
	v_lshl_add_u64 v[172:173], s[22:23], 0, v[148:149]
	v_lshl_add_u64 v[176:177], v[146:147], 0, v[190:191]
	v_lshl_add_u64 v[184:185], v[146:147], 0, v[192:193]
	v_lshl_add_u64 v[194:195], v[172:173], 0, v[144:145]
	global_load_dwordx4 v[172:175], v[176:177], off nt
	s_nop 0
	global_load_dwordx4 v[176:179], v[176:177], off offset:256 nt
	s_nop 0
	global_load_dwordx4 v[180:183], v[184:185], off nt
	s_nop 0
	global_load_dwordx4 v[184:187], v[184:185], off offset:256 nt
	s_and_b64 vcc, exec, s[0:1]
	s_mov_b32 s43, s16
	s_mov_b32 s24, s14
	s_mov_b64 s[28:29], s[20:21]
	s_mov_b64 s[26:27], s[18:19]
	s_waitcnt vmcnt(0)
; __device__ __forceinline__ float bflo(unsigned w) { return __uint_as_float(w << 16); }
; __device__ __forceinline__ float bfhi(unsigned w) { return __uint_as_float(w & 0xffff0000u); }
;     __device__ __forceinline__ void operator()(const f32x4 (&acc)[2][2][4][2], const Unit& u, int wr, int wc, int fr, int fq) const {
;     ...
;                 u32x4 bs[4][2];
; #pragma unroll
;                 for (int m = 0; m < 4; ++m) { const size_t off = (size_t)(row0 + ai * HALF + m * 16) * DM + col0;
; #pragma unroll
;                     for (int bj = 0; bj < 2; ++bj) bs[m][bj] = *(const u32x4*)(baseb + off + bj * HALF); }
; #pragma unroll
;                 for (int m = 0; m < 4; ++m) { const size_t off = (size_t)(row0 + ai * HALF + m * 16) * DM + col0;
;                     float ss = 0.f;
; #pragma unroll
;                     for (int bj = 0; bj < 2; ++bj) { const u32x4 q = bs[m][bj]; const f32x4 a0 = acc[ai][bj][m][0], a1 = acc[ai][bj][m][1];
;                         const float h0 = bflo(q.x) + a0[0], h1 = bfhi(q.x) + a0[1], h2 = bflo(q.y) + a0[2], h3 = bfhi(q.y) + a0[3], h4 = bflo(q.z) + a1[0], h5 = bfhi(q.z) + a1[1], h6 = bflo(q.w) + a1[2], h7 = bfhi(q.w) + a1[3];
;                         ss += (h0 * h0 + h1 * h1) + (h2 * h2 + h3 * h3) + (h4 * h4 + h5 * h5) + (h6 * h6 + h7 * h7);
;                         u32x4 w; w.x = pk2(h0, h1); w.y = pk2(h2, h3); w.z = pk2(h4, h5); w.w = pk2(h6, h7);
;                         *(u32x4*)(out + off + bj * HALF) = w; }
;                     if (ssqp) { ss += __shfl_xor(ss, 16); ss += __shfl_xor(ss, 32); if (fq == 0) ssqp[(size_t)(row0 + ai * HALF + m * 16) * 32 + u.pn * 4 + wc] = ss; } }
;                 asm volatile("" ::: "memory");
	v_lshlrev_b32_e32 v196, 16, v156
	v_and_b32_e32 v156, 0xffff0000, v156
	v_lshlrev_b32_e32 v197, 16, v157
	v_and_b32_e32 v157, 0xffff0000, v157
	v_lshlrev_b32_e32 v198, 16, v158
	v_and_b32_e32 v158, 0xffff0000, v158
	v_lshlrev_b32_e32 v199, 16, v159
	v_and_b32_e32 v159, 0xffff0000, v159
	v_lshlrev_b32_e32 v200, 16, v160
	v_and_b32_e32 v160, 0xffff0000, v160
	v_lshlrev_b32_e32 v201, 16, v161
	v_and_b32_e32 v161, 0xffff0000, v161
	v_lshlrev_b32_e32 v202, 16, v162
	v_and_b32_e32 v162, 0xffff0000, v162
	v_lshlrev_b32_e32 v203, 16, v163
	v_and_b32_e32 v163, 0xffff0000, v163
	v_add_f32_e32 v124, v124, v196
	v_add_f32_e32 v125, v125, v156
	v_add_f32_e32 v126, v126, v197
	v_add_f32_e32 v127, v127, v157
	v_add_f32_e32 v120, v120, v198
	v_add_f32_e32 v121, v121, v158
	v_add_f32_e32 v122, v122, v199
	v_add_f32_e32 v123, v123, v159
	v_add_f32_e32 v108, v108, v200
	v_add_f32_e32 v109, v109, v160
	v_add_f32_e32 v110, v110, v201
	v_add_f32_e32 v111, v111, v161
	v_add_f32_e32 v156, v104, v202
	v_add_f32_e32 v157, v105, v162
	v_add_f32_e32 v158, v106, v203
	v_add_f32_e32 v159, v107, v163
	v_cvt_pk_bf16_f32 v104, v124, v125
	v_cvt_pk_bf16_f32 v105, v126, v127
	v_cvt_pk_bf16_f32 v106, v120, v121
	v_cvt_pk_bf16_f32 v107, v122, v123
	v_cvt_pk_bf16_f32 v108, v108, v109
	v_cvt_pk_bf16_f32 v109, v110, v111
	v_cvt_pk_bf16_f32 v110, v156, v157
	v_cvt_pk_bf16_f32 v111, v158, v159
	global_store_dwordx4 v[194:195], v[104:107], off sc0 sc1
	global_store_dwordx4 v[194:195], v[108:111], off offset:256 sc0 sc1
	v_lshlrev_b32_e32 v204, 16, v164
	v_lshlrev_b32_e32 v106, 16, v168
	v_add_f32_e32 v100, v100, v106
	v_and_b32_e32 v106, 0xffff0000, v168
	v_add_f32_e32 v101, v101, v106
	v_lshlrev_b32_e32 v106, 16, v169
	v_add_f32_e32 v102, v102, v106
	v_and_b32_e32 v106, 0xffff0000, v169
	v_add_f32_e32 v103, v103, v106
	v_lshlrev_b32_e32 v106, 16, v170
	v_add_f32_e32 v106, v92, v106
	v_and_b32_e32 v92, 0xffff0000, v170
	v_add_f32_e32 v107, v93, v92
	v_lshlrev_b32_e32 v92, 16, v171
	v_add_f32_e32 v108, v94, v92
	v_and_b32_e32 v92, 0xffff0000, v171
	v_lshl_add_u64 v[104:105], s[22:23], 0, v[188:189]
	v_add_f32_e32 v95, v95, v92
	v_lshl_add_u64 v[104:105], v[104:105], 0, v[144:145]
	v_cvt_pk_bf16_f32 v92, v100, v101
	v_cvt_pk_bf16_f32 v93, v102, v103
	v_cvt_pk_bf16_f32 v94, v106, v107
	v_cvt_pk_bf16_f32 v95, v108, v95
	global_store_dwordx4 v[104:105], v[92:95], off offset:256 sc0 sc1
	v_and_b32_e32 v164, 0xffff0000, v164
	v_lshlrev_b32_e32 v205, 16, v165
	v_lshlrev_b32_e32 v92, 16, v172
	v_add_f32_e32 v92, v96, v92
	v_lshlrev_b32_e32 v96, 16, v174
	v_and_b32_e32 v93, 0xffff0000, v172
	v_add_f32_e32 v96, v88, v96
	v_and_b32_e32 v88, 0xffff0000, v174
	v_add_f32_e32 v93, v97, v93
	v_lshlrev_b32_e32 v94, 16, v173
	v_add_f32_e32 v97, v89, v88
	v_lshlrev_b32_e32 v88, 16, v175
	v_add_f32_e32 v94, v98, v94
	v_and_b32_e32 v95, 0xffff0000, v173
	v_add_f32_e32 v98, v90, v88
	v_and_b32_e32 v88, 0xffff0000, v175
	v_add_f32_e32 v95, v99, v95
	v_add_f32_e32 v91, v91, v88
	v_cvt_pk_bf16_f32 v88, v92, v93
	v_lshl_add_u64 v[92:93], s[22:23], 0, v[190:191]
	v_cvt_pk_bf16_f32 v89, v94, v95
	v_cvt_pk_bf16_f32 v90, v96, v97
	v_cvt_pk_bf16_f32 v91, v98, v91
	v_lshl_add_u64 v[92:93], v[92:93], 0, v[144:145]
	global_store_dwordx4 v[92:93], v[88:91], off sc0 sc1
	v_and_b32_e32 v165, 0xffff0000, v165
	v_lshlrev_b32_e32 v206, 16, v166
	v_lshlrev_b32_e32 v88, 16, v176
	v_add_f32_e32 v84, v84, v88
	v_and_b32_e32 v88, 0xffff0000, v176
	v_add_f32_e32 v85, v85, v88
	v_lshlrev_b32_e32 v88, 16, v177
	v_add_f32_e32 v86, v86, v88
	v_and_b32_e32 v88, 0xffff0000, v177
	v_add_f32_e32 v87, v87, v88
	v_lshlrev_b32_e32 v88, 16, v178
	v_add_f32_e32 v88, v76, v88
	v_and_b32_e32 v76, 0xffff0000, v178
	v_add_f32_e32 v89, v77, v76
	v_lshlrev_b32_e32 v76, 16, v179
	v_add_f32_e32 v90, v78, v76
	v_and_b32_e32 v76, 0xffff0000, v179
	v_add_f32_e32 v79, v79, v76
	v_cvt_pk_bf16_f32 v76, v84, v85
	v_cvt_pk_bf16_f32 v77, v86, v87
	v_cvt_pk_bf16_f32 v78, v88, v89
	v_cvt_pk_bf16_f32 v79, v90, v79
	global_store_dwordx4 v[92:93], v[76:79], off offset:256 sc0 sc1
	v_and_b32_e32 v166, 0xffff0000, v166
	v_lshlrev_b32_e32 v207, 16, v167
	v_lshlrev_b32_e32 v76, 16, v180
	v_add_f32_e32 v76, v80, v76
	v_lshlrev_b32_e32 v80, 16, v182
	v_and_b32_e32 v77, 0xffff0000, v180
	v_add_f32_e32 v80, v72, v80
	v_and_b32_e32 v72, 0xffff0000, v182
	v_add_f32_e32 v77, v81, v77
	v_lshlrev_b32_e32 v78, 16, v181
	v_add_f32_e32 v81, v73, v72
	v_lshlrev_b32_e32 v72, 16, v183
	v_add_f32_e32 v78, v82, v78
	v_and_b32_e32 v79, 0xffff0000, v181
	v_add_f32_e32 v82, v74, v72
	v_and_b32_e32 v72, 0xffff0000, v183
	v_add_f32_e32 v79, v83, v79
	v_add_f32_e32 v75, v75, v72
	v_cvt_pk_bf16_f32 v72, v76, v77
	v_lshl_add_u64 v[76:77], s[22:23], 0, v[192:193]
	v_cvt_pk_bf16_f32 v73, v78, v79
	v_cvt_pk_bf16_f32 v74, v80, v81
	v_cvt_pk_bf16_f32 v75, v82, v75
	v_lshl_add_u64 v[76:77], v[76:77], 0, v[144:145]
	global_store_dwordx4 v[76:77], v[72:75], off sc0 sc1
	v_and_b32_e32 v167, 0xffff0000, v167
	v_add_f32_e32 v116, v116, v204
	v_lshlrev_b32_e32 v72, 16, v184
	v_add_f32_e32 v68, v68, v72
	v_and_b32_e32 v72, 0xffff0000, v184
	v_add_f32_e32 v69, v69, v72
	v_lshlrev_b32_e32 v72, 16, v185
	v_add_f32_e32 v70, v70, v72
	v_and_b32_e32 v72, 0xffff0000, v185
	v_add_f32_e32 v71, v71, v72
	v_lshlrev_b32_e32 v72, 16, v186
	v_add_f32_e32 v72, v64, v72
	v_and_b32_e32 v64, 0xffff0000, v186
	v_add_f32_e32 v73, v65, v64
	v_lshlrev_b32_e32 v64, 16, v187
	v_add_f32_e32 v74, v66, v64
	v_and_b32_e32 v64, 0xffff0000, v187
	v_add_f32_e32 v117, v117, v164
	v_add_f32_e32 v118, v118, v205
	v_add_f32_e32 v119, v119, v165
	v_add_f32_e32 v160, v112, v206
	v_add_f32_e32 v161, v113, v166
	v_add_f32_e32 v162, v114, v207
	v_add_f32_e32 v115, v115, v167
	v_add_f32_e32 v67, v67, v64
	v_cvt_pk_bf16_f32 v112, v116, v117
	v_cvt_pk_bf16_f32 v113, v118, v119
	v_cvt_pk_bf16_f32 v114, v160, v161
	v_cvt_pk_bf16_f32 v115, v162, v115
	v_cvt_pk_bf16_f32 v64, v68, v69
	v_cvt_pk_bf16_f32 v65, v70, v71
	v_cvt_pk_bf16_f32 v66, v72, v73
	v_cvt_pk_bf16_f32 v67, v74, v67
	global_store_dwordx4 v[104:105], v[112:115], off sc0 sc1
	global_store_dwordx4 v[76:77], v[64:67], off offset:256 sc0 sc1
	v_lshl_add_u64 v[96:97], v[148:149], 0, s[6:7]
	v_lshl_add_u64 v[68:69], v[146:147], 0, v[96:97]
	global_load_dwordx4 v[64:67], v[68:69], off nt
	s_nop 0
	global_load_dwordx4 v[68:71], v[68:69], off offset:256 nt
	v_lshl_add_u64 v[98:99], v[148:149], 0, s[8:9]
	v_lshl_add_u64 v[76:77], v[146:147], 0, v[98:99]
	global_load_dwordx4 v[72:75], v[76:77], off nt
	s_nop 0
	global_load_dwordx4 v[76:79], v[76:77], off offset:256 nt
	v_lshl_add_u64 v[100:101], v[148:149], 0, s[10:11]
	v_lshl_add_u64 v[84:85], v[146:147], 0, v[100:101]
	global_load_dwordx4 v[80:83], v[84:85], off nt
	s_nop 0
	global_load_dwordx4 v[84:87], v[84:85], off offset:256 nt
	v_lshl_add_u64 v[102:103], v[148:149], 0, s[12:13]
	v_lshl_add_u64 v[92:93], v[146:147], 0, v[102:103]
	global_load_dwordx4 v[88:91], v[92:93], off nt
	s_nop 0
	global_load_dwordx4 v[92:95], v[92:93], off offset:256 nt
	s_waitcnt vmcnt(0)
; __device__ __forceinline__ float bflo(unsigned w) { return __uint_as_float(w << 16); }
; __device__ __forceinline__ float bfhi(unsigned w) { return __uint_as_float(w & 0xffff0000u); }
;     __device__ __forceinline__ void operator()(const f32x4 (&acc)[2][2][4][2], const Unit& u, int wr, int wc, int fr, int fq) const {
;     ...
;                 for (int m = 0; m < 4; ++m) { const size_t off = (size_t)(row0 + ai * HALF + m * 16) * DM + col0;
;                     float ss = 0.f;
; #pragma unroll
;                     for (int bj = 0; bj < 2; ++bj) { const u32x4 q = bs[m][bj]; const f32x4 a0 = acc[ai][bj][m][0], a1 = acc[ai][bj][m][1];
;                         const float h0 = bflo(q.x) + a0[0], h1 = bfhi(q.x) + a0[1], h2 = bflo(q.y) + a0[2], h3 = bfhi(q.y) + a0[3], h4 = bflo(q.z) + a1[0], h5 = bfhi(q.z) + a1[1], h6 = bflo(q.w) + a1[2], h7 = bfhi(q.w) + a1[3];
;                         ss += (h0 * h0 + h1 * h1) + (h2 * h2 + h3 * h3) + (h4 * h4 + h5 * h5) + (h6 * h6 + h7 * h7);
;                         u32x4 w; w.x = pk2(h0, h1); w.y = pk2(h2, h3); w.z = pk2(h4, h5); w.w = pk2(h6, h7);
;                         *(u32x4*)(out + off + bj * HALF) = w; }
	v_lshlrev_b32_e32 v104, 16, v64
	v_and_b32_e32 v64, 0xffff0000, v64
	v_add_f32_e32 v61, v61, v64
	v_lshlrev_b32_e32 v64, 16, v65
	v_add_f32_e32 v62, v62, v64
	v_and_b32_e32 v64, 0xffff0000, v65
	v_add_f32_e32 v63, v63, v64
	v_lshlrev_b32_e32 v64, 16, v66
	v_add_f32_e32 v64, v56, v64
	v_and_b32_e32 v56, 0xffff0000, v66
	v_add_f32_e32 v65, v57, v56
	v_lshlrev_b32_e32 v56, 16, v67
	v_add_f32_e32 v60, v60, v104
	v_add_f32_e32 v66, v58, v56
	v_and_b32_e32 v56, 0xffff0000, v67
	v_add_f32_e32 v59, v59, v56
	v_cvt_pk_bf16_f32 v56, v60, v61
	v_lshl_add_u64 v[60:61], s[22:23], 0, v[96:97]
	v_cvt_pk_bf16_f32 v57, v62, v63
	v_cvt_pk_bf16_f32 v58, v64, v65
	v_cvt_pk_bf16_f32 v59, v66, v59
	v_lshl_add_u64 v[60:61], v[60:61], 0, v[144:145]
	global_store_dwordx4 v[60:61], v[56:59], off sc0 sc1
	s_nop 1
	v_lshlrev_b32_e32 v56, 16, v68
	v_add_f32_e32 v52, v52, v56
	v_and_b32_e32 v56, 0xffff0000, v68
	v_add_f32_e32 v53, v53, v56
	v_lshlrev_b32_e32 v56, 16, v69
	v_add_f32_e32 v54, v54, v56
	v_and_b32_e32 v56, 0xffff0000, v69
	v_add_f32_e32 v55, v55, v56
	v_lshlrev_b32_e32 v56, 16, v70
	v_add_f32_e32 v56, v44, v56
	v_and_b32_e32 v44, 0xffff0000, v70
	v_add_f32_e32 v57, v45, v44
	v_lshlrev_b32_e32 v44, 16, v71
	v_add_f32_e32 v58, v46, v44
	v_and_b32_e32 v44, 0xffff0000, v71
	v_add_f32_e32 v47, v47, v44
	v_cvt_pk_bf16_f32 v44, v52, v53
	v_cvt_pk_bf16_f32 v45, v54, v55
	v_cvt_pk_bf16_f32 v46, v56, v57
	v_cvt_pk_bf16_f32 v47, v58, v47
	global_store_dwordx4 v[60:61], v[44:47], off offset:256 sc0 sc1
	s_nop 1
	v_lshlrev_b32_e32 v44, 16, v72
	v_add_f32_e32 v44, v48, v44
	v_lshlrev_b32_e32 v48, 16, v74
	v_and_b32_e32 v45, 0xffff0000, v72
	v_add_f32_e32 v48, v40, v48
	v_and_b32_e32 v40, 0xffff0000, v74
	v_add_f32_e32 v45, v49, v45
	v_lshlrev_b32_e32 v46, 16, v73
	v_add_f32_e32 v49, v41, v40
	v_lshlrev_b32_e32 v40, 16, v75
	v_add_f32_e32 v46, v50, v46
	v_and_b32_e32 v47, 0xffff0000, v73
	v_add_f32_e32 v50, v42, v40
	v_and_b32_e32 v40, 0xffff0000, v75
	v_add_f32_e32 v47, v51, v47
	v_add_f32_e32 v43, v43, v40
	v_cvt_pk_bf16_f32 v40, v44, v45
	v_lshl_add_u64 v[44:45], s[22:23], 0, v[98:99]
	v_cvt_pk_bf16_f32 v41, v46, v47
	v_cvt_pk_bf16_f32 v42, v48, v49
	v_cvt_pk_bf16_f32 v43, v50, v43
	v_lshl_add_u64 v[44:45], v[44:45], 0, v[144:145]
	global_store_dwordx4 v[44:45], v[40:43], off sc0 sc1
	s_nop 1
	v_lshlrev_b32_e32 v40, 16, v76
	v_add_f32_e32 v36, v36, v40
	v_and_b32_e32 v40, 0xffff0000, v76
	v_add_f32_e32 v37, v37, v40
	v_lshlrev_b32_e32 v40, 16, v77
	v_add_f32_e32 v38, v38, v40
	v_and_b32_e32 v40, 0xffff0000, v77
	v_add_f32_e32 v39, v39, v40
	v_lshlrev_b32_e32 v40, 16, v78
	v_add_f32_e32 v40, v28, v40
	v_and_b32_e32 v28, 0xffff0000, v78
	v_add_f32_e32 v41, v29, v28
	v_lshlrev_b32_e32 v28, 16, v79
	v_add_f32_e32 v42, v30, v28
	v_and_b32_e32 v28, 0xffff0000, v79
	v_add_f32_e32 v31, v31, v28
	v_cvt_pk_bf16_f32 v28, v36, v37
	v_cvt_pk_bf16_f32 v29, v38, v39
	v_cvt_pk_bf16_f32 v30, v40, v41
	v_cvt_pk_bf16_f32 v31, v42, v31
	global_store_dwordx4 v[44:45], v[28:31], off offset:256 sc0 sc1
	s_nop 1
	v_lshlrev_b32_e32 v28, 16, v80
	v_add_f32_e32 v28, v32, v28
	v_lshlrev_b32_e32 v32, 16, v82
	v_and_b32_e32 v29, 0xffff0000, v80
	v_add_f32_e32 v32, v24, v32
	v_and_b32_e32 v24, 0xffff0000, v82
	v_add_f32_e32 v29, v33, v29
	v_lshlrev_b32_e32 v30, 16, v81
	v_add_f32_e32 v33, v25, v24
	v_lshlrev_b32_e32 v24, 16, v83
	v_add_f32_e32 v30, v34, v30
	v_and_b32_e32 v31, 0xffff0000, v81
	v_add_f32_e32 v34, v26, v24
	v_and_b32_e32 v24, 0xffff0000, v83
	v_add_f32_e32 v31, v35, v31
	v_add_f32_e32 v27, v27, v24
	v_cvt_pk_bf16_f32 v24, v28, v29
	v_lshl_add_u64 v[28:29], s[22:23], 0, v[100:101]
	v_cvt_pk_bf16_f32 v25, v30, v31
	v_cvt_pk_bf16_f32 v26, v32, v33
	v_cvt_pk_bf16_f32 v27, v34, v27
	v_lshl_add_u64 v[28:29], v[28:29], 0, v[144:145]
	global_store_dwordx4 v[28:29], v[24:27], off sc0 sc1
	s_nop 1
	v_lshlrev_b32_e32 v24, 16, v84
	v_add_f32_e32 v20, v20, v24
	v_and_b32_e32 v24, 0xffff0000, v84
	v_add_f32_e32 v21, v21, v24
	v_lshlrev_b32_e32 v24, 16, v85
	v_add_f32_e32 v22, v22, v24
	v_and_b32_e32 v24, 0xffff0000, v85
	v_add_f32_e32 v23, v23, v24
	v_lshlrev_b32_e32 v24, 16, v86
	v_add_f32_e32 v24, v12, v24
	v_and_b32_e32 v12, 0xffff0000, v86
	v_add_f32_e32 v25, v13, v12
	v_lshlrev_b32_e32 v12, 16, v87
	v_add_f32_e32 v26, v14, v12
	v_and_b32_e32 v12, 0xffff0000, v87
	v_add_f32_e32 v15, v15, v12
	v_cvt_pk_bf16_f32 v12, v20, v21
	v_cvt_pk_bf16_f32 v13, v22, v23
	v_cvt_pk_bf16_f32 v14, v24, v25
	v_cvt_pk_bf16_f32 v15, v26, v15
	global_store_dwordx4 v[28:29], v[12:15], off offset:256 sc0 sc1
	s_nop 1
	v_lshlrev_b32_e32 v12, 16, v88
	v_add_f32_e32 v12, v16, v12
	v_lshlrev_b32_e32 v16, 16, v90
	v_and_b32_e32 v13, 0xffff0000, v88
	v_add_f32_e32 v16, v8, v16
	v_and_b32_e32 v8, 0xffff0000, v90
	v_add_f32_e32 v13, v17, v13
	v_lshlrev_b32_e32 v14, 16, v89
	v_add_f32_e32 v17, v9, v8
	v_lshlrev_b32_e32 v8, 16, v91
	v_add_f32_e32 v14, v18, v14
	v_and_b32_e32 v15, 0xffff0000, v89
	v_add_f32_e32 v18, v10, v8
	v_and_b32_e32 v8, 0xffff0000, v91
	v_add_f32_e32 v15, v19, v15
	v_add_f32_e32 v11, v11, v8
	v_cvt_pk_bf16_f32 v8, v12, v13
	v_lshl_add_u64 v[12:13], s[22:23], 0, v[102:103]
	v_cvt_pk_bf16_f32 v9, v14, v15
	v_cvt_pk_bf16_f32 v10, v16, v17
	v_cvt_pk_bf16_f32 v11, v18, v11
	v_lshl_add_u64 v[12:13], v[12:13], 0, v[144:145]
	global_store_dwordx4 v[12:13], v[8:11], off sc0 sc1
	s_nop 1
	v_lshlrev_b32_e32 v8, 16, v92
	v_add_f32_e32 v4, v4, v8
	v_and_b32_e32 v8, 0xffff0000, v92
	v_add_f32_e32 v5, v5, v8
	v_lshlrev_b32_e32 v8, 16, v93
	v_add_f32_e32 v6, v6, v8
	v_and_b32_e32 v8, 0xffff0000, v93
	v_add_f32_e32 v7, v7, v8
	v_lshlrev_b32_e32 v8, 16, v94
	v_add_f32_e32 v8, v0, v8
	v_and_b32_e32 v0, 0xffff0000, v94
	v_add_f32_e32 v9, v1, v0
	v_lshlrev_b32_e32 v0, 16, v95
	v_add_f32_e32 v10, v2, v0
	v_and_b32_e32 v0, 0xffff0000, v95
	v_add_f32_e32 v3, v3, v0
	v_cvt_pk_bf16_f32 v0, v4, v5
	v_cvt_pk_bf16_f32 v1, v6, v7
	v_cvt_pk_bf16_f32 v2, v8, v9
	v_cvt_pk_bf16_f32 v3, v10, v3
	global_store_dwordx4 v[12:13], v[0:3], off offset:256 sc0 sc1
	s_cbranch_vccz .LBB0_931
	s_waitcnt vmcnt(0)
	s_cmpk_gt_u32 s3, 0xff
	s_cbranch_scc1 .LBB0_942
	s_barrier
